# GEMM K-loops (14 instances plus peeled copies): loop-counter and pointer SALU moved in front of the loop-back barrier, only the branch remains after it
# speedup vs baseline: 1.0091x; 1.0091x over previous
.LBB0_151:
	s_ashr_i32 s27, s26, 31
	s_lshl_b64 s[42:43], s[26:27], 19
	s_add_u32 s42, s3, s42
	s_addc_u32 s43, s23, s43
	s_and_b64 s[44:45], s[4:5], exec
	s_cselect_b32 s27, s43, s49
	s_cselect_b32 s69, s42, s48
	s_ashr_i32 s25, s24, 31
	s_lshl_b64 s[44:45], s[24:25], 19
	s_add_u32 s44, s29, s44
	s_addc_u32 s45, s31, s45
	s_and_b64 s[52:53], s[4:5], exec
	s_cselect_b32 s25, s45, s51
	s_cselect_b32 s70, s44, s50
	s_add_u32 s48, s48, 0x40080
	s_addc_u32 s49, s49, 0
	s_add_u32 s71, s50, 0x100
	s_addc_u32 s72, s51, 0
	s_mov_b32 s73, -2
	s_add_u32 s50, s48, 0xfffc0080
	s_addc_u32 s51, s49, -1
	s_cmp_eq_u32 s73, 12
	s_cselect_b32 s53, s27, s51
	s_cselect_b32 s52, s69, s50
	s_cselect_b32 s51, s25, s72
	s_cselect_b32 s50, s70, s71
	v_lshl_add_u64 v[148:149], s[48:49], 0, v[140:141]
	s_add_i32 m0, s57, 0xc000
	global_load_lds_dwordx4 v[148:149], off
	v_lshl_add_u64 v[148:149], s[48:49], 0, v[142:143]
	s_add_i32 m0, s57, 0xe000
	s_nop 0
	global_load_lds_dwordx4 v[148:149], off
	s_waitcnt vmcnt(8)
	s_waitcnt lgkmcnt(0)
	s_setprio 1
	s_barrier
	v_mfma_f32_16x16x32_bf16 v[118:121], v[160:163], v[192:195], 0
	v_mfma_f32_16x16x32_bf16 v[114:117], v[168:171], v[192:195], 0
	v_mfma_f32_16x16x32_bf16 v[106:109], v[160:163], v[200:203], 0
	v_mfma_f32_16x16x32_bf16 v[98:101], v[168:171], v[200:203], 0
	v_mfma_f32_16x16x32_bf16 v[90:93], v[160:163], v[208:211], 0
	v_mfma_f32_16x16x32_bf16 v[82:85], v[168:171], v[208:211], 0
	v_mfma_f32_16x16x32_bf16 v[74:77], v[160:163], v[216:219], 0
	v_mfma_f32_16x16x32_bf16 v[66:69], v[168:171], v[216:219], 0
	v_mfma_f32_16x16x32_bf16 v[118:121], v[164:167], v[196:199], v[118:121]
	v_mfma_f32_16x16x32_bf16 v[114:117], v[172:175], v[196:199], v[114:117]
	v_mfma_f32_16x16x32_bf16 v[106:109], v[164:167], v[204:207], v[106:109]
	v_mfma_f32_16x16x32_bf16 v[98:101], v[172:175], v[204:207], v[98:101]
	v_mfma_f32_16x16x32_bf16 v[90:93], v[164:167], v[212:215], v[90:93]
	v_mfma_f32_16x16x32_bf16 v[82:85], v[172:175], v[212:215], v[82:85]
	v_mfma_f32_16x16x32_bf16 v[74:77], v[164:167], v[220:223], v[74:77]
	v_mfma_f32_16x16x32_bf16 v[66:69], v[172:175], v[220:223], v[66:69]
	s_setprio 0
	s_setprio 1
	v_mfma_f32_16x16x32_bf16 v[126:129], v[176:179], v[192:195], 0
	v_mfma_f32_16x16x32_bf16 v[122:125], v[184:187], v[192:195], 0
	v_mfma_f32_16x16x32_bf16 v[110:113], v[176:179], v[200:203], 0
	v_mfma_f32_16x16x32_bf16 v[102:105], v[184:187], v[200:203], 0
	v_mfma_f32_16x16x32_bf16 v[94:97], v[176:179], v[208:211], 0
	v_mfma_f32_16x16x32_bf16 v[86:89], v[184:187], v[208:211], 0
	v_mfma_f32_16x16x32_bf16 v[78:81], v[176:179], v[216:219], 0
	v_mfma_f32_16x16x32_bf16 v[70:73], v[184:187], v[216:219], 0
	v_mfma_f32_16x16x32_bf16 v[126:129], v[180:183], v[196:199], v[126:129]
	v_mfma_f32_16x16x32_bf16 v[122:125], v[188:191], v[196:199], v[122:125]
	v_mfma_f32_16x16x32_bf16 v[110:113], v[180:183], v[204:207], v[110:113]
	v_mfma_f32_16x16x32_bf16 v[102:105], v[188:191], v[204:207], v[102:105]
	v_mfma_f32_16x16x32_bf16 v[94:97], v[180:183], v[212:215], v[94:97]
	v_mfma_f32_16x16x32_bf16 v[86:89], v[188:191], v[212:215], v[86:89]
	v_mfma_f32_16x16x32_bf16 v[78:81], v[180:183], v[220:223], v[78:81]
	v_mfma_f32_16x16x32_bf16 v[70:73], v[188:191], v[220:223], v[70:73]
	s_setprio 0
	s_barrier
	s_add_i32 s74, s66, s54
	v_lshl_add_u64 v[148:149], s[50:51], 0, v[134:135]
	s_mov_b32 m0, s74
	ds_read_b128 v[192:195], v157 offset:16384
	ds_read_b128 v[196:199], v157 offset:17408
	ds_read_b128 v[200:203], v157 offset:18432
	ds_read_b128 v[204:207], v157 offset:19456
	ds_read_b128 v[208:211], v157 offset:20480
	ds_read_b128 v[212:215], v157 offset:21504
	ds_read_b128 v[216:219], v157 offset:22528
	ds_read_b128 v[220:223], v157 offset:23552
	global_load_lds_dwordx4 v[148:149], off
	s_add_i32 m0, s74, 0x2000
	s_add_u32 s74, s50, 0x40000
	v_lshl_add_u64 v[224:225], s[50:51], 0, v[130:131]
	s_addc_u32 s75, s51, 0
	s_add_i32 s76, s67, s54
	global_load_lds_dwordx4 v[224:225], off
	v_lshl_add_u64 v[226:227], s[74:75], 0, v[134:135]
	s_mov_b32 m0, s76
	v_lshl_add_u64 v[228:229], s[52:53], 0, v[132:133]
	global_load_lds_dwordx4 v[226:227], off
	v_lshl_add_u64 v[226:227], s[74:75], 0, v[130:131]
	s_add_i32 m0, s76, 0x2000
	s_nop 0
	global_load_lds_dwordx4 v[226:227], off
	v_lshl_add_u64 v[226:227], s[52:53], 0, v[136:137]
	s_mov_b32 m0, s57
	s_nop 0
	global_load_lds_dwordx4 v[226:227], off
	s_mov_b32 m0, s58
	s_nop 0
	global_load_lds_dwordx4 v[228:229], off
	s_waitcnt vmcnt(8)
	s_waitcnt lgkmcnt(0)
	s_setprio 1
	s_barrier
	v_mfma_f32_16x16x32_bf16 v[58:61], v[160:163], v[192:195], 0
	v_mfma_f32_16x16x32_bf16 v[50:53], v[168:171], v[192:195], 0
	v_mfma_f32_16x16x32_bf16 v[42:45], v[160:163], v[200:203], 0
	v_mfma_f32_16x16x32_bf16 v[34:37], v[168:171], v[200:203], 0
	v_mfma_f32_16x16x32_bf16 v[26:29], v[160:163], v[208:211], 0
	v_mfma_f32_16x16x32_bf16 v[18:21], v[168:171], v[208:211], 0
	v_mfma_f32_16x16x32_bf16 v[10:13], v[160:163], v[216:219], 0
	v_mfma_f32_16x16x32_bf16 v[6:9], v[168:171], v[216:219], 0
	v_mfma_f32_16x16x32_bf16 v[58:61], v[164:167], v[196:199], v[58:61]
	v_mfma_f32_16x16x32_bf16 v[50:53], v[172:175], v[196:199], v[50:53]
	v_mfma_f32_16x16x32_bf16 v[42:45], v[164:167], v[204:207], v[42:45]
	v_mfma_f32_16x16x32_bf16 v[34:37], v[172:175], v[204:207], v[34:37]
	v_mfma_f32_16x16x32_bf16 v[26:29], v[164:167], v[212:215], v[26:29]
	v_mfma_f32_16x16x32_bf16 v[18:21], v[172:175], v[212:215], v[18:21]
	v_mfma_f32_16x16x32_bf16 v[10:13], v[164:167], v[220:223], v[10:13]
	v_mfma_f32_16x16x32_bf16 v[6:9], v[172:175], v[220:223], v[6:9]
	s_setprio 0
	s_setprio 1
	v_mfma_f32_16x16x32_bf16 v[62:65], v[176:179], v[192:195], 0
	v_mfma_f32_16x16x32_bf16 v[54:57], v[184:187], v[192:195], 0
	v_mfma_f32_16x16x32_bf16 v[46:49], v[176:179], v[200:203], 0
	v_mfma_f32_16x16x32_bf16 v[38:41], v[184:187], v[200:203], 0
	v_mfma_f32_16x16x32_bf16 v[30:33], v[176:179], v[208:211], 0
	v_mfma_f32_16x16x32_bf16 v[22:25], v[184:187], v[208:211], 0
	v_mfma_f32_16x16x32_bf16 v[14:17], v[176:179], v[216:219], 0
	v_mfma_f32_16x16x32_bf16 v[2:5], v[184:187], v[216:219], 0
	v_mfma_f32_16x16x32_bf16 v[62:65], v[180:183], v[196:199], v[62:65]
	v_mfma_f32_16x16x32_bf16 v[54:57], v[188:191], v[196:199], v[54:57]
	v_mfma_f32_16x16x32_bf16 v[46:49], v[180:183], v[204:207], v[46:49]
	v_mfma_f32_16x16x32_bf16 v[38:41], v[188:191], v[204:207], v[38:41]
	v_mfma_f32_16x16x32_bf16 v[30:33], v[180:183], v[212:215], v[30:33]
	v_mfma_f32_16x16x32_bf16 v[22:25], v[188:191], v[212:215], v[22:25]
	v_mfma_f32_16x16x32_bf16 v[14:17], v[180:183], v[220:223], v[14:17]
	v_mfma_f32_16x16x32_bf16 v[2:5], v[188:191], v[220:223], v[2:5]
	s_setprio 0
	s_barrier
	s_add_i32 s74, 0, 0x18000
	v_add_u32_e32 v159, s74, v151
	s_add_i32 s75, 0, 0x1c000
	ds_read_b128 v[160:163], v159
	ds_read_b128 v[164:167], v159 offset:1024
	ds_read_b128 v[168:171], v159 offset:2048
	ds_read_b128 v[172:175], v159 offset:3072
	v_add_u32_e32 v159, s75, v151
	ds_read_b128 v[176:179], v159
	ds_read_b128 v[180:183], v159 offset:1024
	ds_read_b128 v[184:187], v159 offset:2048
	ds_read_b128 v[188:191], v159 offset:3072
	s_add_u32 s52, s52, 0x40000
	s_addc_u32 s53, s53, 0
	s_mov_b32 m0, s59
	v_lshl_add_u64 v[230:231], s[52:53], 0, v[136:137]
	ds_read_b128 v[192:195], v157 offset:32768
	ds_read_b128 v[196:199], v157 offset:33792
	ds_read_b128 v[200:203], v157 offset:34816
	ds_read_b128 v[204:207], v157 offset:35840
	ds_read_b128 v[208:211], v157 offset:36864
	ds_read_b128 v[212:215], v157 offset:37888
	ds_read_b128 v[216:219], v157 offset:38912
	ds_read_b128 v[220:223], v157 offset:39936
	global_load_lds_dwordx4 v[230:231], off
	v_lshl_add_u64 v[230:231], s[52:53], 0, v[132:133]
	s_mov_b32 m0, s60
	s_nop 0
	global_load_lds_dwordx4 v[230:231], off
	s_waitcnt vmcnt(8)
	s_waitcnt lgkmcnt(0)
	s_setprio 1
	s_barrier
	v_mfma_f32_16x16x32_bf16 v[118:121], v[160:163], v[192:195], v[118:121]
	v_mfma_f32_16x16x32_bf16 v[114:117], v[168:171], v[192:195], v[114:117]
	v_mfma_f32_16x16x32_bf16 v[106:109], v[160:163], v[200:203], v[106:109]
	v_mfma_f32_16x16x32_bf16 v[98:101], v[168:171], v[200:203], v[98:101]
	v_mfma_f32_16x16x32_bf16 v[90:93], v[160:163], v[208:211], v[90:93]
	v_mfma_f32_16x16x32_bf16 v[82:85], v[168:171], v[208:211], v[82:85]
	v_mfma_f32_16x16x32_bf16 v[74:77], v[160:163], v[216:219], v[74:77]
	v_mfma_f32_16x16x32_bf16 v[66:69], v[168:171], v[216:219], v[66:69]
	v_mfma_f32_16x16x32_bf16 v[118:121], v[164:167], v[196:199], v[118:121]
	v_mfma_f32_16x16x32_bf16 v[114:117], v[172:175], v[196:199], v[114:117]
	v_mfma_f32_16x16x32_bf16 v[106:109], v[164:167], v[204:207], v[106:109]
	v_mfma_f32_16x16x32_bf16 v[98:101], v[172:175], v[204:207], v[98:101]
	v_mfma_f32_16x16x32_bf16 v[90:93], v[164:167], v[212:215], v[90:93]
	v_mfma_f32_16x16x32_bf16 v[82:85], v[172:175], v[212:215], v[82:85]
	v_mfma_f32_16x16x32_bf16 v[74:77], v[164:167], v[220:223], v[74:77]
	v_mfma_f32_16x16x32_bf16 v[66:69], v[172:175], v[220:223], v[66:69]
	s_setprio 0
	s_setprio 1
	v_mfma_f32_16x16x32_bf16 v[126:129], v[176:179], v[192:195], v[126:129]
	v_mfma_f32_16x16x32_bf16 v[122:125], v[184:187], v[192:195], v[122:125]
	v_mfma_f32_16x16x32_bf16 v[110:113], v[176:179], v[200:203], v[110:113]
	v_mfma_f32_16x16x32_bf16 v[102:105], v[184:187], v[200:203], v[102:105]
	v_mfma_f32_16x16x32_bf16 v[94:97], v[176:179], v[208:211], v[94:97]
	v_mfma_f32_16x16x32_bf16 v[86:89], v[184:187], v[208:211], v[86:89]
	v_mfma_f32_16x16x32_bf16 v[78:81], v[176:179], v[216:219], v[78:81]
	v_mfma_f32_16x16x32_bf16 v[70:73], v[184:187], v[216:219], v[70:73]
	v_mfma_f32_16x16x32_bf16 v[126:129], v[180:183], v[196:199], v[126:129]
	v_mfma_f32_16x16x32_bf16 v[122:125], v[188:191], v[196:199], v[122:125]
	v_mfma_f32_16x16x32_bf16 v[110:113], v[180:183], v[204:207], v[110:113]
	v_mfma_f32_16x16x32_bf16 v[102:105], v[188:191], v[204:207], v[102:105]
	v_mfma_f32_16x16x32_bf16 v[94:97], v[180:183], v[212:215], v[94:97]
	v_mfma_f32_16x16x32_bf16 v[86:89], v[188:191], v[212:215], v[86:89]
	v_mfma_f32_16x16x32_bf16 v[78:81], v[180:183], v[220:223], v[78:81]
	v_mfma_f32_16x16x32_bf16 v[70:73], v[188:191], v[220:223], v[70:73]
	s_setprio 0
	s_barrier
	s_add_i32 s52, s74, s54
	v_lshl_add_u64 v[148:149], v[148:149], 0, s[14:15]
	s_mov_b32 m0, s52
	ds_read_b128 v[192:195], v157 offset:49152
	ds_read_b128 v[196:199], v157 offset:50176
	ds_read_b128 v[200:203], v157 offset:51200
	ds_read_b128 v[204:207], v157 offset:52224
	ds_read_b128 v[208:211], v157 offset:53248
	ds_read_b128 v[212:215], v157 offset:54272
	ds_read_b128 v[216:219], v157 offset:55296
	ds_read_b128 v[220:223], v157 offset:56320
	global_load_lds_dwordx4 v[148:149], off
	s_add_i32 m0, s52, 0x2000
	s_add_u32 s50, s50, 0x40080
	v_lshl_add_u64 v[148:149], v[224:225], 0, s[14:15]
	s_addc_u32 s51, s51, 0
	s_add_i32 s52, s75, s54
	global_load_lds_dwordx4 v[148:149], off
	v_lshl_add_u64 v[148:149], s[50:51], 0, v[134:135]
	s_mov_b32 m0, s52
	s_nop 0
	global_load_lds_dwordx4 v[148:149], off
	v_lshl_add_u64 v[148:149], s[50:51], 0, v[130:131]
	s_add_i32 m0, s52, 0x2000
	s_nop 0
	global_load_lds_dwordx4 v[148:149], off
	v_lshl_add_u64 v[148:149], v[226:227], 0, s[14:15]
	s_mov_b32 m0, s62
	s_nop 0
	global_load_lds_dwordx4 v[148:149], off
	v_lshl_add_u64 v[148:149], v[228:229], 0, s[14:15]
	s_mov_b32 m0, s63
	s_nop 0
	global_load_lds_dwordx4 v[148:149], off
	s_waitcnt vmcnt(8)
	s_waitcnt lgkmcnt(0)
	s_setprio 1
	s_barrier
	v_mfma_f32_16x16x32_bf16 v[58:61], v[160:163], v[192:195], v[58:61]
	v_mfma_f32_16x16x32_bf16 v[50:53], v[168:171], v[192:195], v[50:53]
	v_mfma_f32_16x16x32_bf16 v[42:45], v[160:163], v[200:203], v[42:45]
	v_mfma_f32_16x16x32_bf16 v[34:37], v[168:171], v[200:203], v[34:37]
	v_mfma_f32_16x16x32_bf16 v[26:29], v[160:163], v[208:211], v[26:29]
	v_mfma_f32_16x16x32_bf16 v[18:21], v[168:171], v[208:211], v[18:21]
	v_mfma_f32_16x16x32_bf16 v[10:13], v[160:163], v[216:219], v[10:13]
	v_mfma_f32_16x16x32_bf16 v[6:9], v[168:171], v[216:219], v[6:9]
	v_mfma_f32_16x16x32_bf16 v[58:61], v[164:167], v[196:199], v[58:61]
	v_mfma_f32_16x16x32_bf16 v[50:53], v[172:175], v[196:199], v[50:53]
	v_mfma_f32_16x16x32_bf16 v[42:45], v[164:167], v[204:207], v[42:45]
	v_mfma_f32_16x16x32_bf16 v[34:37], v[172:175], v[204:207], v[34:37]
	v_mfma_f32_16x16x32_bf16 v[26:29], v[164:167], v[212:215], v[26:29]
	v_mfma_f32_16x16x32_bf16 v[18:21], v[172:175], v[212:215], v[18:21]
	v_mfma_f32_16x16x32_bf16 v[10:13], v[164:167], v[220:223], v[10:13]
	v_mfma_f32_16x16x32_bf16 v[6:9], v[172:175], v[220:223], v[6:9]
	s_setprio 0
	s_setprio 1
	v_mfma_f32_16x16x32_bf16 v[62:65], v[176:179], v[192:195], v[62:65]
	v_mfma_f32_16x16x32_bf16 v[54:57], v[184:187], v[192:195], v[54:57]
	v_mfma_f32_16x16x32_bf16 v[46:49], v[176:179], v[200:203], v[46:49]
	v_mfma_f32_16x16x32_bf16 v[38:41], v[184:187], v[200:203], v[38:41]
	v_mfma_f32_16x16x32_bf16 v[30:33], v[176:179], v[208:211], v[30:33]
	v_mfma_f32_16x16x32_bf16 v[22:25], v[184:187], v[208:211], v[22:25]
	v_mfma_f32_16x16x32_bf16 v[14:17], v[176:179], v[216:219], v[14:17]
	v_mfma_f32_16x16x32_bf16 v[2:5], v[184:187], v[216:219], v[2:5]
	v_mfma_f32_16x16x32_bf16 v[62:65], v[180:183], v[196:199], v[62:65]
	v_mfma_f32_16x16x32_bf16 v[54:57], v[188:191], v[196:199], v[54:57]
	v_mfma_f32_16x16x32_bf16 v[46:49], v[180:183], v[204:207], v[46:49]
	v_mfma_f32_16x16x32_bf16 v[38:41], v[188:191], v[204:207], v[38:41]
	v_mfma_f32_16x16x32_bf16 v[30:33], v[180:183], v[212:215], v[30:33]
	v_mfma_f32_16x16x32_bf16 v[22:25], v[188:191], v[212:215], v[22:25]
	v_mfma_f32_16x16x32_bf16 v[14:17], v[180:183], v[220:223], v[14:17]
	v_mfma_f32_16x16x32_bf16 v[2:5], v[188:191], v[220:223], v[2:5]
	s_setprio 0
	s_add_i32 s73, s73, 2
	s_add_u32 s48, s48, 0x100
	s_addc_u32 s49, s49, 0
	s_add_u32 s71, s71, 0x100
	s_addc_u32 s72, s72, 0
	s_cmp_gt_u32 s73, 13
	s_barrier
	s_cbranch_scc0 .LBB0_152
	s_branch .Lz_post_p1
.LBB0_152:
	ds_read_b128 v[160:163], v155
	ds_read_b128 v[164:167], v155 offset:1024
	ds_read_b128 v[168:171], v155 offset:2048
	ds_read_b128 v[172:175], v155 offset:3072
	ds_read_b128 v[176:179], v156
	ds_read_b128 v[180:183], v156 offset:1024
	ds_read_b128 v[184:187], v156 offset:2048
	ds_read_b128 v[188:191], v156 offset:3072
	s_add_u32 s50, s48, 0xfffc0080
	s_addc_u32 s51, s49, -1
	s_cmp_eq_u32 s73, 12
	s_cselect_b32 s53, s27, s51
	s_cselect_b32 s52, s69, s50
	s_cselect_b32 s51, s25, s72
	s_cselect_b32 s50, s70, s71
	v_lshl_add_u64 v[148:149], s[48:49], 0, v[140:141]
	s_add_i32 m0, s57, 0xc000
	ds_read_b128 v[192:195], v157
	ds_read_b128 v[196:199], v157 offset:1024
	ds_read_b128 v[200:203], v157 offset:2048
	ds_read_b128 v[204:207], v157 offset:3072
	ds_read_b128 v[208:211], v157 offset:4096
	ds_read_b128 v[212:215], v157 offset:5120
	ds_read_b128 v[216:219], v157 offset:6144
	ds_read_b128 v[220:223], v157 offset:7168
	global_load_lds_dwordx4 v[148:149], off
	v_lshl_add_u64 v[148:149], s[48:49], 0, v[142:143]
	s_add_i32 m0, s57, 0xe000
	s_nop 0
	global_load_lds_dwordx4 v[148:149], off
	s_waitcnt vmcnt(8)
	s_waitcnt lgkmcnt(0)
	s_setprio 1
	s_barrier
	v_mfma_f32_16x16x32_bf16 v[118:121], v[160:163], v[192:195], v[118:121]
	v_mfma_f32_16x16x32_bf16 v[114:117], v[168:171], v[192:195], v[114:117]
	v_mfma_f32_16x16x32_bf16 v[106:109], v[160:163], v[200:203], v[106:109]
	v_mfma_f32_16x16x32_bf16 v[98:101], v[168:171], v[200:203], v[98:101]
	v_mfma_f32_16x16x32_bf16 v[90:93], v[160:163], v[208:211], v[90:93]
	v_mfma_f32_16x16x32_bf16 v[82:85], v[168:171], v[208:211], v[82:85]
	v_mfma_f32_16x16x32_bf16 v[74:77], v[160:163], v[216:219], v[74:77]
	v_mfma_f32_16x16x32_bf16 v[66:69], v[168:171], v[216:219], v[66:69]
	v_mfma_f32_16x16x32_bf16 v[118:121], v[164:167], v[196:199], v[118:121]
	v_mfma_f32_16x16x32_bf16 v[114:117], v[172:175], v[196:199], v[114:117]
	v_mfma_f32_16x16x32_bf16 v[106:109], v[164:167], v[204:207], v[106:109]
	v_mfma_f32_16x16x32_bf16 v[98:101], v[172:175], v[204:207], v[98:101]
	v_mfma_f32_16x16x32_bf16 v[90:93], v[164:167], v[212:215], v[90:93]
	v_mfma_f32_16x16x32_bf16 v[82:85], v[172:175], v[212:215], v[82:85]
	v_mfma_f32_16x16x32_bf16 v[74:77], v[164:167], v[220:223], v[74:77]
	v_mfma_f32_16x16x32_bf16 v[66:69], v[172:175], v[220:223], v[66:69]
	s_setprio 0
	s_setprio 1
	v_mfma_f32_16x16x32_bf16 v[126:129], v[176:179], v[192:195], v[126:129]
	v_mfma_f32_16x16x32_bf16 v[122:125], v[184:187], v[192:195], v[122:125]
	v_mfma_f32_16x16x32_bf16 v[110:113], v[176:179], v[200:203], v[110:113]
	v_mfma_f32_16x16x32_bf16 v[102:105], v[184:187], v[200:203], v[102:105]
	v_mfma_f32_16x16x32_bf16 v[94:97], v[176:179], v[208:211], v[94:97]
	v_mfma_f32_16x16x32_bf16 v[86:89], v[184:187], v[208:211], v[86:89]
	v_mfma_f32_16x16x32_bf16 v[78:81], v[176:179], v[216:219], v[78:81]
	v_mfma_f32_16x16x32_bf16 v[70:73], v[184:187], v[216:219], v[70:73]
	v_mfma_f32_16x16x32_bf16 v[126:129], v[180:183], v[196:199], v[126:129]
	v_mfma_f32_16x16x32_bf16 v[122:125], v[188:191], v[196:199], v[122:125]
	v_mfma_f32_16x16x32_bf16 v[110:113], v[180:183], v[204:207], v[110:113]
	v_mfma_f32_16x16x32_bf16 v[102:105], v[188:191], v[204:207], v[102:105]
	v_mfma_f32_16x16x32_bf16 v[94:97], v[180:183], v[212:215], v[94:97]
	v_mfma_f32_16x16x32_bf16 v[86:89], v[188:191], v[212:215], v[86:89]
	v_mfma_f32_16x16x32_bf16 v[78:81], v[180:183], v[220:223], v[78:81]
	v_mfma_f32_16x16x32_bf16 v[70:73], v[188:191], v[220:223], v[70:73]
	s_setprio 0
	s_barrier
	s_add_i32 s74, s66, s54
	v_lshl_add_u64 v[148:149], s[50:51], 0, v[134:135]
	s_mov_b32 m0, s74
	ds_read_b128 v[192:195], v157 offset:16384
	ds_read_b128 v[196:199], v157 offset:17408
	ds_read_b128 v[200:203], v157 offset:18432
	ds_read_b128 v[204:207], v157 offset:19456
	ds_read_b128 v[208:211], v157 offset:20480
	ds_read_b128 v[212:215], v157 offset:21504
	ds_read_b128 v[216:219], v157 offset:22528
	ds_read_b128 v[220:223], v157 offset:23552
	global_load_lds_dwordx4 v[148:149], off
	s_add_i32 m0, s74, 0x2000
	s_add_u32 s74, s50, 0x40000
	v_lshl_add_u64 v[224:225], s[50:51], 0, v[130:131]
	s_addc_u32 s75, s51, 0
	s_add_i32 s76, s67, s54
	global_load_lds_dwordx4 v[224:225], off
	v_lshl_add_u64 v[226:227], s[74:75], 0, v[134:135]
	s_mov_b32 m0, s76
	v_lshl_add_u64 v[228:229], s[52:53], 0, v[132:133]
	global_load_lds_dwordx4 v[226:227], off
	v_lshl_add_u64 v[226:227], s[74:75], 0, v[130:131]
	s_add_i32 m0, s76, 0x2000
	s_nop 0
	global_load_lds_dwordx4 v[226:227], off
	v_lshl_add_u64 v[226:227], s[52:53], 0, v[136:137]
	s_mov_b32 m0, s57
	s_nop 0
	global_load_lds_dwordx4 v[226:227], off
	s_mov_b32 m0, s58
	s_nop 0
	global_load_lds_dwordx4 v[228:229], off
	s_waitcnt vmcnt(8)
	s_waitcnt lgkmcnt(0)
	s_setprio 1
	s_barrier
	v_mfma_f32_16x16x32_bf16 v[58:61], v[160:163], v[192:195], v[58:61]
	v_mfma_f32_16x16x32_bf16 v[50:53], v[168:171], v[192:195], v[50:53]
	v_mfma_f32_16x16x32_bf16 v[42:45], v[160:163], v[200:203], v[42:45]
	v_mfma_f32_16x16x32_bf16 v[34:37], v[168:171], v[200:203], v[34:37]
	v_mfma_f32_16x16x32_bf16 v[26:29], v[160:163], v[208:211], v[26:29]
	v_mfma_f32_16x16x32_bf16 v[18:21], v[168:171], v[208:211], v[18:21]
	v_mfma_f32_16x16x32_bf16 v[10:13], v[160:163], v[216:219], v[10:13]
	v_mfma_f32_16x16x32_bf16 v[6:9], v[168:171], v[216:219], v[6:9]
	v_mfma_f32_16x16x32_bf16 v[58:61], v[164:167], v[196:199], v[58:61]
	v_mfma_f32_16x16x32_bf16 v[50:53], v[172:175], v[196:199], v[50:53]
	v_mfma_f32_16x16x32_bf16 v[42:45], v[164:167], v[204:207], v[42:45]
	v_mfma_f32_16x16x32_bf16 v[34:37], v[172:175], v[204:207], v[34:37]
	v_mfma_f32_16x16x32_bf16 v[26:29], v[164:167], v[212:215], v[26:29]
	v_mfma_f32_16x16x32_bf16 v[18:21], v[172:175], v[212:215], v[18:21]
	v_mfma_f32_16x16x32_bf16 v[10:13], v[164:167], v[220:223], v[10:13]
	v_mfma_f32_16x16x32_bf16 v[6:9], v[172:175], v[220:223], v[6:9]
	s_setprio 0
	s_setprio 1
	v_mfma_f32_16x16x32_bf16 v[62:65], v[176:179], v[192:195], v[62:65]
	v_mfma_f32_16x16x32_bf16 v[54:57], v[184:187], v[192:195], v[54:57]
	v_mfma_f32_16x16x32_bf16 v[46:49], v[176:179], v[200:203], v[46:49]
	v_mfma_f32_16x16x32_bf16 v[38:41], v[184:187], v[200:203], v[38:41]
	v_mfma_f32_16x16x32_bf16 v[30:33], v[176:179], v[208:211], v[30:33]
	v_mfma_f32_16x16x32_bf16 v[22:25], v[184:187], v[208:211], v[22:25]
	v_mfma_f32_16x16x32_bf16 v[14:17], v[176:179], v[216:219], v[14:17]
	v_mfma_f32_16x16x32_bf16 v[2:5], v[184:187], v[216:219], v[2:5]
	v_mfma_f32_16x16x32_bf16 v[62:65], v[180:183], v[196:199], v[62:65]
	v_mfma_f32_16x16x32_bf16 v[54:57], v[188:191], v[196:199], v[54:57]
	v_mfma_f32_16x16x32_bf16 v[46:49], v[180:183], v[204:207], v[46:49]
	v_mfma_f32_16x16x32_bf16 v[38:41], v[188:191], v[204:207], v[38:41]
	v_mfma_f32_16x16x32_bf16 v[30:33], v[180:183], v[212:215], v[30:33]
	v_mfma_f32_16x16x32_bf16 v[22:25], v[188:191], v[212:215], v[22:25]
	v_mfma_f32_16x16x32_bf16 v[14:17], v[180:183], v[220:223], v[14:17]
	v_mfma_f32_16x16x32_bf16 v[2:5], v[188:191], v[220:223], v[2:5]
	s_setprio 0
	s_barrier
	s_add_i32 s74, 0, 0x18000
	v_add_u32_e32 v159, s74, v151
	s_add_i32 s75, 0, 0x1c000
	ds_read_b128 v[160:163], v159
	ds_read_b128 v[164:167], v159 offset:1024
	ds_read_b128 v[168:171], v159 offset:2048
	ds_read_b128 v[172:175], v159 offset:3072
	v_add_u32_e32 v159, s75, v151
	ds_read_b128 v[176:179], v159
	ds_read_b128 v[180:183], v159 offset:1024
	ds_read_b128 v[184:187], v159 offset:2048
	ds_read_b128 v[188:191], v159 offset:3072
	s_add_u32 s52, s52, 0x40000
	s_addc_u32 s53, s53, 0
	s_mov_b32 m0, s59
	v_lshl_add_u64 v[230:231], s[52:53], 0, v[136:137]
	ds_read_b128 v[192:195], v157 offset:32768
	ds_read_b128 v[196:199], v157 offset:33792
	ds_read_b128 v[200:203], v157 offset:34816
	ds_read_b128 v[204:207], v157 offset:35840
	ds_read_b128 v[208:211], v157 offset:36864
	ds_read_b128 v[212:215], v157 offset:37888
	ds_read_b128 v[216:219], v157 offset:38912
	ds_read_b128 v[220:223], v157 offset:39936
	global_load_lds_dwordx4 v[230:231], off
	v_lshl_add_u64 v[230:231], s[52:53], 0, v[132:133]
	s_mov_b32 m0, s60
	s_nop 0
	global_load_lds_dwordx4 v[230:231], off
	s_waitcnt vmcnt(8)
	s_waitcnt lgkmcnt(0)
	s_setprio 1
	s_barrier
	v_mfma_f32_16x16x32_bf16 v[118:121], v[160:163], v[192:195], v[118:121]
	v_mfma_f32_16x16x32_bf16 v[114:117], v[168:171], v[192:195], v[114:117]
	v_mfma_f32_16x16x32_bf16 v[106:109], v[160:163], v[200:203], v[106:109]
	v_mfma_f32_16x16x32_bf16 v[98:101], v[168:171], v[200:203], v[98:101]
	v_mfma_f32_16x16x32_bf16 v[90:93], v[160:163], v[208:211], v[90:93]
	v_mfma_f32_16x16x32_bf16 v[82:85], v[168:171], v[208:211], v[82:85]
	v_mfma_f32_16x16x32_bf16 v[74:77], v[160:163], v[216:219], v[74:77]
	v_mfma_f32_16x16x32_bf16 v[66:69], v[168:171], v[216:219], v[66:69]
	v_mfma_f32_16x16x32_bf16 v[118:121], v[164:167], v[196:199], v[118:121]
	v_mfma_f32_16x16x32_bf16 v[114:117], v[172:175], v[196:199], v[114:117]
	v_mfma_f32_16x16x32_bf16 v[106:109], v[164:167], v[204:207], v[106:109]
	v_mfma_f32_16x16x32_bf16 v[98:101], v[172:175], v[204:207], v[98:101]
	v_mfma_f32_16x16x32_bf16 v[90:93], v[164:167], v[212:215], v[90:93]
	v_mfma_f32_16x16x32_bf16 v[82:85], v[172:175], v[212:215], v[82:85]
	v_mfma_f32_16x16x32_bf16 v[74:77], v[164:167], v[220:223], v[74:77]
	v_mfma_f32_16x16x32_bf16 v[66:69], v[172:175], v[220:223], v[66:69]
	s_setprio 0
	s_setprio 1
	v_mfma_f32_16x16x32_bf16 v[126:129], v[176:179], v[192:195], v[126:129]
	v_mfma_f32_16x16x32_bf16 v[122:125], v[184:187], v[192:195], v[122:125]
	v_mfma_f32_16x16x32_bf16 v[110:113], v[176:179], v[200:203], v[110:113]
	v_mfma_f32_16x16x32_bf16 v[102:105], v[184:187], v[200:203], v[102:105]
	v_mfma_f32_16x16x32_bf16 v[94:97], v[176:179], v[208:211], v[94:97]
	v_mfma_f32_16x16x32_bf16 v[86:89], v[184:187], v[208:211], v[86:89]
	v_mfma_f32_16x16x32_bf16 v[78:81], v[176:179], v[216:219], v[78:81]
	v_mfma_f32_16x16x32_bf16 v[70:73], v[184:187], v[216:219], v[70:73]
	v_mfma_f32_16x16x32_bf16 v[126:129], v[180:183], v[196:199], v[126:129]
	v_mfma_f32_16x16x32_bf16 v[122:125], v[188:191], v[196:199], v[122:125]
	v_mfma_f32_16x16x32_bf16 v[110:113], v[180:183], v[204:207], v[110:113]
	v_mfma_f32_16x16x32_bf16 v[102:105], v[188:191], v[204:207], v[102:105]
	v_mfma_f32_16x16x32_bf16 v[94:97], v[180:183], v[212:215], v[94:97]
	v_mfma_f32_16x16x32_bf16 v[86:89], v[188:191], v[212:215], v[86:89]
	v_mfma_f32_16x16x32_bf16 v[78:81], v[180:183], v[220:223], v[78:81]
	v_mfma_f32_16x16x32_bf16 v[70:73], v[188:191], v[220:223], v[70:73]
	s_setprio 0
	s_barrier
	s_add_i32 s52, s74, s54
	v_lshl_add_u64 v[148:149], v[148:149], 0, s[14:15]
	s_mov_b32 m0, s52
	ds_read_b128 v[192:195], v157 offset:49152
	ds_read_b128 v[196:199], v157 offset:50176
	ds_read_b128 v[200:203], v157 offset:51200
	ds_read_b128 v[204:207], v157 offset:52224
	ds_read_b128 v[208:211], v157 offset:53248
	ds_read_b128 v[212:215], v157 offset:54272
	ds_read_b128 v[216:219], v157 offset:55296
	ds_read_b128 v[220:223], v157 offset:56320
	global_load_lds_dwordx4 v[148:149], off
	s_add_i32 m0, s52, 0x2000
	s_add_u32 s50, s50, 0x40080
	v_lshl_add_u64 v[148:149], v[224:225], 0, s[14:15]
	s_addc_u32 s51, s51, 0
	s_add_i32 s52, s75, s54
	global_load_lds_dwordx4 v[148:149], off
	v_lshl_add_u64 v[148:149], s[50:51], 0, v[134:135]
	s_mov_b32 m0, s52
	s_nop 0
	global_load_lds_dwordx4 v[148:149], off
	v_lshl_add_u64 v[148:149], s[50:51], 0, v[130:131]
	s_add_i32 m0, s52, 0x2000
	s_nop 0
	global_load_lds_dwordx4 v[148:149], off
	v_lshl_add_u64 v[148:149], v[226:227], 0, s[14:15]
	s_mov_b32 m0, s62
	s_nop 0
	global_load_lds_dwordx4 v[148:149], off
	v_lshl_add_u64 v[148:149], v[228:229], 0, s[14:15]
	s_mov_b32 m0, s63
	s_nop 0
	global_load_lds_dwordx4 v[148:149], off
	s_waitcnt vmcnt(8)
	s_waitcnt lgkmcnt(0)
	s_setprio 1
	s_barrier
	v_mfma_f32_16x16x32_bf16 v[58:61], v[160:163], v[192:195], v[58:61]
	v_mfma_f32_16x16x32_bf16 v[50:53], v[168:171], v[192:195], v[50:53]
	v_mfma_f32_16x16x32_bf16 v[42:45], v[160:163], v[200:203], v[42:45]
	v_mfma_f32_16x16x32_bf16 v[34:37], v[168:171], v[200:203], v[34:37]
	v_mfma_f32_16x16x32_bf16 v[26:29], v[160:163], v[208:211], v[26:29]
	v_mfma_f32_16x16x32_bf16 v[18:21], v[168:171], v[208:211], v[18:21]
	v_mfma_f32_16x16x32_bf16 v[10:13], v[160:163], v[216:219], v[10:13]
	v_mfma_f32_16x16x32_bf16 v[6:9], v[168:171], v[216:219], v[6:9]
	v_mfma_f32_16x16x32_bf16 v[58:61], v[164:167], v[196:199], v[58:61]
	v_mfma_f32_16x16x32_bf16 v[50:53], v[172:175], v[196:199], v[50:53]
	v_mfma_f32_16x16x32_bf16 v[42:45], v[164:167], v[204:207], v[42:45]
	v_mfma_f32_16x16x32_bf16 v[34:37], v[172:175], v[204:207], v[34:37]
	v_mfma_f32_16x16x32_bf16 v[26:29], v[164:167], v[212:215], v[26:29]
	v_mfma_f32_16x16x32_bf16 v[18:21], v[172:175], v[212:215], v[18:21]
	v_mfma_f32_16x16x32_bf16 v[10:13], v[164:167], v[220:223], v[10:13]
	v_mfma_f32_16x16x32_bf16 v[6:9], v[172:175], v[220:223], v[6:9]
	s_setprio 0
	s_setprio 1
	v_mfma_f32_16x16x32_bf16 v[62:65], v[176:179], v[192:195], v[62:65]
	v_mfma_f32_16x16x32_bf16 v[54:57], v[184:187], v[192:195], v[54:57]
	v_mfma_f32_16x16x32_bf16 v[46:49], v[176:179], v[200:203], v[46:49]
	v_mfma_f32_16x16x32_bf16 v[38:41], v[184:187], v[200:203], v[38:41]
	v_mfma_f32_16x16x32_bf16 v[30:33], v[176:179], v[208:211], v[30:33]
	v_mfma_f32_16x16x32_bf16 v[22:25], v[184:187], v[208:211], v[22:25]
	v_mfma_f32_16x16x32_bf16 v[14:17], v[176:179], v[216:219], v[14:17]
	v_mfma_f32_16x16x32_bf16 v[2:5], v[184:187], v[216:219], v[2:5]
	v_mfma_f32_16x16x32_bf16 v[62:65], v[180:183], v[196:199], v[62:65]
	v_mfma_f32_16x16x32_bf16 v[54:57], v[188:191], v[196:199], v[54:57]
	v_mfma_f32_16x16x32_bf16 v[46:49], v[180:183], v[204:207], v[46:49]
	v_mfma_f32_16x16x32_bf16 v[38:41], v[188:191], v[204:207], v[38:41]
	v_mfma_f32_16x16x32_bf16 v[30:33], v[180:183], v[212:215], v[30:33]
	v_mfma_f32_16x16x32_bf16 v[22:25], v[188:191], v[212:215], v[22:25]
	v_mfma_f32_16x16x32_bf16 v[14:17], v[180:183], v[220:223], v[14:17]
	v_mfma_f32_16x16x32_bf16 v[2:5], v[188:191], v[220:223], v[2:5]
	s_setprio 0
	s_add_i32 s73, s73, 2
	s_add_u32 s48, s48, 0x100
	s_addc_u32 s49, s49, 0
	s_add_u32 s71, s71, 0x100
	s_addc_u32 s72, s72, 0
	s_cmp_gt_u32 s73, 13
	s_barrier
	s_cbranch_scc0 .LBB0_152

.LBB0_250:
	s_add_u32 s69, s46, 0x100
	s_addc_u32 s70, s47, 0
	s_mov_b32 s71, -2
	ds_read_b128 v[122:125], v245
	ds_read_b128 v[126:129], v245 offset:1024
	ds_read_b128 v[130:133], v245 offset:2048
	ds_read_b128 v[134:137], v245 offset:3072
	ds_read_b128 v[138:141], v246
	ds_read_b128 v[142:145], v246 offset:1024
	ds_read_b128 v[146:149], v246 offset:2048
	ds_read_b128 v[158:161], v246 offset:3072
	s_add_u32 s46, s44, 0x100
	s_addc_u32 s47, s45, 0
	s_cmp_eq_u32 s71, 40
	s_cselect_b32 s51, s9, s47
	s_cselect_b32 s50, s8, s46
	s_cselect_b32 s49, s43, s70
	s_cselect_b32 s48, s42, s69
	v_lshl_add_u64 v[210:211], s[44:45], 0, v[206:207]
	s_add_i32 m0, s53, 0xc000
	ds_read_b128 v[162:165], v247
	ds_read_b128 v[166:169], v247 offset:1024
	ds_read_b128 v[170:173], v247 offset:2048
	ds_read_b128 v[174:177], v247 offset:3072
	ds_read_b128 v[178:181], v247 offset:4096
	ds_read_b128 v[182:185], v247 offset:5120
	ds_read_b128 v[186:189], v247 offset:6144
	ds_read_b128 v[190:193], v247 offset:7168
	global_load_lds_dwordx4 v[210:211], off
	v_lshl_add_u64 v[210:211], s[44:45], 0, v[208:209]
	s_add_i32 m0, s53, 0xe000
	s_nop 0
	global_load_lds_dwordx4 v[210:211], off
	s_waitcnt vmcnt(8)
	s_waitcnt lgkmcnt(0)
	s_setprio 1
	s_barrier
	v_mfma_f32_16x16x32_bf16 v[154:157], v[122:125], v[162:165], 0
	v_mfma_f32_16x16x32_bf16 v[150:153], v[130:133], v[162:165], 0
	v_mfma_f32_16x16x32_bf16 v[110:113], v[122:125], v[170:173], 0
	v_mfma_f32_16x16x32_bf16 v[106:109], v[130:133], v[170:173], 0
	v_mfma_f32_16x16x32_bf16 v[94:97], v[122:125], v[178:181], 0
	v_mfma_f32_16x16x32_bf16 v[90:93], v[130:133], v[178:181], 0
	v_mfma_f32_16x16x32_bf16 v[78:81], v[122:125], v[186:189], 0
	v_mfma_f32_16x16x32_bf16 v[74:77], v[130:133], v[186:189], 0
	v_mfma_f32_16x16x32_bf16 v[154:157], v[126:129], v[166:169], v[154:157]
	v_mfma_f32_16x16x32_bf16 v[150:153], v[134:137], v[166:169], v[150:153]
	v_mfma_f32_16x16x32_bf16 v[110:113], v[126:129], v[174:177], v[110:113]
	v_mfma_f32_16x16x32_bf16 v[106:109], v[134:137], v[174:177], v[106:109]
	v_mfma_f32_16x16x32_bf16 v[94:97], v[126:129], v[182:185], v[94:97]
	v_mfma_f32_16x16x32_bf16 v[90:93], v[134:137], v[182:185], v[90:93]
	v_mfma_f32_16x16x32_bf16 v[78:81], v[126:129], v[190:193], v[78:81]
	v_mfma_f32_16x16x32_bf16 v[74:77], v[134:137], v[190:193], v[74:77]
	s_setprio 0
	s_setprio 1
	v_mfma_f32_16x16x32_bf16 v[118:121], v[138:141], v[162:165], 0
	v_mfma_f32_16x16x32_bf16 v[114:117], v[146:149], v[162:165], 0
	v_mfma_f32_16x16x32_bf16 v[102:105], v[138:141], v[170:173], 0
	v_mfma_f32_16x16x32_bf16 v[98:101], v[146:149], v[170:173], 0
	v_mfma_f32_16x16x32_bf16 v[86:89], v[138:141], v[178:181], 0
	v_mfma_f32_16x16x32_bf16 v[82:85], v[146:149], v[178:181], 0
	v_mfma_f32_16x16x32_bf16 v[70:73], v[138:141], v[186:189], 0
	v_mfma_f32_16x16x32_bf16 v[66:69], v[146:149], v[186:189], 0
	v_mfma_f32_16x16x32_bf16 v[118:121], v[142:145], v[166:169], v[118:121]
	v_mfma_f32_16x16x32_bf16 v[114:117], v[158:161], v[166:169], v[114:117]
	v_mfma_f32_16x16x32_bf16 v[102:105], v[142:145], v[174:177], v[102:105]
	v_mfma_f32_16x16x32_bf16 v[98:101], v[158:161], v[174:177], v[98:101]
	v_mfma_f32_16x16x32_bf16 v[86:89], v[142:145], v[182:185], v[86:89]
	v_mfma_f32_16x16x32_bf16 v[82:85], v[158:161], v[182:185], v[82:85]
	v_mfma_f32_16x16x32_bf16 v[70:73], v[142:145], v[190:193], v[70:73]
	v_mfma_f32_16x16x32_bf16 v[66:69], v[158:161], v[190:193], v[66:69]
	s_setprio 0
	s_barrier
	s_add_i32 s44, s63, s52
	v_lshl_add_u64 v[210:211], s[48:49], 0, v[196:197]
	s_mov_b32 m0, s44
	ds_read_b128 v[162:165], v247 offset:16384
	ds_read_b128 v[166:169], v247 offset:17408
	ds_read_b128 v[170:173], v247 offset:18432
	ds_read_b128 v[174:177], v247 offset:19456
	ds_read_b128 v[178:181], v247 offset:20480
	ds_read_b128 v[182:185], v247 offset:21504
	ds_read_b128 v[186:189], v247 offset:22528
	ds_read_b128 v[190:193], v247 offset:23552
	global_load_lds_dwordx4 v[210:211], off
	s_add_i32 m0, s44, 0x2000
	s_add_u32 s44, s48, 0xb0000
	v_lshl_add_u64 v[212:213], s[48:49], 0, v[200:201]
	s_addc_u32 s45, s49, 0
	s_add_i32 s72, s64, s52
	global_load_lds_dwordx4 v[212:213], off
	v_lshl_add_u64 v[214:215], s[44:45], 0, v[196:197]
	s_mov_b32 m0, s72
	v_lshl_add_u64 v[216:217], s[50:51], 0, v[198:199]
	global_load_lds_dwordx4 v[214:215], off
	v_lshl_add_u64 v[214:215], s[44:45], 0, v[200:201]
	s_add_i32 m0, s72, 0x2000
	s_nop 0
	global_load_lds_dwordx4 v[214:215], off
	v_lshl_add_u64 v[214:215], s[50:51], 0, v[194:195]
	s_mov_b32 m0, s53
	s_nop 0
	global_load_lds_dwordx4 v[214:215], off
	s_mov_b32 m0, s54
	s_nop 0
	global_load_lds_dwordx4 v[216:217], off
	s_waitcnt vmcnt(8)
	s_waitcnt lgkmcnt(0)
	s_setprio 1
	s_barrier
	v_mfma_f32_16x16x32_bf16 v[62:65], v[122:125], v[162:165], 0
	v_mfma_f32_16x16x32_bf16 v[58:61], v[130:133], v[162:165], 0
	v_mfma_f32_16x16x32_bf16 v[46:49], v[122:125], v[170:173], 0
	v_mfma_f32_16x16x32_bf16 v[42:45], v[130:133], v[170:173], 0
	v_mfma_f32_16x16x32_bf16 v[30:33], v[122:125], v[178:181], 0
	v_mfma_f32_16x16x32_bf16 v[26:29], v[130:133], v[178:181], 0
	v_mfma_f32_16x16x32_bf16 v[14:17], v[122:125], v[186:189], 0
	v_mfma_f32_16x16x32_bf16 v[10:13], v[130:133], v[186:189], 0
	v_mfma_f32_16x16x32_bf16 v[62:65], v[126:129], v[166:169], v[62:65]
	v_mfma_f32_16x16x32_bf16 v[58:61], v[134:137], v[166:169], v[58:61]
	v_mfma_f32_16x16x32_bf16 v[46:49], v[126:129], v[174:177], v[46:49]
	v_mfma_f32_16x16x32_bf16 v[42:45], v[134:137], v[174:177], v[42:45]
	v_mfma_f32_16x16x32_bf16 v[30:33], v[126:129], v[182:185], v[30:33]
	v_mfma_f32_16x16x32_bf16 v[26:29], v[134:137], v[182:185], v[26:29]
	v_mfma_f32_16x16x32_bf16 v[14:17], v[126:129], v[190:193], v[14:17]
	v_mfma_f32_16x16x32_bf16 v[10:13], v[134:137], v[190:193], v[10:13]
	s_setprio 0
	s_setprio 1
	v_mfma_f32_16x16x32_bf16 v[54:57], v[138:141], v[162:165], 0
	v_mfma_f32_16x16x32_bf16 v[50:53], v[146:149], v[162:165], 0
	v_mfma_f32_16x16x32_bf16 v[38:41], v[138:141], v[170:173], 0
	v_mfma_f32_16x16x32_bf16 v[34:37], v[146:149], v[170:173], 0
	v_mfma_f32_16x16x32_bf16 v[22:25], v[138:141], v[178:181], 0
	v_mfma_f32_16x16x32_bf16 v[18:21], v[146:149], v[178:181], 0
	v_mfma_f32_16x16x32_bf16 v[6:9], v[138:141], v[186:189], 0
	v_mfma_f32_16x16x32_bf16 v[2:5], v[146:149], v[186:189], 0
	v_mfma_f32_16x16x32_bf16 v[54:57], v[142:145], v[166:169], v[54:57]
	v_mfma_f32_16x16x32_bf16 v[50:53], v[158:161], v[166:169], v[50:53]
	v_mfma_f32_16x16x32_bf16 v[38:41], v[142:145], v[174:177], v[38:41]
	v_mfma_f32_16x16x32_bf16 v[34:37], v[158:161], v[174:177], v[34:37]
	v_mfma_f32_16x16x32_bf16 v[22:25], v[142:145], v[182:185], v[22:25]
	v_mfma_f32_16x16x32_bf16 v[18:21], v[158:161], v[182:185], v[18:21]
	v_mfma_f32_16x16x32_bf16 v[6:9], v[142:145], v[190:193], v[6:9]
	v_mfma_f32_16x16x32_bf16 v[2:5], v[158:161], v[190:193], v[2:5]
	s_setprio 0
	s_barrier
	s_add_i32 s72, 0, 0x18000
	s_add_i32 s73, 0, 0x1c000
	v_add_u32_e32 v134, s72, v244
	v_add_u32_e32 v158, s73, v244
	ds_read_b128 v[122:125], v134
	ds_read_b128 v[126:129], v134 offset:1024
	ds_read_b128 v[130:133], v134 offset:2048
	ds_read_b128 v[134:137], v134 offset:3072
	ds_read_b128 v[138:141], v158
	ds_read_b128 v[142:145], v158 offset:1024
	ds_read_b128 v[146:149], v158 offset:2048
	ds_read_b128 v[158:161], v158 offset:3072
	s_add_u32 s44, s50, 0xb0000
	s_addc_u32 s45, s51, 0
	s_mov_b32 m0, s55
	v_lshl_add_u64 v[218:219], s[44:45], 0, v[194:195]
	ds_read_b128 v[162:165], v247 offset:32768
	ds_read_b128 v[166:169], v247 offset:33792
	ds_read_b128 v[170:173], v247 offset:34816
	ds_read_b128 v[174:177], v247 offset:35840
	ds_read_b128 v[178:181], v247 offset:36864
	ds_read_b128 v[182:185], v247 offset:37888
	ds_read_b128 v[186:189], v247 offset:38912
	ds_read_b128 v[190:193], v247 offset:39936
	global_load_lds_dwordx4 v[218:219], off
	v_lshl_add_u64 v[218:219], s[44:45], 0, v[198:199]
	s_mov_b32 m0, s56
	s_nop 0
	global_load_lds_dwordx4 v[218:219], off
	s_waitcnt vmcnt(8)
	s_waitcnt lgkmcnt(0)
	s_setprio 1
	s_barrier
	v_mfma_f32_16x16x32_bf16 v[154:157], v[122:125], v[162:165], v[154:157]
	v_mfma_f32_16x16x32_bf16 v[150:153], v[130:133], v[162:165], v[150:153]
	v_mfma_f32_16x16x32_bf16 v[110:113], v[122:125], v[170:173], v[110:113]
	v_mfma_f32_16x16x32_bf16 v[106:109], v[130:133], v[170:173], v[106:109]
	v_mfma_f32_16x16x32_bf16 v[94:97], v[122:125], v[178:181], v[94:97]
	v_mfma_f32_16x16x32_bf16 v[90:93], v[130:133], v[178:181], v[90:93]
	v_mfma_f32_16x16x32_bf16 v[78:81], v[122:125], v[186:189], v[78:81]
	v_mfma_f32_16x16x32_bf16 v[74:77], v[130:133], v[186:189], v[74:77]
	v_mfma_f32_16x16x32_bf16 v[154:157], v[126:129], v[166:169], v[154:157]
	v_mfma_f32_16x16x32_bf16 v[150:153], v[134:137], v[166:169], v[150:153]
	v_mfma_f32_16x16x32_bf16 v[110:113], v[126:129], v[174:177], v[110:113]
	v_mfma_f32_16x16x32_bf16 v[106:109], v[134:137], v[174:177], v[106:109]
	v_mfma_f32_16x16x32_bf16 v[94:97], v[126:129], v[182:185], v[94:97]
	v_mfma_f32_16x16x32_bf16 v[90:93], v[134:137], v[182:185], v[90:93]
	v_mfma_f32_16x16x32_bf16 v[78:81], v[126:129], v[190:193], v[78:81]
	v_mfma_f32_16x16x32_bf16 v[74:77], v[134:137], v[190:193], v[74:77]
	s_setprio 0
	s_setprio 1
	v_mfma_f32_16x16x32_bf16 v[118:121], v[138:141], v[162:165], v[118:121]
	v_mfma_f32_16x16x32_bf16 v[114:117], v[146:149], v[162:165], v[114:117]
	v_mfma_f32_16x16x32_bf16 v[102:105], v[138:141], v[170:173], v[102:105]
	v_mfma_f32_16x16x32_bf16 v[98:101], v[146:149], v[170:173], v[98:101]
	v_mfma_f32_16x16x32_bf16 v[86:89], v[138:141], v[178:181], v[86:89]
	v_mfma_f32_16x16x32_bf16 v[82:85], v[146:149], v[178:181], v[82:85]
	v_mfma_f32_16x16x32_bf16 v[70:73], v[138:141], v[186:189], v[70:73]
	v_mfma_f32_16x16x32_bf16 v[66:69], v[146:149], v[186:189], v[66:69]
	v_mfma_f32_16x16x32_bf16 v[118:121], v[142:145], v[166:169], v[118:121]
	v_mfma_f32_16x16x32_bf16 v[114:117], v[158:161], v[166:169], v[114:117]
	v_mfma_f32_16x16x32_bf16 v[102:105], v[142:145], v[174:177], v[102:105]
	v_mfma_f32_16x16x32_bf16 v[98:101], v[158:161], v[174:177], v[98:101]
	v_mfma_f32_16x16x32_bf16 v[86:89], v[142:145], v[182:185], v[86:89]
	v_mfma_f32_16x16x32_bf16 v[82:85], v[158:161], v[182:185], v[82:85]
	v_mfma_f32_16x16x32_bf16 v[70:73], v[142:145], v[190:193], v[70:73]
	v_mfma_f32_16x16x32_bf16 v[66:69], v[158:161], v[190:193], v[66:69]
	s_setprio 0
	s_barrier
	s_add_i32 s44, s72, s52
	v_lshl_add_u64 v[210:211], v[210:211], 0, s[24:25]
	s_mov_b32 m0, s44
	ds_read_b128 v[162:165], v247 offset:49152
	ds_read_b128 v[166:169], v247 offset:50176
	ds_read_b128 v[170:173], v247 offset:51200
	ds_read_b128 v[174:177], v247 offset:52224
	ds_read_b128 v[178:181], v247 offset:53248
	ds_read_b128 v[182:185], v247 offset:54272
	ds_read_b128 v[186:189], v247 offset:55296
	ds_read_b128 v[190:193], v247 offset:56320
	global_load_lds_dwordx4 v[210:211], off
	s_add_i32 m0, s44, 0x2000
	s_add_u32 s44, s48, 0xb0080
	v_lshl_add_u64 v[210:211], v[212:213], 0, s[24:25]
	s_addc_u32 s45, s49, 0
	s_add_i32 s48, s73, s52
	global_load_lds_dwordx4 v[210:211], off
	v_lshl_add_u64 v[210:211], s[44:45], 0, v[196:197]
	s_mov_b32 m0, s48
	s_nop 0
	global_load_lds_dwordx4 v[210:211], off
	v_lshl_add_u64 v[210:211], s[44:45], 0, v[200:201]
	s_add_i32 m0, s48, 0x2000
	s_nop 0
	global_load_lds_dwordx4 v[210:211], off
	v_lshl_add_u64 v[210:211], v[214:215], 0, s[24:25]
	s_mov_b32 m0, s58
	s_nop 0
	global_load_lds_dwordx4 v[210:211], off
	v_lshl_add_u64 v[210:211], v[216:217], 0, s[24:25]
	s_mov_b32 m0, s59
	s_nop 0
	global_load_lds_dwordx4 v[210:211], off
	s_waitcnt vmcnt(8)
	s_waitcnt lgkmcnt(0)
	s_setprio 1
	s_barrier
	v_mfma_f32_16x16x32_bf16 v[62:65], v[122:125], v[162:165], v[62:65]
	v_mfma_f32_16x16x32_bf16 v[58:61], v[130:133], v[162:165], v[58:61]
	v_mfma_f32_16x16x32_bf16 v[46:49], v[122:125], v[170:173], v[46:49]
	v_mfma_f32_16x16x32_bf16 v[42:45], v[130:133], v[170:173], v[42:45]
	v_mfma_f32_16x16x32_bf16 v[30:33], v[122:125], v[178:181], v[30:33]
	v_mfma_f32_16x16x32_bf16 v[26:29], v[130:133], v[178:181], v[26:29]
	v_mfma_f32_16x16x32_bf16 v[14:17], v[122:125], v[186:189], v[14:17]
	v_mfma_f32_16x16x32_bf16 v[10:13], v[130:133], v[186:189], v[10:13]
	v_mfma_f32_16x16x32_bf16 v[62:65], v[126:129], v[166:169], v[62:65]
	v_mfma_f32_16x16x32_bf16 v[58:61], v[134:137], v[166:169], v[58:61]
	v_mfma_f32_16x16x32_bf16 v[46:49], v[126:129], v[174:177], v[46:49]
	v_mfma_f32_16x16x32_bf16 v[42:45], v[134:137], v[174:177], v[42:45]
	v_mfma_f32_16x16x32_bf16 v[30:33], v[126:129], v[182:185], v[30:33]
	v_mfma_f32_16x16x32_bf16 v[26:29], v[134:137], v[182:185], v[26:29]
	v_mfma_f32_16x16x32_bf16 v[14:17], v[126:129], v[190:193], v[14:17]
	v_mfma_f32_16x16x32_bf16 v[10:13], v[134:137], v[190:193], v[10:13]
	s_setprio 0
	s_setprio 1
	v_mfma_f32_16x16x32_bf16 v[54:57], v[138:141], v[162:165], v[54:57]
	v_mfma_f32_16x16x32_bf16 v[50:53], v[146:149], v[162:165], v[50:53]
	v_mfma_f32_16x16x32_bf16 v[38:41], v[138:141], v[170:173], v[38:41]
	v_mfma_f32_16x16x32_bf16 v[34:37], v[146:149], v[170:173], v[34:37]
	v_mfma_f32_16x16x32_bf16 v[22:25], v[138:141], v[178:181], v[22:25]
	v_mfma_f32_16x16x32_bf16 v[18:21], v[146:149], v[178:181], v[18:21]
	v_mfma_f32_16x16x32_bf16 v[6:9], v[138:141], v[186:189], v[6:9]
	v_mfma_f32_16x16x32_bf16 v[2:5], v[146:149], v[186:189], v[2:5]
	v_mfma_f32_16x16x32_bf16 v[54:57], v[142:145], v[166:169], v[54:57]
	v_mfma_f32_16x16x32_bf16 v[50:53], v[158:161], v[166:169], v[50:53]
	v_mfma_f32_16x16x32_bf16 v[38:41], v[142:145], v[174:177], v[38:41]
	v_mfma_f32_16x16x32_bf16 v[34:37], v[158:161], v[174:177], v[34:37]
	v_mfma_f32_16x16x32_bf16 v[22:25], v[142:145], v[182:185], v[22:25]
	v_mfma_f32_16x16x32_bf16 v[18:21], v[158:161], v[182:185], v[18:21]
	v_mfma_f32_16x16x32_bf16 v[6:9], v[142:145], v[190:193], v[6:9]
	v_mfma_f32_16x16x32_bf16 v[2:5], v[158:161], v[190:193], v[2:5]
	s_setprio 0
	s_add_i32 s71, s71, 2
	s_add_u32 s69, s69, 0x100
	s_addc_u32 s70, s70, 0
	s_cmp_gt_u32 s71, 41
	s_mov_b64 s[44:45], s[46:47]
	s_barrier
	s_cbranch_scc0 .LBB0_251
	s_branch .Lz_post_p2
.LBB0_251:
	ds_read_b128 v[122:125], v245
	ds_read_b128 v[126:129], v245 offset:1024
	ds_read_b128 v[130:133], v245 offset:2048
	ds_read_b128 v[134:137], v245 offset:3072
	ds_read_b128 v[138:141], v246
	ds_read_b128 v[142:145], v246 offset:1024
	ds_read_b128 v[146:149], v246 offset:2048
	ds_read_b128 v[158:161], v246 offset:3072
	s_add_u32 s46, s44, 0x100
	s_addc_u32 s47, s45, 0
	s_cmp_eq_u32 s71, 40
	s_cselect_b32 s51, s9, s47
	s_cselect_b32 s50, s8, s46
	s_cselect_b32 s49, s43, s70
	s_cselect_b32 s48, s42, s69
	v_lshl_add_u64 v[210:211], s[44:45], 0, v[206:207]
	s_add_i32 m0, s53, 0xc000
	ds_read_b128 v[162:165], v247
	ds_read_b128 v[166:169], v247 offset:1024
	ds_read_b128 v[170:173], v247 offset:2048
	ds_read_b128 v[174:177], v247 offset:3072
	ds_read_b128 v[178:181], v247 offset:4096
	ds_read_b128 v[182:185], v247 offset:5120
	ds_read_b128 v[186:189], v247 offset:6144
	ds_read_b128 v[190:193], v247 offset:7168
	global_load_lds_dwordx4 v[210:211], off
	v_lshl_add_u64 v[210:211], s[44:45], 0, v[208:209]
	s_add_i32 m0, s53, 0xe000
	s_nop 0
	global_load_lds_dwordx4 v[210:211], off
	s_waitcnt vmcnt(8)
	s_waitcnt lgkmcnt(0)
	s_setprio 1
	s_barrier
	v_mfma_f32_16x16x32_bf16 v[154:157], v[122:125], v[162:165], v[154:157]
	v_mfma_f32_16x16x32_bf16 v[150:153], v[130:133], v[162:165], v[150:153]
	v_mfma_f32_16x16x32_bf16 v[110:113], v[122:125], v[170:173], v[110:113]
	v_mfma_f32_16x16x32_bf16 v[106:109], v[130:133], v[170:173], v[106:109]
	v_mfma_f32_16x16x32_bf16 v[94:97], v[122:125], v[178:181], v[94:97]
	v_mfma_f32_16x16x32_bf16 v[90:93], v[130:133], v[178:181], v[90:93]
	v_mfma_f32_16x16x32_bf16 v[78:81], v[122:125], v[186:189], v[78:81]
	v_mfma_f32_16x16x32_bf16 v[74:77], v[130:133], v[186:189], v[74:77]
	v_mfma_f32_16x16x32_bf16 v[154:157], v[126:129], v[166:169], v[154:157]
	v_mfma_f32_16x16x32_bf16 v[150:153], v[134:137], v[166:169], v[150:153]
	v_mfma_f32_16x16x32_bf16 v[110:113], v[126:129], v[174:177], v[110:113]
	v_mfma_f32_16x16x32_bf16 v[106:109], v[134:137], v[174:177], v[106:109]
	v_mfma_f32_16x16x32_bf16 v[94:97], v[126:129], v[182:185], v[94:97]
	v_mfma_f32_16x16x32_bf16 v[90:93], v[134:137], v[182:185], v[90:93]
	v_mfma_f32_16x16x32_bf16 v[78:81], v[126:129], v[190:193], v[78:81]
	v_mfma_f32_16x16x32_bf16 v[74:77], v[134:137], v[190:193], v[74:77]
	s_setprio 0
	s_setprio 1
	v_mfma_f32_16x16x32_bf16 v[118:121], v[138:141], v[162:165], v[118:121]
	v_mfma_f32_16x16x32_bf16 v[114:117], v[146:149], v[162:165], v[114:117]
	v_mfma_f32_16x16x32_bf16 v[102:105], v[138:141], v[170:173], v[102:105]
	v_mfma_f32_16x16x32_bf16 v[98:101], v[146:149], v[170:173], v[98:101]
	v_mfma_f32_16x16x32_bf16 v[86:89], v[138:141], v[178:181], v[86:89]
	v_mfma_f32_16x16x32_bf16 v[82:85], v[146:149], v[178:181], v[82:85]
	v_mfma_f32_16x16x32_bf16 v[70:73], v[138:141], v[186:189], v[70:73]
	v_mfma_f32_16x16x32_bf16 v[66:69], v[146:149], v[186:189], v[66:69]
	v_mfma_f32_16x16x32_bf16 v[118:121], v[142:145], v[166:169], v[118:121]
	v_mfma_f32_16x16x32_bf16 v[114:117], v[158:161], v[166:169], v[114:117]
	v_mfma_f32_16x16x32_bf16 v[102:105], v[142:145], v[174:177], v[102:105]
	v_mfma_f32_16x16x32_bf16 v[98:101], v[158:161], v[174:177], v[98:101]
	v_mfma_f32_16x16x32_bf16 v[86:89], v[142:145], v[182:185], v[86:89]
	v_mfma_f32_16x16x32_bf16 v[82:85], v[158:161], v[182:185], v[82:85]
	v_mfma_f32_16x16x32_bf16 v[70:73], v[142:145], v[190:193], v[70:73]
	v_mfma_f32_16x16x32_bf16 v[66:69], v[158:161], v[190:193], v[66:69]
	s_setprio 0
	s_barrier
	s_add_i32 s44, s63, s52
	v_lshl_add_u64 v[210:211], s[48:49], 0, v[196:197]
	s_mov_b32 m0, s44
	ds_read_b128 v[162:165], v247 offset:16384
	ds_read_b128 v[166:169], v247 offset:17408
	ds_read_b128 v[170:173], v247 offset:18432
	ds_read_b128 v[174:177], v247 offset:19456
	ds_read_b128 v[178:181], v247 offset:20480
	ds_read_b128 v[182:185], v247 offset:21504
	ds_read_b128 v[186:189], v247 offset:22528
	ds_read_b128 v[190:193], v247 offset:23552
	global_load_lds_dwordx4 v[210:211], off
	s_add_i32 m0, s44, 0x2000
	s_add_u32 s44, s48, 0xb0000
	v_lshl_add_u64 v[212:213], s[48:49], 0, v[200:201]
	s_addc_u32 s45, s49, 0
	s_add_i32 s72, s64, s52
	global_load_lds_dwordx4 v[212:213], off
	v_lshl_add_u64 v[214:215], s[44:45], 0, v[196:197]
	s_mov_b32 m0, s72
	v_lshl_add_u64 v[216:217], s[50:51], 0, v[198:199]
	global_load_lds_dwordx4 v[214:215], off
	v_lshl_add_u64 v[214:215], s[44:45], 0, v[200:201]
	s_add_i32 m0, s72, 0x2000
	s_nop 0
	global_load_lds_dwordx4 v[214:215], off
	v_lshl_add_u64 v[214:215], s[50:51], 0, v[194:195]
	s_mov_b32 m0, s53
	s_nop 0
	global_load_lds_dwordx4 v[214:215], off
	s_mov_b32 m0, s54
	s_nop 0
	global_load_lds_dwordx4 v[216:217], off
	s_waitcnt vmcnt(8)
	s_waitcnt lgkmcnt(0)
	s_setprio 1
	s_barrier
	v_mfma_f32_16x16x32_bf16 v[62:65], v[122:125], v[162:165], v[62:65]
	v_mfma_f32_16x16x32_bf16 v[58:61], v[130:133], v[162:165], v[58:61]
	v_mfma_f32_16x16x32_bf16 v[46:49], v[122:125], v[170:173], v[46:49]
	v_mfma_f32_16x16x32_bf16 v[42:45], v[130:133], v[170:173], v[42:45]
	v_mfma_f32_16x16x32_bf16 v[30:33], v[122:125], v[178:181], v[30:33]
	v_mfma_f32_16x16x32_bf16 v[26:29], v[130:133], v[178:181], v[26:29]
	v_mfma_f32_16x16x32_bf16 v[14:17], v[122:125], v[186:189], v[14:17]
	v_mfma_f32_16x16x32_bf16 v[10:13], v[130:133], v[186:189], v[10:13]
	v_mfma_f32_16x16x32_bf16 v[62:65], v[126:129], v[166:169], v[62:65]
	v_mfma_f32_16x16x32_bf16 v[58:61], v[134:137], v[166:169], v[58:61]
	v_mfma_f32_16x16x32_bf16 v[46:49], v[126:129], v[174:177], v[46:49]
	v_mfma_f32_16x16x32_bf16 v[42:45], v[134:137], v[174:177], v[42:45]
	v_mfma_f32_16x16x32_bf16 v[30:33], v[126:129], v[182:185], v[30:33]
	v_mfma_f32_16x16x32_bf16 v[26:29], v[134:137], v[182:185], v[26:29]
	v_mfma_f32_16x16x32_bf16 v[14:17], v[126:129], v[190:193], v[14:17]
	v_mfma_f32_16x16x32_bf16 v[10:13], v[134:137], v[190:193], v[10:13]
	s_setprio 0
	s_setprio 1
	v_mfma_f32_16x16x32_bf16 v[54:57], v[138:141], v[162:165], v[54:57]
	v_mfma_f32_16x16x32_bf16 v[50:53], v[146:149], v[162:165], v[50:53]
	v_mfma_f32_16x16x32_bf16 v[38:41], v[138:141], v[170:173], v[38:41]
	v_mfma_f32_16x16x32_bf16 v[34:37], v[146:149], v[170:173], v[34:37]
	v_mfma_f32_16x16x32_bf16 v[22:25], v[138:141], v[178:181], v[22:25]
	v_mfma_f32_16x16x32_bf16 v[18:21], v[146:149], v[178:181], v[18:21]
	v_mfma_f32_16x16x32_bf16 v[6:9], v[138:141], v[186:189], v[6:9]
	v_mfma_f32_16x16x32_bf16 v[2:5], v[146:149], v[186:189], v[2:5]
	v_mfma_f32_16x16x32_bf16 v[54:57], v[142:145], v[166:169], v[54:57]
	v_mfma_f32_16x16x32_bf16 v[50:53], v[158:161], v[166:169], v[50:53]
	v_mfma_f32_16x16x32_bf16 v[38:41], v[142:145], v[174:177], v[38:41]
	v_mfma_f32_16x16x32_bf16 v[34:37], v[158:161], v[174:177], v[34:37]
	v_mfma_f32_16x16x32_bf16 v[22:25], v[142:145], v[182:185], v[22:25]
	v_mfma_f32_16x16x32_bf16 v[18:21], v[158:161], v[182:185], v[18:21]
	v_mfma_f32_16x16x32_bf16 v[6:9], v[142:145], v[190:193], v[6:9]
	v_mfma_f32_16x16x32_bf16 v[2:5], v[158:161], v[190:193], v[2:5]
	s_setprio 0
	s_barrier
	s_add_i32 s72, 0, 0x18000
	s_add_i32 s73, 0, 0x1c000
	v_add_u32_e32 v134, s72, v244
	v_add_u32_e32 v158, s73, v244
	ds_read_b128 v[122:125], v134
	ds_read_b128 v[126:129], v134 offset:1024
	ds_read_b128 v[130:133], v134 offset:2048
	ds_read_b128 v[134:137], v134 offset:3072
	ds_read_b128 v[138:141], v158
	ds_read_b128 v[142:145], v158 offset:1024
	ds_read_b128 v[146:149], v158 offset:2048
	ds_read_b128 v[158:161], v158 offset:3072
	s_add_u32 s44, s50, 0xb0000
	s_addc_u32 s45, s51, 0
	s_mov_b32 m0, s55
	v_lshl_add_u64 v[218:219], s[44:45], 0, v[194:195]
	ds_read_b128 v[162:165], v247 offset:32768
	ds_read_b128 v[166:169], v247 offset:33792
	ds_read_b128 v[170:173], v247 offset:34816
	ds_read_b128 v[174:177], v247 offset:35840
	ds_read_b128 v[178:181], v247 offset:36864
	ds_read_b128 v[182:185], v247 offset:37888
	ds_read_b128 v[186:189], v247 offset:38912
	ds_read_b128 v[190:193], v247 offset:39936
	global_load_lds_dwordx4 v[218:219], off
	v_lshl_add_u64 v[218:219], s[44:45], 0, v[198:199]
	s_mov_b32 m0, s56
	s_nop 0
	global_load_lds_dwordx4 v[218:219], off
	s_waitcnt vmcnt(8)
	s_waitcnt lgkmcnt(0)
	s_setprio 1
	s_barrier
	v_mfma_f32_16x16x32_bf16 v[154:157], v[122:125], v[162:165], v[154:157]
	v_mfma_f32_16x16x32_bf16 v[150:153], v[130:133], v[162:165], v[150:153]
	v_mfma_f32_16x16x32_bf16 v[110:113], v[122:125], v[170:173], v[110:113]
	v_mfma_f32_16x16x32_bf16 v[106:109], v[130:133], v[170:173], v[106:109]
	v_mfma_f32_16x16x32_bf16 v[94:97], v[122:125], v[178:181], v[94:97]
	v_mfma_f32_16x16x32_bf16 v[90:93], v[130:133], v[178:181], v[90:93]
	v_mfma_f32_16x16x32_bf16 v[78:81], v[122:125], v[186:189], v[78:81]
	v_mfma_f32_16x16x32_bf16 v[74:77], v[130:133], v[186:189], v[74:77]
	v_mfma_f32_16x16x32_bf16 v[154:157], v[126:129], v[166:169], v[154:157]
	v_mfma_f32_16x16x32_bf16 v[150:153], v[134:137], v[166:169], v[150:153]
	v_mfma_f32_16x16x32_bf16 v[110:113], v[126:129], v[174:177], v[110:113]
	v_mfma_f32_16x16x32_bf16 v[106:109], v[134:137], v[174:177], v[106:109]
	v_mfma_f32_16x16x32_bf16 v[94:97], v[126:129], v[182:185], v[94:97]
	v_mfma_f32_16x16x32_bf16 v[90:93], v[134:137], v[182:185], v[90:93]
	v_mfma_f32_16x16x32_bf16 v[78:81], v[126:129], v[190:193], v[78:81]
	v_mfma_f32_16x16x32_bf16 v[74:77], v[134:137], v[190:193], v[74:77]
	s_setprio 0
	s_setprio 1
	v_mfma_f32_16x16x32_bf16 v[118:121], v[138:141], v[162:165], v[118:121]
	v_mfma_f32_16x16x32_bf16 v[114:117], v[146:149], v[162:165], v[114:117]
	v_mfma_f32_16x16x32_bf16 v[102:105], v[138:141], v[170:173], v[102:105]
	v_mfma_f32_16x16x32_bf16 v[98:101], v[146:149], v[170:173], v[98:101]
	v_mfma_f32_16x16x32_bf16 v[86:89], v[138:141], v[178:181], v[86:89]
	v_mfma_f32_16x16x32_bf16 v[82:85], v[146:149], v[178:181], v[82:85]
	v_mfma_f32_16x16x32_bf16 v[70:73], v[138:141], v[186:189], v[70:73]
	v_mfma_f32_16x16x32_bf16 v[66:69], v[146:149], v[186:189], v[66:69]
	v_mfma_f32_16x16x32_bf16 v[118:121], v[142:145], v[166:169], v[118:121]
	v_mfma_f32_16x16x32_bf16 v[114:117], v[158:161], v[166:169], v[114:117]
	v_mfma_f32_16x16x32_bf16 v[102:105], v[142:145], v[174:177], v[102:105]
	v_mfma_f32_16x16x32_bf16 v[98:101], v[158:161], v[174:177], v[98:101]
	v_mfma_f32_16x16x32_bf16 v[86:89], v[142:145], v[182:185], v[86:89]
	v_mfma_f32_16x16x32_bf16 v[82:85], v[158:161], v[182:185], v[82:85]
	v_mfma_f32_16x16x32_bf16 v[70:73], v[142:145], v[190:193], v[70:73]
	v_mfma_f32_16x16x32_bf16 v[66:69], v[158:161], v[190:193], v[66:69]
	s_setprio 0
	s_barrier
	s_add_i32 s44, s72, s52
	v_lshl_add_u64 v[210:211], v[210:211], 0, s[24:25]
	s_mov_b32 m0, s44
	ds_read_b128 v[162:165], v247 offset:49152
	ds_read_b128 v[166:169], v247 offset:50176
	ds_read_b128 v[170:173], v247 offset:51200
	ds_read_b128 v[174:177], v247 offset:52224
	ds_read_b128 v[178:181], v247 offset:53248
	ds_read_b128 v[182:185], v247 offset:54272
	ds_read_b128 v[186:189], v247 offset:55296
	ds_read_b128 v[190:193], v247 offset:56320
	global_load_lds_dwordx4 v[210:211], off
	s_add_i32 m0, s44, 0x2000
	s_add_u32 s44, s48, 0xb0080
	v_lshl_add_u64 v[210:211], v[212:213], 0, s[24:25]
	s_addc_u32 s45, s49, 0
	s_add_i32 s48, s73, s52
	global_load_lds_dwordx4 v[210:211], off
	v_lshl_add_u64 v[210:211], s[44:45], 0, v[196:197]
	s_mov_b32 m0, s48
	s_nop 0
	global_load_lds_dwordx4 v[210:211], off
	v_lshl_add_u64 v[210:211], s[44:45], 0, v[200:201]
	s_add_i32 m0, s48, 0x2000
	s_nop 0
	global_load_lds_dwordx4 v[210:211], off
	v_lshl_add_u64 v[210:211], v[214:215], 0, s[24:25]
	s_mov_b32 m0, s58
	s_nop 0
	global_load_lds_dwordx4 v[210:211], off
	v_lshl_add_u64 v[210:211], v[216:217], 0, s[24:25]
	s_mov_b32 m0, s59
	s_nop 0
	global_load_lds_dwordx4 v[210:211], off
	s_waitcnt vmcnt(8)
	s_waitcnt lgkmcnt(0)
	s_setprio 1
	s_barrier
	v_mfma_f32_16x16x32_bf16 v[62:65], v[122:125], v[162:165], v[62:65]
	v_mfma_f32_16x16x32_bf16 v[58:61], v[130:133], v[162:165], v[58:61]
	v_mfma_f32_16x16x32_bf16 v[46:49], v[122:125], v[170:173], v[46:49]
	v_mfma_f32_16x16x32_bf16 v[42:45], v[130:133], v[170:173], v[42:45]
	v_mfma_f32_16x16x32_bf16 v[30:33], v[122:125], v[178:181], v[30:33]
	v_mfma_f32_16x16x32_bf16 v[26:29], v[130:133], v[178:181], v[26:29]
	v_mfma_f32_16x16x32_bf16 v[14:17], v[122:125], v[186:189], v[14:17]
	v_mfma_f32_16x16x32_bf16 v[10:13], v[130:133], v[186:189], v[10:13]
	v_mfma_f32_16x16x32_bf16 v[62:65], v[126:129], v[166:169], v[62:65]
	v_mfma_f32_16x16x32_bf16 v[58:61], v[134:137], v[166:169], v[58:61]
	v_mfma_f32_16x16x32_bf16 v[46:49], v[126:129], v[174:177], v[46:49]
	v_mfma_f32_16x16x32_bf16 v[42:45], v[134:137], v[174:177], v[42:45]
	v_mfma_f32_16x16x32_bf16 v[30:33], v[126:129], v[182:185], v[30:33]
	v_mfma_f32_16x16x32_bf16 v[26:29], v[134:137], v[182:185], v[26:29]
	v_mfma_f32_16x16x32_bf16 v[14:17], v[126:129], v[190:193], v[14:17]
	v_mfma_f32_16x16x32_bf16 v[10:13], v[134:137], v[190:193], v[10:13]
	s_setprio 0
	s_setprio 1
	v_mfma_f32_16x16x32_bf16 v[54:57], v[138:141], v[162:165], v[54:57]
	v_mfma_f32_16x16x32_bf16 v[50:53], v[146:149], v[162:165], v[50:53]
	v_mfma_f32_16x16x32_bf16 v[38:41], v[138:141], v[170:173], v[38:41]
	v_mfma_f32_16x16x32_bf16 v[34:37], v[146:149], v[170:173], v[34:37]
	v_mfma_f32_16x16x32_bf16 v[22:25], v[138:141], v[178:181], v[22:25]
	v_mfma_f32_16x16x32_bf16 v[18:21], v[146:149], v[178:181], v[18:21]
	v_mfma_f32_16x16x32_bf16 v[6:9], v[138:141], v[186:189], v[6:9]
	v_mfma_f32_16x16x32_bf16 v[2:5], v[146:149], v[186:189], v[2:5]
	v_mfma_f32_16x16x32_bf16 v[54:57], v[142:145], v[166:169], v[54:57]
	v_mfma_f32_16x16x32_bf16 v[50:53], v[158:161], v[166:169], v[50:53]
	v_mfma_f32_16x16x32_bf16 v[38:41], v[142:145], v[174:177], v[38:41]
	v_mfma_f32_16x16x32_bf16 v[34:37], v[158:161], v[174:177], v[34:37]
	v_mfma_f32_16x16x32_bf16 v[22:25], v[142:145], v[182:185], v[22:25]
	v_mfma_f32_16x16x32_bf16 v[18:21], v[158:161], v[182:185], v[18:21]
	v_mfma_f32_16x16x32_bf16 v[6:9], v[142:145], v[190:193], v[6:9]
	v_mfma_f32_16x16x32_bf16 v[2:5], v[158:161], v[190:193], v[2:5]
	s_setprio 0
	s_add_i32 s71, s71, 2
	s_add_u32 s69, s69, 0x100
	s_addc_u32 s70, s70, 0
	s_cmp_gt_u32 s71, 41
	s_mov_b64 s[44:45], s[46:47]
	s_barrier
	s_cbranch_scc0 .LBB0_251

.LBB0_351:
	s_ashr_i32 s43, s42, 31
	s_lshl_b64 s[44:45], s[42:43], 19
	s_add_u32 s44, s3, s44
	s_addc_u32 s45, s23, s45
	s_and_b64 s[46:47], s[4:5], exec
	s_cselect_b32 s7, s45, s49
	s_cselect_b32 s43, s44, s48
	s_ashr_i32 s27, s26, 31
	s_lshl_b64 s[46:47], s[26:27], 19
	s_add_u32 s46, s29, s46
	s_addc_u32 s47, s31, s47
	s_and_b64 s[52:53], s[4:5], exec
	s_cselect_b32 s27, s47, s51
	s_cselect_b32 s70, s46, s50
	s_add_u32 s48, s48, 0x40080
	s_addc_u32 s49, s49, 0
	s_add_u32 s71, s50, 0x100
	s_addc_u32 s72, s51, 0
	s_mov_b32 s73, -2
	ds_read_b128 v[156:159], v152
	ds_read_b128 v[160:163], v152 offset:1024
	ds_read_b128 v[164:167], v152 offset:2048
	ds_read_b128 v[168:171], v152 offset:3072
	ds_read_b128 v[172:175], v153
	ds_read_b128 v[176:179], v153 offset:1024
	ds_read_b128 v[180:183], v153 offset:2048
	ds_read_b128 v[184:187], v153 offset:3072
	s_add_u32 s50, s48, 0xfffc0080
	s_addc_u32 s51, s49, -1
	s_cmp_eq_u32 s73, 12
	s_cselect_b32 s53, s7, s51
	s_cselect_b32 s52, s43, s50
	s_cselect_b32 s51, s27, s72
	s_cselect_b32 s50, s70, s71
	v_lshl_add_u64 v[148:149], s[48:49], 0, v[140:141]
	s_add_i32 m0, s57, 0xc000
	ds_read_b128 v[188:191], v154
	ds_read_b128 v[192:195], v154 offset:1024
	ds_read_b128 v[196:199], v154 offset:2048
	ds_read_b128 v[200:203], v154 offset:3072
	ds_read_b128 v[204:207], v154 offset:4096
	ds_read_b128 v[208:211], v154 offset:5120
	ds_read_b128 v[212:215], v154 offset:6144
	ds_read_b128 v[216:219], v154 offset:7168
	global_load_lds_dwordx4 v[148:149], off
	v_lshl_add_u64 v[148:149], s[48:49], 0, v[142:143]
	s_add_i32 m0, s57, 0xe000
	s_nop 0
	global_load_lds_dwordx4 v[148:149], off
	s_waitcnt vmcnt(8)
	s_waitcnt lgkmcnt(0)
	s_setprio 1
	s_barrier
	v_mfma_f32_16x16x32_bf16 v[126:129], v[156:159], v[188:191], 0
	v_mfma_f32_16x16x32_bf16 v[122:125], v[164:167], v[188:191], 0
	v_mfma_f32_16x16x32_bf16 v[110:113], v[156:159], v[196:199], 0
	v_mfma_f32_16x16x32_bf16 v[106:109], v[164:167], v[196:199], 0
	v_mfma_f32_16x16x32_bf16 v[94:97], v[156:159], v[204:207], 0
	v_mfma_f32_16x16x32_bf16 v[90:93], v[164:167], v[204:207], 0
	v_mfma_f32_16x16x32_bf16 v[78:81], v[156:159], v[212:215], 0
	v_mfma_f32_16x16x32_bf16 v[74:77], v[164:167], v[212:215], 0
	v_mfma_f32_16x16x32_bf16 v[126:129], v[160:163], v[192:195], v[126:129]
	v_mfma_f32_16x16x32_bf16 v[122:125], v[168:171], v[192:195], v[122:125]
	v_mfma_f32_16x16x32_bf16 v[110:113], v[160:163], v[200:203], v[110:113]
	v_mfma_f32_16x16x32_bf16 v[106:109], v[168:171], v[200:203], v[106:109]
	v_mfma_f32_16x16x32_bf16 v[94:97], v[160:163], v[208:211], v[94:97]
	v_mfma_f32_16x16x32_bf16 v[90:93], v[168:171], v[208:211], v[90:93]
	v_mfma_f32_16x16x32_bf16 v[78:81], v[160:163], v[216:219], v[78:81]
	v_mfma_f32_16x16x32_bf16 v[74:77], v[168:171], v[216:219], v[74:77]
	s_setprio 0
	s_setprio 1
	v_mfma_f32_16x16x32_bf16 v[118:121], v[172:175], v[188:191], 0
	v_mfma_f32_16x16x32_bf16 v[114:117], v[180:183], v[188:191], 0
	v_mfma_f32_16x16x32_bf16 v[102:105], v[172:175], v[196:199], 0
	v_mfma_f32_16x16x32_bf16 v[98:101], v[180:183], v[196:199], 0
	v_mfma_f32_16x16x32_bf16 v[86:89], v[172:175], v[204:207], 0
	v_mfma_f32_16x16x32_bf16 v[82:85], v[180:183], v[204:207], 0
	v_mfma_f32_16x16x32_bf16 v[70:73], v[172:175], v[212:215], 0
	v_mfma_f32_16x16x32_bf16 v[66:69], v[180:183], v[212:215], 0
	v_mfma_f32_16x16x32_bf16 v[118:121], v[176:179], v[192:195], v[118:121]
	v_mfma_f32_16x16x32_bf16 v[114:117], v[184:187], v[192:195], v[114:117]
	v_mfma_f32_16x16x32_bf16 v[102:105], v[176:179], v[200:203], v[102:105]
	v_mfma_f32_16x16x32_bf16 v[98:101], v[184:187], v[200:203], v[98:101]
	v_mfma_f32_16x16x32_bf16 v[86:89], v[176:179], v[208:211], v[86:89]
	v_mfma_f32_16x16x32_bf16 v[82:85], v[184:187], v[208:211], v[82:85]
	v_mfma_f32_16x16x32_bf16 v[70:73], v[176:179], v[216:219], v[70:73]
	v_mfma_f32_16x16x32_bf16 v[66:69], v[184:187], v[216:219], v[66:69]
	s_setprio 0
	s_barrier
	s_add_i32 s74, s67, s54
	v_lshl_add_u64 v[148:149], s[50:51], 0, v[134:135]
	s_mov_b32 m0, s74
	ds_read_b128 v[188:191], v154 offset:16384
	ds_read_b128 v[192:195], v154 offset:17408
	ds_read_b128 v[196:199], v154 offset:18432
	ds_read_b128 v[200:203], v154 offset:19456
	ds_read_b128 v[204:207], v154 offset:20480
	ds_read_b128 v[208:211], v154 offset:21504
	ds_read_b128 v[212:215], v154 offset:22528
	ds_read_b128 v[216:219], v154 offset:23552
	global_load_lds_dwordx4 v[148:149], off
	s_add_i32 m0, s74, 0x2000
	s_add_u32 s74, s50, 0x40000
	v_lshl_add_u64 v[220:221], s[50:51], 0, v[130:131]
	s_addc_u32 s75, s51, 0
	s_add_i32 s76, s68, s54
	global_load_lds_dwordx4 v[220:221], off
	v_lshl_add_u64 v[222:223], s[74:75], 0, v[134:135]
	s_mov_b32 m0, s76
	v_lshl_add_u64 v[224:225], s[52:53], 0, v[132:133]
	global_load_lds_dwordx4 v[222:223], off
	v_lshl_add_u64 v[222:223], s[74:75], 0, v[130:131]
	s_add_i32 m0, s76, 0x2000
	s_nop 0
	global_load_lds_dwordx4 v[222:223], off
	v_lshl_add_u64 v[222:223], s[52:53], 0, v[136:137]
	s_mov_b32 m0, s57
	s_nop 0
	global_load_lds_dwordx4 v[222:223], off
	s_mov_b32 m0, s58
	s_nop 0
	global_load_lds_dwordx4 v[224:225], off
	s_waitcnt vmcnt(8)
	s_waitcnt lgkmcnt(0)
	s_setprio 1
	s_barrier
	v_mfma_f32_16x16x32_bf16 v[62:65], v[156:159], v[188:191], 0
	v_mfma_f32_16x16x32_bf16 v[58:61], v[164:167], v[188:191], 0
	v_mfma_f32_16x16x32_bf16 v[46:49], v[156:159], v[196:199], 0
	v_mfma_f32_16x16x32_bf16 v[42:45], v[164:167], v[196:199], 0
	v_mfma_f32_16x16x32_bf16 v[30:33], v[156:159], v[204:207], 0
	v_mfma_f32_16x16x32_bf16 v[26:29], v[164:167], v[204:207], 0
	v_mfma_f32_16x16x32_bf16 v[14:17], v[156:159], v[212:215], 0
	v_mfma_f32_16x16x32_bf16 v[10:13], v[164:167], v[212:215], 0
	v_mfma_f32_16x16x32_bf16 v[62:65], v[160:163], v[192:195], v[62:65]
	v_mfma_f32_16x16x32_bf16 v[58:61], v[168:171], v[192:195], v[58:61]
	v_mfma_f32_16x16x32_bf16 v[46:49], v[160:163], v[200:203], v[46:49]
	v_mfma_f32_16x16x32_bf16 v[42:45], v[168:171], v[200:203], v[42:45]
	v_mfma_f32_16x16x32_bf16 v[30:33], v[160:163], v[208:211], v[30:33]
	v_mfma_f32_16x16x32_bf16 v[26:29], v[168:171], v[208:211], v[26:29]
	v_mfma_f32_16x16x32_bf16 v[14:17], v[160:163], v[216:219], v[14:17]
	v_mfma_f32_16x16x32_bf16 v[10:13], v[168:171], v[216:219], v[10:13]
	s_setprio 0
	s_setprio 1
	v_mfma_f32_16x16x32_bf16 v[54:57], v[172:175], v[188:191], 0
	v_mfma_f32_16x16x32_bf16 v[50:53], v[180:183], v[188:191], 0
	v_mfma_f32_16x16x32_bf16 v[38:41], v[172:175], v[196:199], 0
	v_mfma_f32_16x16x32_bf16 v[34:37], v[180:183], v[196:199], 0
	v_mfma_f32_16x16x32_bf16 v[22:25], v[172:175], v[204:207], 0
	v_mfma_f32_16x16x32_bf16 v[18:21], v[180:183], v[204:207], 0
	v_mfma_f32_16x16x32_bf16 v[6:9], v[172:175], v[212:215], 0
	v_mfma_f32_16x16x32_bf16 v[2:5], v[180:183], v[212:215], 0
	v_mfma_f32_16x16x32_bf16 v[54:57], v[176:179], v[192:195], v[54:57]
	v_mfma_f32_16x16x32_bf16 v[50:53], v[184:187], v[192:195], v[50:53]
	v_mfma_f32_16x16x32_bf16 v[38:41], v[176:179], v[200:203], v[38:41]
	v_mfma_f32_16x16x32_bf16 v[34:37], v[184:187], v[200:203], v[34:37]
	v_mfma_f32_16x16x32_bf16 v[22:25], v[176:179], v[208:211], v[22:25]
	v_mfma_f32_16x16x32_bf16 v[18:21], v[184:187], v[208:211], v[18:21]
	v_mfma_f32_16x16x32_bf16 v[6:9], v[176:179], v[216:219], v[6:9]
	v_mfma_f32_16x16x32_bf16 v[2:5], v[184:187], v[216:219], v[2:5]
	s_setprio 0
	s_barrier
	s_add_i32 s74, 0, 0x18000
	s_add_i32 s75, 0, 0x1c000
	v_add_u32_e32 v168, s74, v151
	v_add_u32_e32 v184, s75, v151
	ds_read_b128 v[156:159], v168
	ds_read_b128 v[160:163], v168 offset:1024
	ds_read_b128 v[164:167], v168 offset:2048
	ds_read_b128 v[168:171], v168 offset:3072
	ds_read_b128 v[172:175], v184
	ds_read_b128 v[176:179], v184 offset:1024
	ds_read_b128 v[180:183], v184 offset:2048
	ds_read_b128 v[184:187], v184 offset:3072
	s_add_u32 s52, s52, 0x40000
	s_addc_u32 s53, s53, 0
	s_mov_b32 m0, s59
	v_lshl_add_u64 v[226:227], s[52:53], 0, v[136:137]
	ds_read_b128 v[188:191], v154 offset:32768
	ds_read_b128 v[192:195], v154 offset:33792
	ds_read_b128 v[196:199], v154 offset:34816
	ds_read_b128 v[200:203], v154 offset:35840
	ds_read_b128 v[204:207], v154 offset:36864
	ds_read_b128 v[208:211], v154 offset:37888
	ds_read_b128 v[212:215], v154 offset:38912
	ds_read_b128 v[216:219], v154 offset:39936
	global_load_lds_dwordx4 v[226:227], off
	v_lshl_add_u64 v[226:227], s[52:53], 0, v[132:133]
	s_mov_b32 m0, s60
	s_nop 0
	global_load_lds_dwordx4 v[226:227], off
	s_waitcnt vmcnt(8)
	s_waitcnt lgkmcnt(0)
	s_setprio 1
	s_barrier
	v_mfma_f32_16x16x32_bf16 v[126:129], v[156:159], v[188:191], v[126:129]
	v_mfma_f32_16x16x32_bf16 v[122:125], v[164:167], v[188:191], v[122:125]
	v_mfma_f32_16x16x32_bf16 v[110:113], v[156:159], v[196:199], v[110:113]
	v_mfma_f32_16x16x32_bf16 v[106:109], v[164:167], v[196:199], v[106:109]
	v_mfma_f32_16x16x32_bf16 v[94:97], v[156:159], v[204:207], v[94:97]
	v_mfma_f32_16x16x32_bf16 v[90:93], v[164:167], v[204:207], v[90:93]
	v_mfma_f32_16x16x32_bf16 v[78:81], v[156:159], v[212:215], v[78:81]
	v_mfma_f32_16x16x32_bf16 v[74:77], v[164:167], v[212:215], v[74:77]
	v_mfma_f32_16x16x32_bf16 v[126:129], v[160:163], v[192:195], v[126:129]
	v_mfma_f32_16x16x32_bf16 v[122:125], v[168:171], v[192:195], v[122:125]
	v_mfma_f32_16x16x32_bf16 v[110:113], v[160:163], v[200:203], v[110:113]
	v_mfma_f32_16x16x32_bf16 v[106:109], v[168:171], v[200:203], v[106:109]
	v_mfma_f32_16x16x32_bf16 v[94:97], v[160:163], v[208:211], v[94:97]
	v_mfma_f32_16x16x32_bf16 v[90:93], v[168:171], v[208:211], v[90:93]
	v_mfma_f32_16x16x32_bf16 v[78:81], v[160:163], v[216:219], v[78:81]
	v_mfma_f32_16x16x32_bf16 v[74:77], v[168:171], v[216:219], v[74:77]
	s_setprio 0
	s_setprio 1
	v_mfma_f32_16x16x32_bf16 v[118:121], v[172:175], v[188:191], v[118:121]
	v_mfma_f32_16x16x32_bf16 v[114:117], v[180:183], v[188:191], v[114:117]
	v_mfma_f32_16x16x32_bf16 v[102:105], v[172:175], v[196:199], v[102:105]
	v_mfma_f32_16x16x32_bf16 v[98:101], v[180:183], v[196:199], v[98:101]
	v_mfma_f32_16x16x32_bf16 v[86:89], v[172:175], v[204:207], v[86:89]
	v_mfma_f32_16x16x32_bf16 v[82:85], v[180:183], v[204:207], v[82:85]
	v_mfma_f32_16x16x32_bf16 v[70:73], v[172:175], v[212:215], v[70:73]
	v_mfma_f32_16x16x32_bf16 v[66:69], v[180:183], v[212:215], v[66:69]
	v_mfma_f32_16x16x32_bf16 v[118:121], v[176:179], v[192:195], v[118:121]
	v_mfma_f32_16x16x32_bf16 v[114:117], v[184:187], v[192:195], v[114:117]
	v_mfma_f32_16x16x32_bf16 v[102:105], v[176:179], v[200:203], v[102:105]
	v_mfma_f32_16x16x32_bf16 v[98:101], v[184:187], v[200:203], v[98:101]
	v_mfma_f32_16x16x32_bf16 v[86:89], v[176:179], v[208:211], v[86:89]
	v_mfma_f32_16x16x32_bf16 v[82:85], v[184:187], v[208:211], v[82:85]
	v_mfma_f32_16x16x32_bf16 v[70:73], v[176:179], v[216:219], v[70:73]
	v_mfma_f32_16x16x32_bf16 v[66:69], v[184:187], v[216:219], v[66:69]
	s_setprio 0
	s_barrier
	s_add_i32 s52, s74, s54
	v_lshl_add_u64 v[148:149], v[148:149], 0, s[16:17]
	s_mov_b32 m0, s52
	ds_read_b128 v[188:191], v154 offset:49152
	ds_read_b128 v[192:195], v154 offset:50176
	ds_read_b128 v[196:199], v154 offset:51200
	ds_read_b128 v[200:203], v154 offset:52224
	ds_read_b128 v[204:207], v154 offset:53248
	ds_read_b128 v[208:211], v154 offset:54272
	ds_read_b128 v[212:215], v154 offset:55296
	ds_read_b128 v[216:219], v154 offset:56320
	global_load_lds_dwordx4 v[148:149], off
	s_add_i32 m0, s52, 0x2000
	s_add_u32 s50, s50, 0x40080
	v_lshl_add_u64 v[148:149], v[220:221], 0, s[16:17]
	s_addc_u32 s51, s51, 0
	s_add_i32 s52, s75, s54
	global_load_lds_dwordx4 v[148:149], off
	v_lshl_add_u64 v[148:149], s[50:51], 0, v[134:135]
	s_mov_b32 m0, s52
	s_nop 0
	global_load_lds_dwordx4 v[148:149], off
	v_lshl_add_u64 v[148:149], s[50:51], 0, v[130:131]
	s_add_i32 m0, s52, 0x2000
	s_nop 0
	global_load_lds_dwordx4 v[148:149], off
	v_lshl_add_u64 v[148:149], v[222:223], 0, s[16:17]
	s_mov_b32 m0, s63
	s_nop 0
	global_load_lds_dwordx4 v[148:149], off
	v_lshl_add_u64 v[148:149], v[224:225], 0, s[16:17]
	s_mov_b32 m0, s64
	s_nop 0
	global_load_lds_dwordx4 v[148:149], off
	s_waitcnt vmcnt(8)
	s_waitcnt lgkmcnt(0)
	s_setprio 1
	s_barrier
	v_mfma_f32_16x16x32_bf16 v[62:65], v[156:159], v[188:191], v[62:65]
	v_mfma_f32_16x16x32_bf16 v[58:61], v[164:167], v[188:191], v[58:61]
	v_mfma_f32_16x16x32_bf16 v[46:49], v[156:159], v[196:199], v[46:49]
	v_mfma_f32_16x16x32_bf16 v[42:45], v[164:167], v[196:199], v[42:45]
	v_mfma_f32_16x16x32_bf16 v[30:33], v[156:159], v[204:207], v[30:33]
	v_mfma_f32_16x16x32_bf16 v[26:29], v[164:167], v[204:207], v[26:29]
	v_mfma_f32_16x16x32_bf16 v[14:17], v[156:159], v[212:215], v[14:17]
	v_mfma_f32_16x16x32_bf16 v[10:13], v[164:167], v[212:215], v[10:13]
	v_mfma_f32_16x16x32_bf16 v[62:65], v[160:163], v[192:195], v[62:65]
	v_mfma_f32_16x16x32_bf16 v[58:61], v[168:171], v[192:195], v[58:61]
	v_mfma_f32_16x16x32_bf16 v[46:49], v[160:163], v[200:203], v[46:49]
	v_mfma_f32_16x16x32_bf16 v[42:45], v[168:171], v[200:203], v[42:45]
	v_mfma_f32_16x16x32_bf16 v[30:33], v[160:163], v[208:211], v[30:33]
	v_mfma_f32_16x16x32_bf16 v[26:29], v[168:171], v[208:211], v[26:29]
	v_mfma_f32_16x16x32_bf16 v[14:17], v[160:163], v[216:219], v[14:17]
	v_mfma_f32_16x16x32_bf16 v[10:13], v[168:171], v[216:219], v[10:13]
	s_setprio 0
	s_setprio 1
	v_mfma_f32_16x16x32_bf16 v[54:57], v[172:175], v[188:191], v[54:57]
	v_mfma_f32_16x16x32_bf16 v[50:53], v[180:183], v[188:191], v[50:53]
	v_mfma_f32_16x16x32_bf16 v[38:41], v[172:175], v[196:199], v[38:41]
	v_mfma_f32_16x16x32_bf16 v[34:37], v[180:183], v[196:199], v[34:37]
	v_mfma_f32_16x16x32_bf16 v[22:25], v[172:175], v[204:207], v[22:25]
	v_mfma_f32_16x16x32_bf16 v[18:21], v[180:183], v[204:207], v[18:21]
	v_mfma_f32_16x16x32_bf16 v[6:9], v[172:175], v[212:215], v[6:9]
	v_mfma_f32_16x16x32_bf16 v[2:5], v[180:183], v[212:215], v[2:5]
	v_mfma_f32_16x16x32_bf16 v[54:57], v[176:179], v[192:195], v[54:57]
	v_mfma_f32_16x16x32_bf16 v[50:53], v[184:187], v[192:195], v[50:53]
	v_mfma_f32_16x16x32_bf16 v[38:41], v[176:179], v[200:203], v[38:41]
	v_mfma_f32_16x16x32_bf16 v[34:37], v[184:187], v[200:203], v[34:37]
	v_mfma_f32_16x16x32_bf16 v[22:25], v[176:179], v[208:211], v[22:25]
	v_mfma_f32_16x16x32_bf16 v[18:21], v[184:187], v[208:211], v[18:21]
	v_mfma_f32_16x16x32_bf16 v[6:9], v[176:179], v[216:219], v[6:9]
	v_mfma_f32_16x16x32_bf16 v[2:5], v[184:187], v[216:219], v[2:5]
	s_setprio 0
	s_add_i32 s73, s73, 2
	s_add_u32 s48, s48, 0x100
	s_addc_u32 s49, s49, 0
	s_add_u32 s71, s71, 0x100
	s_addc_u32 s72, s72, 0
	s_cmp_gt_u32 s73, 13
	s_barrier
	s_cbranch_scc0 .LBB0_352
	s_branch .Lz_post_p3
.LBB0_352:
	ds_read_b128 v[156:159], v152
	ds_read_b128 v[160:163], v152 offset:1024
	ds_read_b128 v[164:167], v152 offset:2048
	ds_read_b128 v[168:171], v152 offset:3072
	ds_read_b128 v[172:175], v153
	ds_read_b128 v[176:179], v153 offset:1024
	ds_read_b128 v[180:183], v153 offset:2048
	ds_read_b128 v[184:187], v153 offset:3072
	s_add_u32 s50, s48, 0xfffc0080
	s_addc_u32 s51, s49, -1
	s_cmp_eq_u32 s73, 12
	s_cselect_b32 s53, s7, s51
	s_cselect_b32 s52, s43, s50
	s_cselect_b32 s51, s27, s72
	s_cselect_b32 s50, s70, s71
	v_lshl_add_u64 v[148:149], s[48:49], 0, v[140:141]
	s_add_i32 m0, s57, 0xc000
	ds_read_b128 v[188:191], v154
	ds_read_b128 v[192:195], v154 offset:1024
	ds_read_b128 v[196:199], v154 offset:2048
	ds_read_b128 v[200:203], v154 offset:3072
	ds_read_b128 v[204:207], v154 offset:4096
	ds_read_b128 v[208:211], v154 offset:5120
	ds_read_b128 v[212:215], v154 offset:6144
	ds_read_b128 v[216:219], v154 offset:7168
	global_load_lds_dwordx4 v[148:149], off
	v_lshl_add_u64 v[148:149], s[48:49], 0, v[142:143]
	s_add_i32 m0, s57, 0xe000
	s_nop 0
	global_load_lds_dwordx4 v[148:149], off
	s_waitcnt vmcnt(8)
	s_waitcnt lgkmcnt(0)
	s_setprio 1
	s_barrier
	v_mfma_f32_16x16x32_bf16 v[126:129], v[156:159], v[188:191], v[126:129]
	v_mfma_f32_16x16x32_bf16 v[122:125], v[164:167], v[188:191], v[122:125]
	v_mfma_f32_16x16x32_bf16 v[110:113], v[156:159], v[196:199], v[110:113]
	v_mfma_f32_16x16x32_bf16 v[106:109], v[164:167], v[196:199], v[106:109]
	v_mfma_f32_16x16x32_bf16 v[94:97], v[156:159], v[204:207], v[94:97]
	v_mfma_f32_16x16x32_bf16 v[90:93], v[164:167], v[204:207], v[90:93]
	v_mfma_f32_16x16x32_bf16 v[78:81], v[156:159], v[212:215], v[78:81]
	v_mfma_f32_16x16x32_bf16 v[74:77], v[164:167], v[212:215], v[74:77]
	v_mfma_f32_16x16x32_bf16 v[126:129], v[160:163], v[192:195], v[126:129]
	v_mfma_f32_16x16x32_bf16 v[122:125], v[168:171], v[192:195], v[122:125]
	v_mfma_f32_16x16x32_bf16 v[110:113], v[160:163], v[200:203], v[110:113]
	v_mfma_f32_16x16x32_bf16 v[106:109], v[168:171], v[200:203], v[106:109]
	v_mfma_f32_16x16x32_bf16 v[94:97], v[160:163], v[208:211], v[94:97]
	v_mfma_f32_16x16x32_bf16 v[90:93], v[168:171], v[208:211], v[90:93]
	v_mfma_f32_16x16x32_bf16 v[78:81], v[160:163], v[216:219], v[78:81]
	v_mfma_f32_16x16x32_bf16 v[74:77], v[168:171], v[216:219], v[74:77]
	s_setprio 0
	s_setprio 1
	v_mfma_f32_16x16x32_bf16 v[118:121], v[172:175], v[188:191], v[118:121]
	v_mfma_f32_16x16x32_bf16 v[114:117], v[180:183], v[188:191], v[114:117]
	v_mfma_f32_16x16x32_bf16 v[102:105], v[172:175], v[196:199], v[102:105]
	v_mfma_f32_16x16x32_bf16 v[98:101], v[180:183], v[196:199], v[98:101]
	v_mfma_f32_16x16x32_bf16 v[86:89], v[172:175], v[204:207], v[86:89]
	v_mfma_f32_16x16x32_bf16 v[82:85], v[180:183], v[204:207], v[82:85]
	v_mfma_f32_16x16x32_bf16 v[70:73], v[172:175], v[212:215], v[70:73]
	v_mfma_f32_16x16x32_bf16 v[66:69], v[180:183], v[212:215], v[66:69]
	v_mfma_f32_16x16x32_bf16 v[118:121], v[176:179], v[192:195], v[118:121]
	v_mfma_f32_16x16x32_bf16 v[114:117], v[184:187], v[192:195], v[114:117]
	v_mfma_f32_16x16x32_bf16 v[102:105], v[176:179], v[200:203], v[102:105]
	v_mfma_f32_16x16x32_bf16 v[98:101], v[184:187], v[200:203], v[98:101]
	v_mfma_f32_16x16x32_bf16 v[86:89], v[176:179], v[208:211], v[86:89]
	v_mfma_f32_16x16x32_bf16 v[82:85], v[184:187], v[208:211], v[82:85]
	v_mfma_f32_16x16x32_bf16 v[70:73], v[176:179], v[216:219], v[70:73]
	v_mfma_f32_16x16x32_bf16 v[66:69], v[184:187], v[216:219], v[66:69]
	s_setprio 0
	s_barrier
	s_add_i32 s74, s67, s54
	v_lshl_add_u64 v[148:149], s[50:51], 0, v[134:135]
	s_mov_b32 m0, s74
	ds_read_b128 v[188:191], v154 offset:16384
	ds_read_b128 v[192:195], v154 offset:17408
	ds_read_b128 v[196:199], v154 offset:18432
	ds_read_b128 v[200:203], v154 offset:19456
	ds_read_b128 v[204:207], v154 offset:20480
	ds_read_b128 v[208:211], v154 offset:21504
	ds_read_b128 v[212:215], v154 offset:22528
	ds_read_b128 v[216:219], v154 offset:23552
	global_load_lds_dwordx4 v[148:149], off
	s_add_i32 m0, s74, 0x2000
	s_add_u32 s74, s50, 0x40000
	v_lshl_add_u64 v[220:221], s[50:51], 0, v[130:131]
	s_addc_u32 s75, s51, 0
	s_add_i32 s76, s68, s54
	global_load_lds_dwordx4 v[220:221], off
	v_lshl_add_u64 v[222:223], s[74:75], 0, v[134:135]
	s_mov_b32 m0, s76
	v_lshl_add_u64 v[224:225], s[52:53], 0, v[132:133]
	global_load_lds_dwordx4 v[222:223], off
	v_lshl_add_u64 v[222:223], s[74:75], 0, v[130:131]
	s_add_i32 m0, s76, 0x2000
	s_nop 0
	global_load_lds_dwordx4 v[222:223], off
	v_lshl_add_u64 v[222:223], s[52:53], 0, v[136:137]
	s_mov_b32 m0, s57
	s_nop 0
	global_load_lds_dwordx4 v[222:223], off
	s_mov_b32 m0, s58
	s_nop 0
	global_load_lds_dwordx4 v[224:225], off
	s_waitcnt vmcnt(8)
	s_waitcnt lgkmcnt(0)
	s_setprio 1
	s_barrier
	v_mfma_f32_16x16x32_bf16 v[62:65], v[156:159], v[188:191], v[62:65]
	v_mfma_f32_16x16x32_bf16 v[58:61], v[164:167], v[188:191], v[58:61]
	v_mfma_f32_16x16x32_bf16 v[46:49], v[156:159], v[196:199], v[46:49]
	v_mfma_f32_16x16x32_bf16 v[42:45], v[164:167], v[196:199], v[42:45]
	v_mfma_f32_16x16x32_bf16 v[30:33], v[156:159], v[204:207], v[30:33]
	v_mfma_f32_16x16x32_bf16 v[26:29], v[164:167], v[204:207], v[26:29]
	v_mfma_f32_16x16x32_bf16 v[14:17], v[156:159], v[212:215], v[14:17]
	v_mfma_f32_16x16x32_bf16 v[10:13], v[164:167], v[212:215], v[10:13]
	v_mfma_f32_16x16x32_bf16 v[62:65], v[160:163], v[192:195], v[62:65]
	v_mfma_f32_16x16x32_bf16 v[58:61], v[168:171], v[192:195], v[58:61]
	v_mfma_f32_16x16x32_bf16 v[46:49], v[160:163], v[200:203], v[46:49]
	v_mfma_f32_16x16x32_bf16 v[42:45], v[168:171], v[200:203], v[42:45]
	v_mfma_f32_16x16x32_bf16 v[30:33], v[160:163], v[208:211], v[30:33]
	v_mfma_f32_16x16x32_bf16 v[26:29], v[168:171], v[208:211], v[26:29]
	v_mfma_f32_16x16x32_bf16 v[14:17], v[160:163], v[216:219], v[14:17]
	v_mfma_f32_16x16x32_bf16 v[10:13], v[168:171], v[216:219], v[10:13]
	s_setprio 0
	s_setprio 1
	v_mfma_f32_16x16x32_bf16 v[54:57], v[172:175], v[188:191], v[54:57]
	v_mfma_f32_16x16x32_bf16 v[50:53], v[180:183], v[188:191], v[50:53]
	v_mfma_f32_16x16x32_bf16 v[38:41], v[172:175], v[196:199], v[38:41]
	v_mfma_f32_16x16x32_bf16 v[34:37], v[180:183], v[196:199], v[34:37]
	v_mfma_f32_16x16x32_bf16 v[22:25], v[172:175], v[204:207], v[22:25]
	v_mfma_f32_16x16x32_bf16 v[18:21], v[180:183], v[204:207], v[18:21]
	v_mfma_f32_16x16x32_bf16 v[6:9], v[172:175], v[212:215], v[6:9]
	v_mfma_f32_16x16x32_bf16 v[2:5], v[180:183], v[212:215], v[2:5]
	v_mfma_f32_16x16x32_bf16 v[54:57], v[176:179], v[192:195], v[54:57]
	v_mfma_f32_16x16x32_bf16 v[50:53], v[184:187], v[192:195], v[50:53]
	v_mfma_f32_16x16x32_bf16 v[38:41], v[176:179], v[200:203], v[38:41]
	v_mfma_f32_16x16x32_bf16 v[34:37], v[184:187], v[200:203], v[34:37]
	v_mfma_f32_16x16x32_bf16 v[22:25], v[176:179], v[208:211], v[22:25]
	v_mfma_f32_16x16x32_bf16 v[18:21], v[184:187], v[208:211], v[18:21]
	v_mfma_f32_16x16x32_bf16 v[6:9], v[176:179], v[216:219], v[6:9]
	v_mfma_f32_16x16x32_bf16 v[2:5], v[184:187], v[216:219], v[2:5]
	s_setprio 0
	s_barrier
	s_add_i32 s74, 0, 0x18000
	s_add_i32 s75, 0, 0x1c000
	v_add_u32_e32 v168, s74, v151
	v_add_u32_e32 v184, s75, v151
	ds_read_b128 v[156:159], v168
	ds_read_b128 v[160:163], v168 offset:1024
	ds_read_b128 v[164:167], v168 offset:2048
	ds_read_b128 v[168:171], v168 offset:3072
	ds_read_b128 v[172:175], v184
	ds_read_b128 v[176:179], v184 offset:1024
	ds_read_b128 v[180:183], v184 offset:2048
	ds_read_b128 v[184:187], v184 offset:3072
	s_add_u32 s52, s52, 0x40000
	s_addc_u32 s53, s53, 0
	s_mov_b32 m0, s59
	v_lshl_add_u64 v[226:227], s[52:53], 0, v[136:137]
	ds_read_b128 v[188:191], v154 offset:32768
	ds_read_b128 v[192:195], v154 offset:33792
	ds_read_b128 v[196:199], v154 offset:34816
	ds_read_b128 v[200:203], v154 offset:35840
	ds_read_b128 v[204:207], v154 offset:36864
	ds_read_b128 v[208:211], v154 offset:37888
	ds_read_b128 v[212:215], v154 offset:38912
	ds_read_b128 v[216:219], v154 offset:39936
	global_load_lds_dwordx4 v[226:227], off
	v_lshl_add_u64 v[226:227], s[52:53], 0, v[132:133]
	s_mov_b32 m0, s60
	s_nop 0
	global_load_lds_dwordx4 v[226:227], off
	s_waitcnt vmcnt(8)
	s_waitcnt lgkmcnt(0)
	s_setprio 1
	s_barrier
	v_mfma_f32_16x16x32_bf16 v[126:129], v[156:159], v[188:191], v[126:129]
	v_mfma_f32_16x16x32_bf16 v[122:125], v[164:167], v[188:191], v[122:125]
	v_mfma_f32_16x16x32_bf16 v[110:113], v[156:159], v[196:199], v[110:113]
	v_mfma_f32_16x16x32_bf16 v[106:109], v[164:167], v[196:199], v[106:109]
	v_mfma_f32_16x16x32_bf16 v[94:97], v[156:159], v[204:207], v[94:97]
	v_mfma_f32_16x16x32_bf16 v[90:93], v[164:167], v[204:207], v[90:93]
	v_mfma_f32_16x16x32_bf16 v[78:81], v[156:159], v[212:215], v[78:81]
	v_mfma_f32_16x16x32_bf16 v[74:77], v[164:167], v[212:215], v[74:77]
	v_mfma_f32_16x16x32_bf16 v[126:129], v[160:163], v[192:195], v[126:129]
	v_mfma_f32_16x16x32_bf16 v[122:125], v[168:171], v[192:195], v[122:125]
	v_mfma_f32_16x16x32_bf16 v[110:113], v[160:163], v[200:203], v[110:113]
	v_mfma_f32_16x16x32_bf16 v[106:109], v[168:171], v[200:203], v[106:109]
	v_mfma_f32_16x16x32_bf16 v[94:97], v[160:163], v[208:211], v[94:97]
	v_mfma_f32_16x16x32_bf16 v[90:93], v[168:171], v[208:211], v[90:93]
	v_mfma_f32_16x16x32_bf16 v[78:81], v[160:163], v[216:219], v[78:81]
	v_mfma_f32_16x16x32_bf16 v[74:77], v[168:171], v[216:219], v[74:77]
	s_setprio 0
	s_setprio 1
	v_mfma_f32_16x16x32_bf16 v[118:121], v[172:175], v[188:191], v[118:121]
	v_mfma_f32_16x16x32_bf16 v[114:117], v[180:183], v[188:191], v[114:117]
	v_mfma_f32_16x16x32_bf16 v[102:105], v[172:175], v[196:199], v[102:105]
	v_mfma_f32_16x16x32_bf16 v[98:101], v[180:183], v[196:199], v[98:101]
	v_mfma_f32_16x16x32_bf16 v[86:89], v[172:175], v[204:207], v[86:89]
	v_mfma_f32_16x16x32_bf16 v[82:85], v[180:183], v[204:207], v[82:85]
	v_mfma_f32_16x16x32_bf16 v[70:73], v[172:175], v[212:215], v[70:73]
	v_mfma_f32_16x16x32_bf16 v[66:69], v[180:183], v[212:215], v[66:69]
	v_mfma_f32_16x16x32_bf16 v[118:121], v[176:179], v[192:195], v[118:121]
	v_mfma_f32_16x16x32_bf16 v[114:117], v[184:187], v[192:195], v[114:117]
	v_mfma_f32_16x16x32_bf16 v[102:105], v[176:179], v[200:203], v[102:105]
	v_mfma_f32_16x16x32_bf16 v[98:101], v[184:187], v[200:203], v[98:101]
	v_mfma_f32_16x16x32_bf16 v[86:89], v[176:179], v[208:211], v[86:89]
	v_mfma_f32_16x16x32_bf16 v[82:85], v[184:187], v[208:211], v[82:85]
	v_mfma_f32_16x16x32_bf16 v[70:73], v[176:179], v[216:219], v[70:73]
	v_mfma_f32_16x16x32_bf16 v[66:69], v[184:187], v[216:219], v[66:69]
	s_setprio 0
	s_barrier
	s_add_i32 s52, s74, s54
	v_lshl_add_u64 v[148:149], v[148:149], 0, s[16:17]
	s_mov_b32 m0, s52
	ds_read_b128 v[188:191], v154 offset:49152
	ds_read_b128 v[192:195], v154 offset:50176
	ds_read_b128 v[196:199], v154 offset:51200
	ds_read_b128 v[200:203], v154 offset:52224
	ds_read_b128 v[204:207], v154 offset:53248
	ds_read_b128 v[208:211], v154 offset:54272
	ds_read_b128 v[212:215], v154 offset:55296
	ds_read_b128 v[216:219], v154 offset:56320
	global_load_lds_dwordx4 v[148:149], off
	s_add_i32 m0, s52, 0x2000
	s_add_u32 s50, s50, 0x40080
	v_lshl_add_u64 v[148:149], v[220:221], 0, s[16:17]
	s_addc_u32 s51, s51, 0
	s_add_i32 s52, s75, s54
	global_load_lds_dwordx4 v[148:149], off
	v_lshl_add_u64 v[148:149], s[50:51], 0, v[134:135]
	s_mov_b32 m0, s52
	s_nop 0
	global_load_lds_dwordx4 v[148:149], off
	v_lshl_add_u64 v[148:149], s[50:51], 0, v[130:131]
	s_add_i32 m0, s52, 0x2000
	s_nop 0
	global_load_lds_dwordx4 v[148:149], off
	v_lshl_add_u64 v[148:149], v[222:223], 0, s[16:17]
	s_mov_b32 m0, s63
	s_nop 0
	global_load_lds_dwordx4 v[148:149], off
	v_lshl_add_u64 v[148:149], v[224:225], 0, s[16:17]
	s_mov_b32 m0, s64
	s_nop 0
	global_load_lds_dwordx4 v[148:149], off
	s_waitcnt vmcnt(8)
	s_waitcnt lgkmcnt(0)
	s_setprio 1
	s_barrier
	v_mfma_f32_16x16x32_bf16 v[62:65], v[156:159], v[188:191], v[62:65]
	v_mfma_f32_16x16x32_bf16 v[58:61], v[164:167], v[188:191], v[58:61]
	v_mfma_f32_16x16x32_bf16 v[46:49], v[156:159], v[196:199], v[46:49]
	v_mfma_f32_16x16x32_bf16 v[42:45], v[164:167], v[196:199], v[42:45]
	v_mfma_f32_16x16x32_bf16 v[30:33], v[156:159], v[204:207], v[30:33]
	v_mfma_f32_16x16x32_bf16 v[26:29], v[164:167], v[204:207], v[26:29]
	v_mfma_f32_16x16x32_bf16 v[14:17], v[156:159], v[212:215], v[14:17]
	v_mfma_f32_16x16x32_bf16 v[10:13], v[164:167], v[212:215], v[10:13]
	v_mfma_f32_16x16x32_bf16 v[62:65], v[160:163], v[192:195], v[62:65]
	v_mfma_f32_16x16x32_bf16 v[58:61], v[168:171], v[192:195], v[58:61]
	v_mfma_f32_16x16x32_bf16 v[46:49], v[160:163], v[200:203], v[46:49]
	v_mfma_f32_16x16x32_bf16 v[42:45], v[168:171], v[200:203], v[42:45]
	v_mfma_f32_16x16x32_bf16 v[30:33], v[160:163], v[208:211], v[30:33]
	v_mfma_f32_16x16x32_bf16 v[26:29], v[168:171], v[208:211], v[26:29]
	v_mfma_f32_16x16x32_bf16 v[14:17], v[160:163], v[216:219], v[14:17]
	v_mfma_f32_16x16x32_bf16 v[10:13], v[168:171], v[216:219], v[10:13]
	s_setprio 0
	s_setprio 1
	v_mfma_f32_16x16x32_bf16 v[54:57], v[172:175], v[188:191], v[54:57]
	v_mfma_f32_16x16x32_bf16 v[50:53], v[180:183], v[188:191], v[50:53]
	v_mfma_f32_16x16x32_bf16 v[38:41], v[172:175], v[196:199], v[38:41]
	v_mfma_f32_16x16x32_bf16 v[34:37], v[180:183], v[196:199], v[34:37]
	v_mfma_f32_16x16x32_bf16 v[22:25], v[172:175], v[204:207], v[22:25]
	v_mfma_f32_16x16x32_bf16 v[18:21], v[180:183], v[204:207], v[18:21]
	v_mfma_f32_16x16x32_bf16 v[6:9], v[172:175], v[212:215], v[6:9]
	v_mfma_f32_16x16x32_bf16 v[2:5], v[180:183], v[212:215], v[2:5]
	v_mfma_f32_16x16x32_bf16 v[54:57], v[176:179], v[192:195], v[54:57]
	v_mfma_f32_16x16x32_bf16 v[50:53], v[184:187], v[192:195], v[50:53]
	v_mfma_f32_16x16x32_bf16 v[38:41], v[176:179], v[200:203], v[38:41]
	v_mfma_f32_16x16x32_bf16 v[34:37], v[184:187], v[200:203], v[34:37]
	v_mfma_f32_16x16x32_bf16 v[22:25], v[176:179], v[208:211], v[22:25]
	v_mfma_f32_16x16x32_bf16 v[18:21], v[184:187], v[208:211], v[18:21]
	v_mfma_f32_16x16x32_bf16 v[6:9], v[176:179], v[216:219], v[6:9]
	v_mfma_f32_16x16x32_bf16 v[2:5], v[184:187], v[216:219], v[2:5]
	s_setprio 0
	s_add_i32 s73, s73, 2
	s_add_u32 s48, s48, 0x100
	s_addc_u32 s49, s49, 0
	s_add_u32 s71, s71, 0x100
	s_addc_u32 s72, s72, 0
	s_cmp_gt_u32 s73, 13
	s_barrier
	s_cbranch_scc0 .LBB0_352

.LBB0_738:
	s_ashr_i32 s43, s42, 31
	s_lshl_b64 s[44:45], s[42:43], 19
	s_add_u32 s44, s3, s44
	s_addc_u32 s45, s23, s45
	s_and_b64 s[46:47], s[6:7], exec
	s_cselect_b32 s43, s45, s53
	s_cselect_b32 s49, s44, s52
	s_ashr_i32 s27, s26, 31
	s_lshl_b64 s[46:47], s[26:27], 19
	s_add_u32 s46, s29, s46
	s_addc_u32 s47, s31, s47
	s_and_b64 s[56:57], s[6:7], exec
	s_cselect_b32 s27, s47, s55
	s_cselect_b32 s51, s46, s54
	s_add_u32 s52, s52, 0x40080
	s_addc_u32 s53, s53, 0
	s_add_u32 s71, s54, 0x100
	s_addc_u32 s72, s55, 0
	s_mov_b32 s73, -2
	s_waitcnt vmcnt(0)
	ds_read_b128 v[122:125], v245
	ds_read_b128 v[126:129], v245 offset:1024
	ds_read_b128 v[130:133], v245 offset:2048
	ds_read_b128 v[134:137], v245 offset:3072
	ds_read_b128 v[138:141], v246
	ds_read_b128 v[142:145], v246 offset:1024
	ds_read_b128 v[146:149], v246 offset:2048
	ds_read_b128 v[158:161], v246 offset:3072
	s_add_u32 s54, s52, 0xfffc0080
	s_addc_u32 s55, s53, -1
	s_cmp_eq_u32 s73, 12
	s_cselect_b32 s57, s43, s55
	s_cselect_b32 s56, s49, s54
	s_cselect_b32 s55, s27, s72
	s_cselect_b32 s54, s51, s71
	v_lshl_add_u64 v[210:211], s[52:53], 0, v[206:207]
	s_add_i32 m0, s59, 0xc000
	ds_read_b128 v[162:165], v247
	ds_read_b128 v[166:169], v247 offset:1024
	ds_read_b128 v[170:173], v247 offset:2048
	ds_read_b128 v[174:177], v247 offset:3072
	ds_read_b128 v[178:181], v247 offset:4096
	ds_read_b128 v[182:185], v247 offset:5120
	ds_read_b128 v[186:189], v247 offset:6144
	ds_read_b128 v[190:193], v247 offset:7168
	global_load_lds_dwordx4 v[210:211], off
	v_lshl_add_u64 v[210:211], s[52:53], 0, v[208:209]
	s_add_i32 m0, s59, 0xe000
	s_nop 0
	global_load_lds_dwordx4 v[210:211], off
	s_waitcnt vmcnt(8)
	s_waitcnt lgkmcnt(0)
	s_setprio 1
	s_barrier
	v_mfma_f32_16x16x32_bf16 v[154:157], v[122:125], v[162:165], 0
	v_mfma_f32_16x16x32_bf16 v[150:153], v[130:133], v[162:165], 0
	v_mfma_f32_16x16x32_bf16 v[110:113], v[122:125], v[170:173], 0
	v_mfma_f32_16x16x32_bf16 v[106:109], v[130:133], v[170:173], 0
	v_mfma_f32_16x16x32_bf16 v[94:97], v[122:125], v[178:181], 0
	v_mfma_f32_16x16x32_bf16 v[90:93], v[130:133], v[178:181], 0
	v_mfma_f32_16x16x32_bf16 v[78:81], v[122:125], v[186:189], 0
	v_mfma_f32_16x16x32_bf16 v[74:77], v[130:133], v[186:189], 0
	v_mfma_f32_16x16x32_bf16 v[154:157], v[126:129], v[166:169], v[154:157]
	v_mfma_f32_16x16x32_bf16 v[150:153], v[134:137], v[166:169], v[150:153]
	v_mfma_f32_16x16x32_bf16 v[110:113], v[126:129], v[174:177], v[110:113]
	v_mfma_f32_16x16x32_bf16 v[106:109], v[134:137], v[174:177], v[106:109]
	v_mfma_f32_16x16x32_bf16 v[94:97], v[126:129], v[182:185], v[94:97]
	v_mfma_f32_16x16x32_bf16 v[90:93], v[134:137], v[182:185], v[90:93]
	v_mfma_f32_16x16x32_bf16 v[78:81], v[126:129], v[190:193], v[78:81]
	v_mfma_f32_16x16x32_bf16 v[74:77], v[134:137], v[190:193], v[74:77]
	s_setprio 0
	s_setprio 1
	v_mfma_f32_16x16x32_bf16 v[118:121], v[138:141], v[162:165], 0
	v_mfma_f32_16x16x32_bf16 v[114:117], v[146:149], v[162:165], 0
	v_mfma_f32_16x16x32_bf16 v[102:105], v[138:141], v[170:173], 0
	v_mfma_f32_16x16x32_bf16 v[98:101], v[146:149], v[170:173], 0
	v_mfma_f32_16x16x32_bf16 v[86:89], v[138:141], v[178:181], 0
	v_mfma_f32_16x16x32_bf16 v[82:85], v[146:149], v[178:181], 0
	v_mfma_f32_16x16x32_bf16 v[70:73], v[138:141], v[186:189], 0
	v_mfma_f32_16x16x32_bf16 v[66:69], v[146:149], v[186:189], 0
	v_mfma_f32_16x16x32_bf16 v[118:121], v[142:145], v[166:169], v[118:121]
	v_mfma_f32_16x16x32_bf16 v[114:117], v[158:161], v[166:169], v[114:117]
	v_mfma_f32_16x16x32_bf16 v[102:105], v[142:145], v[174:177], v[102:105]
	v_mfma_f32_16x16x32_bf16 v[98:101], v[158:161], v[174:177], v[98:101]
	v_mfma_f32_16x16x32_bf16 v[86:89], v[142:145], v[182:185], v[86:89]
	v_mfma_f32_16x16x32_bf16 v[82:85], v[158:161], v[182:185], v[82:85]
	v_mfma_f32_16x16x32_bf16 v[70:73], v[142:145], v[190:193], v[70:73]
	v_mfma_f32_16x16x32_bf16 v[66:69], v[158:161], v[190:193], v[66:69]
	s_setprio 0
	s_barrier
	s_add_i32 s74, s69, s58
	v_lshl_add_u64 v[210:211], s[54:55], 0, v[196:197]
	s_mov_b32 m0, s74
	ds_read_b128 v[162:165], v247 offset:16384
	ds_read_b128 v[166:169], v247 offset:17408
	ds_read_b128 v[170:173], v247 offset:18432
	ds_read_b128 v[174:177], v247 offset:19456
	ds_read_b128 v[178:181], v247 offset:20480
	ds_read_b128 v[182:185], v247 offset:21504
	ds_read_b128 v[186:189], v247 offset:22528
	ds_read_b128 v[190:193], v247 offset:23552
	global_load_lds_dwordx4 v[210:211], off
	s_add_i32 m0, s74, 0x2000
	s_add_u32 s74, s54, 0x40000
	v_lshl_add_u64 v[212:213], s[54:55], 0, v[200:201]
	s_addc_u32 s75, s55, 0
	s_add_i32 s76, s70, s58
	global_load_lds_dwordx4 v[212:213], off
	v_lshl_add_u64 v[214:215], s[74:75], 0, v[196:197]
	s_mov_b32 m0, s76
	v_lshl_add_u64 v[216:217], s[56:57], 0, v[198:199]
	global_load_lds_dwordx4 v[214:215], off
	v_lshl_add_u64 v[214:215], s[74:75], 0, v[200:201]
	s_add_i32 m0, s76, 0x2000
	s_nop 0
	global_load_lds_dwordx4 v[214:215], off
	v_lshl_add_u64 v[214:215], s[56:57], 0, v[194:195]
	s_mov_b32 m0, s59
	s_nop 0
	global_load_lds_dwordx4 v[214:215], off
	s_mov_b32 m0, s60
	s_nop 0
	global_load_lds_dwordx4 v[216:217], off
	s_waitcnt vmcnt(8)
	s_waitcnt lgkmcnt(0)
	s_setprio 1
	s_barrier
	v_mfma_f32_16x16x32_bf16 v[62:65], v[122:125], v[162:165], 0
	v_mfma_f32_16x16x32_bf16 v[58:61], v[130:133], v[162:165], 0
	v_mfma_f32_16x16x32_bf16 v[46:49], v[122:125], v[170:173], 0
	v_mfma_f32_16x16x32_bf16 v[42:45], v[130:133], v[170:173], 0
	v_mfma_f32_16x16x32_bf16 v[30:33], v[122:125], v[178:181], 0
	v_mfma_f32_16x16x32_bf16 v[26:29], v[130:133], v[178:181], 0
	v_mfma_f32_16x16x32_bf16 v[14:17], v[122:125], v[186:189], 0
	v_mfma_f32_16x16x32_bf16 v[10:13], v[130:133], v[186:189], 0
	v_mfma_f32_16x16x32_bf16 v[62:65], v[126:129], v[166:169], v[62:65]
	v_mfma_f32_16x16x32_bf16 v[58:61], v[134:137], v[166:169], v[58:61]
	v_mfma_f32_16x16x32_bf16 v[46:49], v[126:129], v[174:177], v[46:49]
	v_mfma_f32_16x16x32_bf16 v[42:45], v[134:137], v[174:177], v[42:45]
	v_mfma_f32_16x16x32_bf16 v[30:33], v[126:129], v[182:185], v[30:33]
	v_mfma_f32_16x16x32_bf16 v[26:29], v[134:137], v[182:185], v[26:29]
	v_mfma_f32_16x16x32_bf16 v[14:17], v[126:129], v[190:193], v[14:17]
	v_mfma_f32_16x16x32_bf16 v[10:13], v[134:137], v[190:193], v[10:13]
	s_setprio 0
	s_setprio 1
	v_mfma_f32_16x16x32_bf16 v[54:57], v[138:141], v[162:165], 0
	v_mfma_f32_16x16x32_bf16 v[50:53], v[146:149], v[162:165], 0
	v_mfma_f32_16x16x32_bf16 v[38:41], v[138:141], v[170:173], 0
	v_mfma_f32_16x16x32_bf16 v[34:37], v[146:149], v[170:173], 0
	v_mfma_f32_16x16x32_bf16 v[22:25], v[138:141], v[178:181], 0
	v_mfma_f32_16x16x32_bf16 v[18:21], v[146:149], v[178:181], 0
	v_mfma_f32_16x16x32_bf16 v[6:9], v[138:141], v[186:189], 0
	v_mfma_f32_16x16x32_bf16 v[2:5], v[146:149], v[186:189], 0
	v_mfma_f32_16x16x32_bf16 v[54:57], v[142:145], v[166:169], v[54:57]
	v_mfma_f32_16x16x32_bf16 v[50:53], v[158:161], v[166:169], v[50:53]
	v_mfma_f32_16x16x32_bf16 v[38:41], v[142:145], v[174:177], v[38:41]
	v_mfma_f32_16x16x32_bf16 v[34:37], v[158:161], v[174:177], v[34:37]
	v_mfma_f32_16x16x32_bf16 v[22:25], v[142:145], v[182:185], v[22:25]
	v_mfma_f32_16x16x32_bf16 v[18:21], v[158:161], v[182:185], v[18:21]
	v_mfma_f32_16x16x32_bf16 v[6:9], v[142:145], v[190:193], v[6:9]
	v_mfma_f32_16x16x32_bf16 v[2:5], v[158:161], v[190:193], v[2:5]
	s_setprio 0
	s_barrier
	s_add_i32 s74, 0, 0x18000
	s_add_i32 s75, 0, 0x1c000
	v_add_u32_e32 v134, s74, v244
	v_add_u32_e32 v158, s75, v244
	ds_read_b128 v[122:125], v134
	ds_read_b128 v[126:129], v134 offset:1024
	ds_read_b128 v[130:133], v134 offset:2048
	ds_read_b128 v[134:137], v134 offset:3072
	ds_read_b128 v[138:141], v158
	ds_read_b128 v[142:145], v158 offset:1024
	ds_read_b128 v[146:149], v158 offset:2048
	ds_read_b128 v[158:161], v158 offset:3072
	s_add_u32 s56, s56, 0x40000
	s_addc_u32 s57, s57, 0
	s_mov_b32 m0, s61
	v_lshl_add_u64 v[218:219], s[56:57], 0, v[194:195]
	ds_read_b128 v[162:165], v247 offset:32768
	ds_read_b128 v[166:169], v247 offset:33792
	ds_read_b128 v[170:173], v247 offset:34816
	ds_read_b128 v[174:177], v247 offset:35840
	ds_read_b128 v[178:181], v247 offset:36864
	ds_read_b128 v[182:185], v247 offset:37888
	ds_read_b128 v[186:189], v247 offset:38912
	ds_read_b128 v[190:193], v247 offset:39936
	global_load_lds_dwordx4 v[218:219], off
	v_lshl_add_u64 v[218:219], s[56:57], 0, v[198:199]
	s_mov_b32 m0, s62
	s_nop 0
	global_load_lds_dwordx4 v[218:219], off
	s_waitcnt vmcnt(8)
	s_waitcnt lgkmcnt(0)
	s_setprio 1
	s_barrier
	v_mfma_f32_16x16x32_bf16 v[154:157], v[122:125], v[162:165], v[154:157]
	v_mfma_f32_16x16x32_bf16 v[150:153], v[130:133], v[162:165], v[150:153]
	v_mfma_f32_16x16x32_bf16 v[110:113], v[122:125], v[170:173], v[110:113]
	v_mfma_f32_16x16x32_bf16 v[106:109], v[130:133], v[170:173], v[106:109]
	v_mfma_f32_16x16x32_bf16 v[94:97], v[122:125], v[178:181], v[94:97]
	v_mfma_f32_16x16x32_bf16 v[90:93], v[130:133], v[178:181], v[90:93]
	v_mfma_f32_16x16x32_bf16 v[78:81], v[122:125], v[186:189], v[78:81]
	v_mfma_f32_16x16x32_bf16 v[74:77], v[130:133], v[186:189], v[74:77]
	v_mfma_f32_16x16x32_bf16 v[154:157], v[126:129], v[166:169], v[154:157]
	v_mfma_f32_16x16x32_bf16 v[150:153], v[134:137], v[166:169], v[150:153]
	v_mfma_f32_16x16x32_bf16 v[110:113], v[126:129], v[174:177], v[110:113]
	v_mfma_f32_16x16x32_bf16 v[106:109], v[134:137], v[174:177], v[106:109]
	v_mfma_f32_16x16x32_bf16 v[94:97], v[126:129], v[182:185], v[94:97]
	v_mfma_f32_16x16x32_bf16 v[90:93], v[134:137], v[182:185], v[90:93]
	v_mfma_f32_16x16x32_bf16 v[78:81], v[126:129], v[190:193], v[78:81]
	v_mfma_f32_16x16x32_bf16 v[74:77], v[134:137], v[190:193], v[74:77]
	s_setprio 0
	s_setprio 1
	v_mfma_f32_16x16x32_bf16 v[118:121], v[138:141], v[162:165], v[118:121]
	v_mfma_f32_16x16x32_bf16 v[114:117], v[146:149], v[162:165], v[114:117]
	v_mfma_f32_16x16x32_bf16 v[102:105], v[138:141], v[170:173], v[102:105]
	v_mfma_f32_16x16x32_bf16 v[98:101], v[146:149], v[170:173], v[98:101]
	v_mfma_f32_16x16x32_bf16 v[86:89], v[138:141], v[178:181], v[86:89]
	v_mfma_f32_16x16x32_bf16 v[82:85], v[146:149], v[178:181], v[82:85]
	v_mfma_f32_16x16x32_bf16 v[70:73], v[138:141], v[186:189], v[70:73]
	v_mfma_f32_16x16x32_bf16 v[66:69], v[146:149], v[186:189], v[66:69]
	v_mfma_f32_16x16x32_bf16 v[118:121], v[142:145], v[166:169], v[118:121]
	v_mfma_f32_16x16x32_bf16 v[114:117], v[158:161], v[166:169], v[114:117]
	v_mfma_f32_16x16x32_bf16 v[102:105], v[142:145], v[174:177], v[102:105]
	v_mfma_f32_16x16x32_bf16 v[98:101], v[158:161], v[174:177], v[98:101]
	v_mfma_f32_16x16x32_bf16 v[86:89], v[142:145], v[182:185], v[86:89]
	v_mfma_f32_16x16x32_bf16 v[82:85], v[158:161], v[182:185], v[82:85]
	v_mfma_f32_16x16x32_bf16 v[70:73], v[142:145], v[190:193], v[70:73]
	v_mfma_f32_16x16x32_bf16 v[66:69], v[158:161], v[190:193], v[66:69]
	s_setprio 0
	s_barrier
	s_add_i32 s56, s74, s58
	v_lshl_add_u64 v[210:211], v[210:211], 0, s[16:17]
	s_mov_b32 m0, s56
	ds_read_b128 v[162:165], v247 offset:49152
	ds_read_b128 v[166:169], v247 offset:50176
	ds_read_b128 v[170:173], v247 offset:51200
	ds_read_b128 v[174:177], v247 offset:52224
	ds_read_b128 v[178:181], v247 offset:53248
	ds_read_b128 v[182:185], v247 offset:54272
	ds_read_b128 v[186:189], v247 offset:55296
	ds_read_b128 v[190:193], v247 offset:56320
	global_load_lds_dwordx4 v[210:211], off
	s_add_i32 m0, s56, 0x2000
	s_add_u32 s54, s54, 0x40080
	v_lshl_add_u64 v[210:211], v[212:213], 0, s[16:17]
	s_addc_u32 s55, s55, 0
	s_add_i32 s56, s75, s58
	global_load_lds_dwordx4 v[210:211], off
	v_lshl_add_u64 v[210:211], s[54:55], 0, v[196:197]
	s_mov_b32 m0, s56
	s_nop 0
	global_load_lds_dwordx4 v[210:211], off
	v_lshl_add_u64 v[210:211], s[54:55], 0, v[200:201]
	s_add_i32 m0, s56, 0x2000
	s_nop 0
	global_load_lds_dwordx4 v[210:211], off
	v_lshl_add_u64 v[210:211], v[214:215], 0, s[16:17]
	s_mov_b32 m0, s64
	s_nop 0
	global_load_lds_dwordx4 v[210:211], off
	v_lshl_add_u64 v[210:211], v[216:217], 0, s[16:17]
	s_mov_b32 m0, s65
	s_nop 0
	global_load_lds_dwordx4 v[210:211], off
	s_waitcnt vmcnt(8)
	s_waitcnt lgkmcnt(0)
	s_setprio 1
	s_barrier
	v_mfma_f32_16x16x32_bf16 v[62:65], v[122:125], v[162:165], v[62:65]
	v_mfma_f32_16x16x32_bf16 v[58:61], v[130:133], v[162:165], v[58:61]
	v_mfma_f32_16x16x32_bf16 v[46:49], v[122:125], v[170:173], v[46:49]
	v_mfma_f32_16x16x32_bf16 v[42:45], v[130:133], v[170:173], v[42:45]
	v_mfma_f32_16x16x32_bf16 v[30:33], v[122:125], v[178:181], v[30:33]
	v_mfma_f32_16x16x32_bf16 v[26:29], v[130:133], v[178:181], v[26:29]
	v_mfma_f32_16x16x32_bf16 v[14:17], v[122:125], v[186:189], v[14:17]
	v_mfma_f32_16x16x32_bf16 v[10:13], v[130:133], v[186:189], v[10:13]
	v_mfma_f32_16x16x32_bf16 v[62:65], v[126:129], v[166:169], v[62:65]
	v_mfma_f32_16x16x32_bf16 v[58:61], v[134:137], v[166:169], v[58:61]
	v_mfma_f32_16x16x32_bf16 v[46:49], v[126:129], v[174:177], v[46:49]
	v_mfma_f32_16x16x32_bf16 v[42:45], v[134:137], v[174:177], v[42:45]
	v_mfma_f32_16x16x32_bf16 v[30:33], v[126:129], v[182:185], v[30:33]
	v_mfma_f32_16x16x32_bf16 v[26:29], v[134:137], v[182:185], v[26:29]
	v_mfma_f32_16x16x32_bf16 v[14:17], v[126:129], v[190:193], v[14:17]
	v_mfma_f32_16x16x32_bf16 v[10:13], v[134:137], v[190:193], v[10:13]
	s_setprio 0
	s_setprio 1
	v_mfma_f32_16x16x32_bf16 v[54:57], v[138:141], v[162:165], v[54:57]
	v_mfma_f32_16x16x32_bf16 v[50:53], v[146:149], v[162:165], v[50:53]
	v_mfma_f32_16x16x32_bf16 v[38:41], v[138:141], v[170:173], v[38:41]
	v_mfma_f32_16x16x32_bf16 v[34:37], v[146:149], v[170:173], v[34:37]
	v_mfma_f32_16x16x32_bf16 v[22:25], v[138:141], v[178:181], v[22:25]
	v_mfma_f32_16x16x32_bf16 v[18:21], v[146:149], v[178:181], v[18:21]
	v_mfma_f32_16x16x32_bf16 v[6:9], v[138:141], v[186:189], v[6:9]
	v_mfma_f32_16x16x32_bf16 v[2:5], v[146:149], v[186:189], v[2:5]
	v_mfma_f32_16x16x32_bf16 v[54:57], v[142:145], v[166:169], v[54:57]
	v_mfma_f32_16x16x32_bf16 v[50:53], v[158:161], v[166:169], v[50:53]
	v_mfma_f32_16x16x32_bf16 v[38:41], v[142:145], v[174:177], v[38:41]
	v_mfma_f32_16x16x32_bf16 v[34:37], v[158:161], v[174:177], v[34:37]
	v_mfma_f32_16x16x32_bf16 v[22:25], v[142:145], v[182:185], v[22:25]
	v_mfma_f32_16x16x32_bf16 v[18:21], v[158:161], v[182:185], v[18:21]
	v_mfma_f32_16x16x32_bf16 v[6:9], v[142:145], v[190:193], v[6:9]
	v_mfma_f32_16x16x32_bf16 v[2:5], v[158:161], v[190:193], v[2:5]
	s_setprio 0
	s_add_i32 s73, s73, 2
	s_add_u32 s52, s52, 0x100
	s_addc_u32 s53, s53, 0
	s_add_u32 s71, s71, 0x100
	s_addc_u32 s72, s72, 0
	s_cmp_gt_u32 s73, 13
	s_barrier
	s_cbranch_scc0 .LBB0_739
	s_branch .Lz_post_p5
.LBB0_739:
	ds_read_b128 v[122:125], v245
	ds_read_b128 v[126:129], v245 offset:1024
	ds_read_b128 v[130:133], v245 offset:2048
	ds_read_b128 v[134:137], v245 offset:3072
	ds_read_b128 v[138:141], v246
	ds_read_b128 v[142:145], v246 offset:1024
	ds_read_b128 v[146:149], v246 offset:2048
	ds_read_b128 v[158:161], v246 offset:3072
	s_add_u32 s54, s52, 0xfffc0080
	s_addc_u32 s55, s53, -1
	s_cmp_eq_u32 s73, 12
	s_cselect_b32 s57, s43, s55
	s_cselect_b32 s56, s49, s54
	s_cselect_b32 s55, s27, s72
	s_cselect_b32 s54, s51, s71
	v_lshl_add_u64 v[210:211], s[52:53], 0, v[206:207]
	s_add_i32 m0, s59, 0xc000
	ds_read_b128 v[162:165], v247
	ds_read_b128 v[166:169], v247 offset:1024
	ds_read_b128 v[170:173], v247 offset:2048
	ds_read_b128 v[174:177], v247 offset:3072
	ds_read_b128 v[178:181], v247 offset:4096
	ds_read_b128 v[182:185], v247 offset:5120
	ds_read_b128 v[186:189], v247 offset:6144
	ds_read_b128 v[190:193], v247 offset:7168
	global_load_lds_dwordx4 v[210:211], off
	v_lshl_add_u64 v[210:211], s[52:53], 0, v[208:209]
	s_add_i32 m0, s59, 0xe000
	s_nop 0
	global_load_lds_dwordx4 v[210:211], off
	s_waitcnt vmcnt(8)
	s_waitcnt lgkmcnt(0)
	s_setprio 1
	s_barrier
	v_mfma_f32_16x16x32_bf16 v[154:157], v[122:125], v[162:165], v[154:157]
	v_mfma_f32_16x16x32_bf16 v[150:153], v[130:133], v[162:165], v[150:153]
	v_mfma_f32_16x16x32_bf16 v[110:113], v[122:125], v[170:173], v[110:113]
	v_mfma_f32_16x16x32_bf16 v[106:109], v[130:133], v[170:173], v[106:109]
	v_mfma_f32_16x16x32_bf16 v[94:97], v[122:125], v[178:181], v[94:97]
	v_mfma_f32_16x16x32_bf16 v[90:93], v[130:133], v[178:181], v[90:93]
	v_mfma_f32_16x16x32_bf16 v[78:81], v[122:125], v[186:189], v[78:81]
	v_mfma_f32_16x16x32_bf16 v[74:77], v[130:133], v[186:189], v[74:77]
	v_mfma_f32_16x16x32_bf16 v[154:157], v[126:129], v[166:169], v[154:157]
	v_mfma_f32_16x16x32_bf16 v[150:153], v[134:137], v[166:169], v[150:153]
	v_mfma_f32_16x16x32_bf16 v[110:113], v[126:129], v[174:177], v[110:113]
	v_mfma_f32_16x16x32_bf16 v[106:109], v[134:137], v[174:177], v[106:109]
	v_mfma_f32_16x16x32_bf16 v[94:97], v[126:129], v[182:185], v[94:97]
	v_mfma_f32_16x16x32_bf16 v[90:93], v[134:137], v[182:185], v[90:93]
	v_mfma_f32_16x16x32_bf16 v[78:81], v[126:129], v[190:193], v[78:81]
	v_mfma_f32_16x16x32_bf16 v[74:77], v[134:137], v[190:193], v[74:77]
	s_setprio 0
	s_setprio 1
	v_mfma_f32_16x16x32_bf16 v[118:121], v[138:141], v[162:165], v[118:121]
	v_mfma_f32_16x16x32_bf16 v[114:117], v[146:149], v[162:165], v[114:117]
	v_mfma_f32_16x16x32_bf16 v[102:105], v[138:141], v[170:173], v[102:105]
	v_mfma_f32_16x16x32_bf16 v[98:101], v[146:149], v[170:173], v[98:101]
	v_mfma_f32_16x16x32_bf16 v[86:89], v[138:141], v[178:181], v[86:89]
	v_mfma_f32_16x16x32_bf16 v[82:85], v[146:149], v[178:181], v[82:85]
	v_mfma_f32_16x16x32_bf16 v[70:73], v[138:141], v[186:189], v[70:73]
	v_mfma_f32_16x16x32_bf16 v[66:69], v[146:149], v[186:189], v[66:69]
	v_mfma_f32_16x16x32_bf16 v[118:121], v[142:145], v[166:169], v[118:121]
	v_mfma_f32_16x16x32_bf16 v[114:117], v[158:161], v[166:169], v[114:117]
	v_mfma_f32_16x16x32_bf16 v[102:105], v[142:145], v[174:177], v[102:105]
	v_mfma_f32_16x16x32_bf16 v[98:101], v[158:161], v[174:177], v[98:101]
	v_mfma_f32_16x16x32_bf16 v[86:89], v[142:145], v[182:185], v[86:89]
	v_mfma_f32_16x16x32_bf16 v[82:85], v[158:161], v[182:185], v[82:85]
	v_mfma_f32_16x16x32_bf16 v[70:73], v[142:145], v[190:193], v[70:73]
	v_mfma_f32_16x16x32_bf16 v[66:69], v[158:161], v[190:193], v[66:69]
	s_setprio 0
	s_barrier
	s_add_i32 s74, s69, s58
	v_lshl_add_u64 v[210:211], s[54:55], 0, v[196:197]
	s_mov_b32 m0, s74
	ds_read_b128 v[162:165], v247 offset:16384
	ds_read_b128 v[166:169], v247 offset:17408
	ds_read_b128 v[170:173], v247 offset:18432
	ds_read_b128 v[174:177], v247 offset:19456
	ds_read_b128 v[178:181], v247 offset:20480
	ds_read_b128 v[182:185], v247 offset:21504
	ds_read_b128 v[186:189], v247 offset:22528
	ds_read_b128 v[190:193], v247 offset:23552
	global_load_lds_dwordx4 v[210:211], off
	s_add_i32 m0, s74, 0x2000
	s_add_u32 s74, s54, 0x40000
	v_lshl_add_u64 v[212:213], s[54:55], 0, v[200:201]
	s_addc_u32 s75, s55, 0
	s_add_i32 s76, s70, s58
	global_load_lds_dwordx4 v[212:213], off
	v_lshl_add_u64 v[214:215], s[74:75], 0, v[196:197]
	s_mov_b32 m0, s76
	v_lshl_add_u64 v[216:217], s[56:57], 0, v[198:199]
	global_load_lds_dwordx4 v[214:215], off
	v_lshl_add_u64 v[214:215], s[74:75], 0, v[200:201]
	s_add_i32 m0, s76, 0x2000
	s_nop 0
	global_load_lds_dwordx4 v[214:215], off
	v_lshl_add_u64 v[214:215], s[56:57], 0, v[194:195]
	s_mov_b32 m0, s59
	s_nop 0
	global_load_lds_dwordx4 v[214:215], off
	s_mov_b32 m0, s60
	s_nop 0
	global_load_lds_dwordx4 v[216:217], off
	s_waitcnt vmcnt(8)
	s_waitcnt lgkmcnt(0)
	s_setprio 1
	s_barrier
	v_mfma_f32_16x16x32_bf16 v[62:65], v[122:125], v[162:165], v[62:65]
	v_mfma_f32_16x16x32_bf16 v[58:61], v[130:133], v[162:165], v[58:61]
	v_mfma_f32_16x16x32_bf16 v[46:49], v[122:125], v[170:173], v[46:49]
	v_mfma_f32_16x16x32_bf16 v[42:45], v[130:133], v[170:173], v[42:45]
	v_mfma_f32_16x16x32_bf16 v[30:33], v[122:125], v[178:181], v[30:33]
	v_mfma_f32_16x16x32_bf16 v[26:29], v[130:133], v[178:181], v[26:29]
	v_mfma_f32_16x16x32_bf16 v[14:17], v[122:125], v[186:189], v[14:17]
	v_mfma_f32_16x16x32_bf16 v[10:13], v[130:133], v[186:189], v[10:13]
	v_mfma_f32_16x16x32_bf16 v[62:65], v[126:129], v[166:169], v[62:65]
	v_mfma_f32_16x16x32_bf16 v[58:61], v[134:137], v[166:169], v[58:61]
	v_mfma_f32_16x16x32_bf16 v[46:49], v[126:129], v[174:177], v[46:49]
	v_mfma_f32_16x16x32_bf16 v[42:45], v[134:137], v[174:177], v[42:45]
	v_mfma_f32_16x16x32_bf16 v[30:33], v[126:129], v[182:185], v[30:33]
	v_mfma_f32_16x16x32_bf16 v[26:29], v[134:137], v[182:185], v[26:29]
	v_mfma_f32_16x16x32_bf16 v[14:17], v[126:129], v[190:193], v[14:17]
	v_mfma_f32_16x16x32_bf16 v[10:13], v[134:137], v[190:193], v[10:13]
	s_setprio 0
	s_setprio 1
	v_mfma_f32_16x16x32_bf16 v[54:57], v[138:141], v[162:165], v[54:57]
	v_mfma_f32_16x16x32_bf16 v[50:53], v[146:149], v[162:165], v[50:53]
	v_mfma_f32_16x16x32_bf16 v[38:41], v[138:141], v[170:173], v[38:41]
	v_mfma_f32_16x16x32_bf16 v[34:37], v[146:149], v[170:173], v[34:37]
	v_mfma_f32_16x16x32_bf16 v[22:25], v[138:141], v[178:181], v[22:25]
	v_mfma_f32_16x16x32_bf16 v[18:21], v[146:149], v[178:181], v[18:21]
	v_mfma_f32_16x16x32_bf16 v[6:9], v[138:141], v[186:189], v[6:9]
	v_mfma_f32_16x16x32_bf16 v[2:5], v[146:149], v[186:189], v[2:5]
	v_mfma_f32_16x16x32_bf16 v[54:57], v[142:145], v[166:169], v[54:57]
	v_mfma_f32_16x16x32_bf16 v[50:53], v[158:161], v[166:169], v[50:53]
	v_mfma_f32_16x16x32_bf16 v[38:41], v[142:145], v[174:177], v[38:41]
	v_mfma_f32_16x16x32_bf16 v[34:37], v[158:161], v[174:177], v[34:37]
	v_mfma_f32_16x16x32_bf16 v[22:25], v[142:145], v[182:185], v[22:25]
	v_mfma_f32_16x16x32_bf16 v[18:21], v[158:161], v[182:185], v[18:21]
	v_mfma_f32_16x16x32_bf16 v[6:9], v[142:145], v[190:193], v[6:9]
	v_mfma_f32_16x16x32_bf16 v[2:5], v[158:161], v[190:193], v[2:5]
	s_setprio 0
	s_barrier
	s_add_i32 s74, 0, 0x18000
	s_add_i32 s75, 0, 0x1c000
	v_add_u32_e32 v134, s74, v244
	v_add_u32_e32 v158, s75, v244
	ds_read_b128 v[122:125], v134
	ds_read_b128 v[126:129], v134 offset:1024
	ds_read_b128 v[130:133], v134 offset:2048
	ds_read_b128 v[134:137], v134 offset:3072
	ds_read_b128 v[138:141], v158
	ds_read_b128 v[142:145], v158 offset:1024
	ds_read_b128 v[146:149], v158 offset:2048
	ds_read_b128 v[158:161], v158 offset:3072
	s_add_u32 s56, s56, 0x40000
	s_addc_u32 s57, s57, 0
	s_mov_b32 m0, s61
	v_lshl_add_u64 v[218:219], s[56:57], 0, v[194:195]
	ds_read_b128 v[162:165], v247 offset:32768
	ds_read_b128 v[166:169], v247 offset:33792
	ds_read_b128 v[170:173], v247 offset:34816
	ds_read_b128 v[174:177], v247 offset:35840
	ds_read_b128 v[178:181], v247 offset:36864
	ds_read_b128 v[182:185], v247 offset:37888
	ds_read_b128 v[186:189], v247 offset:38912
	ds_read_b128 v[190:193], v247 offset:39936
	global_load_lds_dwordx4 v[218:219], off
	v_lshl_add_u64 v[218:219], s[56:57], 0, v[198:199]
	s_mov_b32 m0, s62
	s_nop 0
	global_load_lds_dwordx4 v[218:219], off
	s_waitcnt vmcnt(8)
	s_waitcnt lgkmcnt(0)
	s_setprio 1
	s_barrier
	v_mfma_f32_16x16x32_bf16 v[154:157], v[122:125], v[162:165], v[154:157]
	v_mfma_f32_16x16x32_bf16 v[150:153], v[130:133], v[162:165], v[150:153]
	v_mfma_f32_16x16x32_bf16 v[110:113], v[122:125], v[170:173], v[110:113]
	v_mfma_f32_16x16x32_bf16 v[106:109], v[130:133], v[170:173], v[106:109]
	v_mfma_f32_16x16x32_bf16 v[94:97], v[122:125], v[178:181], v[94:97]
	v_mfma_f32_16x16x32_bf16 v[90:93], v[130:133], v[178:181], v[90:93]
	v_mfma_f32_16x16x32_bf16 v[78:81], v[122:125], v[186:189], v[78:81]
	v_mfma_f32_16x16x32_bf16 v[74:77], v[130:133], v[186:189], v[74:77]
	v_mfma_f32_16x16x32_bf16 v[154:157], v[126:129], v[166:169], v[154:157]
	v_mfma_f32_16x16x32_bf16 v[150:153], v[134:137], v[166:169], v[150:153]
	v_mfma_f32_16x16x32_bf16 v[110:113], v[126:129], v[174:177], v[110:113]
	v_mfma_f32_16x16x32_bf16 v[106:109], v[134:137], v[174:177], v[106:109]
	v_mfma_f32_16x16x32_bf16 v[94:97], v[126:129], v[182:185], v[94:97]
	v_mfma_f32_16x16x32_bf16 v[90:93], v[134:137], v[182:185], v[90:93]
	v_mfma_f32_16x16x32_bf16 v[78:81], v[126:129], v[190:193], v[78:81]
	v_mfma_f32_16x16x32_bf16 v[74:77], v[134:137], v[190:193], v[74:77]
	s_setprio 0
	s_setprio 1
	v_mfma_f32_16x16x32_bf16 v[118:121], v[138:141], v[162:165], v[118:121]
	v_mfma_f32_16x16x32_bf16 v[114:117], v[146:149], v[162:165], v[114:117]
	v_mfma_f32_16x16x32_bf16 v[102:105], v[138:141], v[170:173], v[102:105]
	v_mfma_f32_16x16x32_bf16 v[98:101], v[146:149], v[170:173], v[98:101]
	v_mfma_f32_16x16x32_bf16 v[86:89], v[138:141], v[178:181], v[86:89]
	v_mfma_f32_16x16x32_bf16 v[82:85], v[146:149], v[178:181], v[82:85]
	v_mfma_f32_16x16x32_bf16 v[70:73], v[138:141], v[186:189], v[70:73]
	v_mfma_f32_16x16x32_bf16 v[66:69], v[146:149], v[186:189], v[66:69]
	v_mfma_f32_16x16x32_bf16 v[118:121], v[142:145], v[166:169], v[118:121]
	v_mfma_f32_16x16x32_bf16 v[114:117], v[158:161], v[166:169], v[114:117]
	v_mfma_f32_16x16x32_bf16 v[102:105], v[142:145], v[174:177], v[102:105]
	v_mfma_f32_16x16x32_bf16 v[98:101], v[158:161], v[174:177], v[98:101]
	v_mfma_f32_16x16x32_bf16 v[86:89], v[142:145], v[182:185], v[86:89]
	v_mfma_f32_16x16x32_bf16 v[82:85], v[158:161], v[182:185], v[82:85]
	v_mfma_f32_16x16x32_bf16 v[70:73], v[142:145], v[190:193], v[70:73]
	v_mfma_f32_16x16x32_bf16 v[66:69], v[158:161], v[190:193], v[66:69]
	s_setprio 0
	s_barrier
	s_add_i32 s56, s74, s58
	v_lshl_add_u64 v[210:211], v[210:211], 0, s[16:17]
	s_mov_b32 m0, s56
	ds_read_b128 v[162:165], v247 offset:49152
	ds_read_b128 v[166:169], v247 offset:50176
	ds_read_b128 v[170:173], v247 offset:51200
	ds_read_b128 v[174:177], v247 offset:52224
	ds_read_b128 v[178:181], v247 offset:53248
	ds_read_b128 v[182:185], v247 offset:54272
	ds_read_b128 v[186:189], v247 offset:55296
	ds_read_b128 v[190:193], v247 offset:56320
	global_load_lds_dwordx4 v[210:211], off
	s_add_i32 m0, s56, 0x2000
	s_add_u32 s54, s54, 0x40080
	v_lshl_add_u64 v[210:211], v[212:213], 0, s[16:17]
	s_addc_u32 s55, s55, 0
	s_add_i32 s56, s75, s58
	global_load_lds_dwordx4 v[210:211], off
	v_lshl_add_u64 v[210:211], s[54:55], 0, v[196:197]
	s_mov_b32 m0, s56
	s_nop 0
	global_load_lds_dwordx4 v[210:211], off
	v_lshl_add_u64 v[210:211], s[54:55], 0, v[200:201]
	s_add_i32 m0, s56, 0x2000
	s_nop 0
	global_load_lds_dwordx4 v[210:211], off
	v_lshl_add_u64 v[210:211], v[214:215], 0, s[16:17]
	s_mov_b32 m0, s64
	s_nop 0
	global_load_lds_dwordx4 v[210:211], off
	v_lshl_add_u64 v[210:211], v[216:217], 0, s[16:17]
	s_mov_b32 m0, s65
	s_nop 0
	global_load_lds_dwordx4 v[210:211], off
	s_waitcnt vmcnt(8)
	s_waitcnt lgkmcnt(0)
	s_setprio 1
	s_barrier
	v_mfma_f32_16x16x32_bf16 v[62:65], v[122:125], v[162:165], v[62:65]
	v_mfma_f32_16x16x32_bf16 v[58:61], v[130:133], v[162:165], v[58:61]
	v_mfma_f32_16x16x32_bf16 v[46:49], v[122:125], v[170:173], v[46:49]
	v_mfma_f32_16x16x32_bf16 v[42:45], v[130:133], v[170:173], v[42:45]
	v_mfma_f32_16x16x32_bf16 v[30:33], v[122:125], v[178:181], v[30:33]
	v_mfma_f32_16x16x32_bf16 v[26:29], v[130:133], v[178:181], v[26:29]
	v_mfma_f32_16x16x32_bf16 v[14:17], v[122:125], v[186:189], v[14:17]
	v_mfma_f32_16x16x32_bf16 v[10:13], v[130:133], v[186:189], v[10:13]
	v_mfma_f32_16x16x32_bf16 v[62:65], v[126:129], v[166:169], v[62:65]
	v_mfma_f32_16x16x32_bf16 v[58:61], v[134:137], v[166:169], v[58:61]
	v_mfma_f32_16x16x32_bf16 v[46:49], v[126:129], v[174:177], v[46:49]
	v_mfma_f32_16x16x32_bf16 v[42:45], v[134:137], v[174:177], v[42:45]
	v_mfma_f32_16x16x32_bf16 v[30:33], v[126:129], v[182:185], v[30:33]
	v_mfma_f32_16x16x32_bf16 v[26:29], v[134:137], v[182:185], v[26:29]
	v_mfma_f32_16x16x32_bf16 v[14:17], v[126:129], v[190:193], v[14:17]
	v_mfma_f32_16x16x32_bf16 v[10:13], v[134:137], v[190:193], v[10:13]
	s_setprio 0
	s_setprio 1
	v_mfma_f32_16x16x32_bf16 v[54:57], v[138:141], v[162:165], v[54:57]
	v_mfma_f32_16x16x32_bf16 v[50:53], v[146:149], v[162:165], v[50:53]
	v_mfma_f32_16x16x32_bf16 v[38:41], v[138:141], v[170:173], v[38:41]
	v_mfma_f32_16x16x32_bf16 v[34:37], v[146:149], v[170:173], v[34:37]
	v_mfma_f32_16x16x32_bf16 v[22:25], v[138:141], v[178:181], v[22:25]
	v_mfma_f32_16x16x32_bf16 v[18:21], v[146:149], v[178:181], v[18:21]
	v_mfma_f32_16x16x32_bf16 v[6:9], v[138:141], v[186:189], v[6:9]
	v_mfma_f32_16x16x32_bf16 v[2:5], v[146:149], v[186:189], v[2:5]
	v_mfma_f32_16x16x32_bf16 v[54:57], v[142:145], v[166:169], v[54:57]
	v_mfma_f32_16x16x32_bf16 v[50:53], v[158:161], v[166:169], v[50:53]
	v_mfma_f32_16x16x32_bf16 v[38:41], v[142:145], v[174:177], v[38:41]
	v_mfma_f32_16x16x32_bf16 v[34:37], v[158:161], v[174:177], v[34:37]
	v_mfma_f32_16x16x32_bf16 v[22:25], v[142:145], v[182:185], v[22:25]
	v_mfma_f32_16x16x32_bf16 v[18:21], v[158:161], v[182:185], v[18:21]
	v_mfma_f32_16x16x32_bf16 v[6:9], v[142:145], v[190:193], v[6:9]
	v_mfma_f32_16x16x32_bf16 v[2:5], v[158:161], v[190:193], v[2:5]
	s_setprio 0
	s_add_i32 s73, s73, 2
	s_add_u32 s52, s52, 0x100
	s_addc_u32 s53, s53, 0
	s_add_u32 s71, s71, 0x100
	s_addc_u32 s72, s72, 0
	s_cmp_gt_u32 s73, 13
	s_barrier
	s_cbranch_scc0 .LBB0_739

.LBB0_839:
	s_ashr_i32 s27, s26, 31
	s_lshl_b64 s[42:43], s[26:27], 19
	s_add_u32 s42, s3, s42
	s_addc_u32 s43, s23, s43
	s_and_b64 s[44:45], s[4:5], exec
	s_cselect_b32 s27, s43, s49
	s_cselect_b32 s69, s42, s48
	s_ashr_i32 s25, s24, 31
	s_lshl_b64 s[44:45], s[24:25], 19
	s_add_u32 s44, s29, s44
	s_addc_u32 s45, s31, s45
	s_and_b64 s[52:53], s[4:5], exec
	s_cselect_b32 s25, s45, s51
	s_cselect_b32 s70, s44, s50
	s_add_u32 s48, s48, 0x40080
	s_addc_u32 s49, s49, 0
	s_add_u32 s71, s50, 0x100
	s_addc_u32 s72, s51, 0
	s_mov_b32 s73, -2
	s_waitcnt vmcnt(0)
	s_add_u32 s50, s48, 0xfffc0080
	s_addc_u32 s51, s49, -1
	s_cmp_eq_u32 s73, 12
	s_cselect_b32 s53, s27, s51
	s_cselect_b32 s52, s69, s50
	s_cselect_b32 s51, s25, s72
	s_cselect_b32 s50, s70, s71
	v_lshl_add_u64 v[148:149], s[48:49], 0, v[140:141]
	s_add_i32 m0, s57, 0xc000
	global_load_lds_dwordx4 v[148:149], off
	v_lshl_add_u64 v[148:149], s[48:49], 0, v[142:143]
	s_add_i32 m0, s57, 0xe000
	s_nop 0
	global_load_lds_dwordx4 v[148:149], off
	s_waitcnt vmcnt(8)
	s_waitcnt lgkmcnt(0)
	s_setprio 1
	s_barrier
	v_mfma_f32_16x16x32_bf16 v[118:121], v[160:163], v[192:195], 0
	v_mfma_f32_16x16x32_bf16 v[114:117], v[168:171], v[192:195], 0
	v_mfma_f32_16x16x32_bf16 v[106:109], v[160:163], v[200:203], 0
	v_mfma_f32_16x16x32_bf16 v[98:101], v[168:171], v[200:203], 0
	v_mfma_f32_16x16x32_bf16 v[90:93], v[160:163], v[208:211], 0
	v_mfma_f32_16x16x32_bf16 v[82:85], v[168:171], v[208:211], 0
	v_mfma_f32_16x16x32_bf16 v[74:77], v[160:163], v[216:219], 0
	v_mfma_f32_16x16x32_bf16 v[66:69], v[168:171], v[216:219], 0
	v_mfma_f32_16x16x32_bf16 v[118:121], v[164:167], v[196:199], v[118:121]
	v_mfma_f32_16x16x32_bf16 v[114:117], v[172:175], v[196:199], v[114:117]
	v_mfma_f32_16x16x32_bf16 v[106:109], v[164:167], v[204:207], v[106:109]
	v_mfma_f32_16x16x32_bf16 v[98:101], v[172:175], v[204:207], v[98:101]
	v_mfma_f32_16x16x32_bf16 v[90:93], v[164:167], v[212:215], v[90:93]
	v_mfma_f32_16x16x32_bf16 v[82:85], v[172:175], v[212:215], v[82:85]
	v_mfma_f32_16x16x32_bf16 v[74:77], v[164:167], v[220:223], v[74:77]
	v_mfma_f32_16x16x32_bf16 v[66:69], v[172:175], v[220:223], v[66:69]
	s_setprio 0
	s_setprio 1
	v_mfma_f32_16x16x32_bf16 v[126:129], v[176:179], v[192:195], 0
	v_mfma_f32_16x16x32_bf16 v[122:125], v[184:187], v[192:195], 0
	v_mfma_f32_16x16x32_bf16 v[110:113], v[176:179], v[200:203], 0
	v_mfma_f32_16x16x32_bf16 v[102:105], v[184:187], v[200:203], 0
	v_mfma_f32_16x16x32_bf16 v[94:97], v[176:179], v[208:211], 0
	v_mfma_f32_16x16x32_bf16 v[86:89], v[184:187], v[208:211], 0
	v_mfma_f32_16x16x32_bf16 v[78:81], v[176:179], v[216:219], 0
	v_mfma_f32_16x16x32_bf16 v[70:73], v[184:187], v[216:219], 0
	v_mfma_f32_16x16x32_bf16 v[126:129], v[180:183], v[196:199], v[126:129]
	v_mfma_f32_16x16x32_bf16 v[122:125], v[188:191], v[196:199], v[122:125]
	v_mfma_f32_16x16x32_bf16 v[110:113], v[180:183], v[204:207], v[110:113]
	v_mfma_f32_16x16x32_bf16 v[102:105], v[188:191], v[204:207], v[102:105]
	v_mfma_f32_16x16x32_bf16 v[94:97], v[180:183], v[212:215], v[94:97]
	v_mfma_f32_16x16x32_bf16 v[86:89], v[188:191], v[212:215], v[86:89]
	v_mfma_f32_16x16x32_bf16 v[78:81], v[180:183], v[220:223], v[78:81]
	v_mfma_f32_16x16x32_bf16 v[70:73], v[188:191], v[220:223], v[70:73]
	s_setprio 0
	s_barrier
	s_add_i32 s74, s66, s54
	v_lshl_add_u64 v[148:149], s[50:51], 0, v[134:135]
	s_mov_b32 m0, s74
	ds_read_b128 v[192:195], v157 offset:16384
	ds_read_b128 v[196:199], v157 offset:17408
	ds_read_b128 v[200:203], v157 offset:18432
	ds_read_b128 v[204:207], v157 offset:19456
	ds_read_b128 v[208:211], v157 offset:20480
	ds_read_b128 v[212:215], v157 offset:21504
	ds_read_b128 v[216:219], v157 offset:22528
	ds_read_b128 v[220:223], v157 offset:23552
	global_load_lds_dwordx4 v[148:149], off
	s_add_i32 m0, s74, 0x2000
	s_add_u32 s74, s50, 0x40000
	v_lshl_add_u64 v[224:225], s[50:51], 0, v[130:131]
	s_addc_u32 s75, s51, 0
	s_add_i32 s76, s67, s54
	global_load_lds_dwordx4 v[224:225], off
	v_lshl_add_u64 v[226:227], s[74:75], 0, v[134:135]
	s_mov_b32 m0, s76
	v_lshl_add_u64 v[228:229], s[52:53], 0, v[132:133]
	global_load_lds_dwordx4 v[226:227], off
	v_lshl_add_u64 v[226:227], s[74:75], 0, v[130:131]
	s_add_i32 m0, s76, 0x2000
	s_nop 0
	global_load_lds_dwordx4 v[226:227], off
	v_lshl_add_u64 v[226:227], s[52:53], 0, v[136:137]
	s_mov_b32 m0, s57
	s_nop 0
	global_load_lds_dwordx4 v[226:227], off
	s_mov_b32 m0, s58
	s_nop 0
	global_load_lds_dwordx4 v[228:229], off
	s_waitcnt vmcnt(8)
	s_waitcnt lgkmcnt(0)
	s_setprio 1
	s_barrier
	v_mfma_f32_16x16x32_bf16 v[58:61], v[160:163], v[192:195], 0
	v_mfma_f32_16x16x32_bf16 v[50:53], v[168:171], v[192:195], 0
	v_mfma_f32_16x16x32_bf16 v[42:45], v[160:163], v[200:203], 0
	v_mfma_f32_16x16x32_bf16 v[34:37], v[168:171], v[200:203], 0
	v_mfma_f32_16x16x32_bf16 v[26:29], v[160:163], v[208:211], 0
	v_mfma_f32_16x16x32_bf16 v[18:21], v[168:171], v[208:211], 0
	v_mfma_f32_16x16x32_bf16 v[10:13], v[160:163], v[216:219], 0
	v_mfma_f32_16x16x32_bf16 v[6:9], v[168:171], v[216:219], 0
	v_mfma_f32_16x16x32_bf16 v[58:61], v[164:167], v[196:199], v[58:61]
	v_mfma_f32_16x16x32_bf16 v[50:53], v[172:175], v[196:199], v[50:53]
	v_mfma_f32_16x16x32_bf16 v[42:45], v[164:167], v[204:207], v[42:45]
	v_mfma_f32_16x16x32_bf16 v[34:37], v[172:175], v[204:207], v[34:37]
	v_mfma_f32_16x16x32_bf16 v[26:29], v[164:167], v[212:215], v[26:29]
	v_mfma_f32_16x16x32_bf16 v[18:21], v[172:175], v[212:215], v[18:21]
	v_mfma_f32_16x16x32_bf16 v[10:13], v[164:167], v[220:223], v[10:13]
	v_mfma_f32_16x16x32_bf16 v[6:9], v[172:175], v[220:223], v[6:9]
	s_setprio 0
	s_setprio 1
	v_mfma_f32_16x16x32_bf16 v[62:65], v[176:179], v[192:195], 0
	v_mfma_f32_16x16x32_bf16 v[54:57], v[184:187], v[192:195], 0
	v_mfma_f32_16x16x32_bf16 v[46:49], v[176:179], v[200:203], 0
	v_mfma_f32_16x16x32_bf16 v[38:41], v[184:187], v[200:203], 0
	v_mfma_f32_16x16x32_bf16 v[30:33], v[176:179], v[208:211], 0
	v_mfma_f32_16x16x32_bf16 v[22:25], v[184:187], v[208:211], 0
	v_mfma_f32_16x16x32_bf16 v[14:17], v[176:179], v[216:219], 0
	v_mfma_f32_16x16x32_bf16 v[2:5], v[184:187], v[216:219], 0
	v_mfma_f32_16x16x32_bf16 v[62:65], v[180:183], v[196:199], v[62:65]
	v_mfma_f32_16x16x32_bf16 v[54:57], v[188:191], v[196:199], v[54:57]
	v_mfma_f32_16x16x32_bf16 v[46:49], v[180:183], v[204:207], v[46:49]
	v_mfma_f32_16x16x32_bf16 v[38:41], v[188:191], v[204:207], v[38:41]
	v_mfma_f32_16x16x32_bf16 v[30:33], v[180:183], v[212:215], v[30:33]
	v_mfma_f32_16x16x32_bf16 v[22:25], v[188:191], v[212:215], v[22:25]
	v_mfma_f32_16x16x32_bf16 v[14:17], v[180:183], v[220:223], v[14:17]
	v_mfma_f32_16x16x32_bf16 v[2:5], v[188:191], v[220:223], v[2:5]
	s_setprio 0
	s_barrier
	s_add_i32 s74, 0, 0x18000
	v_add_u32_e32 v159, s74, v151
	s_add_i32 s75, 0, 0x1c000
	ds_read_b128 v[160:163], v159
	ds_read_b128 v[164:167], v159 offset:1024
	ds_read_b128 v[168:171], v159 offset:2048
	ds_read_b128 v[172:175], v159 offset:3072
	v_add_u32_e32 v159, s75, v151
	ds_read_b128 v[176:179], v159
	ds_read_b128 v[180:183], v159 offset:1024
	ds_read_b128 v[184:187], v159 offset:2048
	ds_read_b128 v[188:191], v159 offset:3072
	s_add_u32 s52, s52, 0x40000
	s_addc_u32 s53, s53, 0
	s_mov_b32 m0, s59
	v_lshl_add_u64 v[230:231], s[52:53], 0, v[136:137]
	ds_read_b128 v[192:195], v157 offset:32768
	ds_read_b128 v[196:199], v157 offset:33792
	ds_read_b128 v[200:203], v157 offset:34816
	ds_read_b128 v[204:207], v157 offset:35840
	ds_read_b128 v[208:211], v157 offset:36864
	ds_read_b128 v[212:215], v157 offset:37888
	ds_read_b128 v[216:219], v157 offset:38912
	ds_read_b128 v[220:223], v157 offset:39936
	global_load_lds_dwordx4 v[230:231], off
	v_lshl_add_u64 v[230:231], s[52:53], 0, v[132:133]
	s_mov_b32 m0, s60
	s_nop 0
	global_load_lds_dwordx4 v[230:231], off
	s_waitcnt vmcnt(8)
	s_waitcnt lgkmcnt(0)
	s_setprio 1
	s_barrier
	v_mfma_f32_16x16x32_bf16 v[118:121], v[160:163], v[192:195], v[118:121]
	v_mfma_f32_16x16x32_bf16 v[114:117], v[168:171], v[192:195], v[114:117]
	v_mfma_f32_16x16x32_bf16 v[106:109], v[160:163], v[200:203], v[106:109]
	v_mfma_f32_16x16x32_bf16 v[98:101], v[168:171], v[200:203], v[98:101]
	v_mfma_f32_16x16x32_bf16 v[90:93], v[160:163], v[208:211], v[90:93]
	v_mfma_f32_16x16x32_bf16 v[82:85], v[168:171], v[208:211], v[82:85]
	v_mfma_f32_16x16x32_bf16 v[74:77], v[160:163], v[216:219], v[74:77]
	v_mfma_f32_16x16x32_bf16 v[66:69], v[168:171], v[216:219], v[66:69]
	v_mfma_f32_16x16x32_bf16 v[118:121], v[164:167], v[196:199], v[118:121]
	v_mfma_f32_16x16x32_bf16 v[114:117], v[172:175], v[196:199], v[114:117]
	v_mfma_f32_16x16x32_bf16 v[106:109], v[164:167], v[204:207], v[106:109]
	v_mfma_f32_16x16x32_bf16 v[98:101], v[172:175], v[204:207], v[98:101]
	v_mfma_f32_16x16x32_bf16 v[90:93], v[164:167], v[212:215], v[90:93]
	v_mfma_f32_16x16x32_bf16 v[82:85], v[172:175], v[212:215], v[82:85]
	v_mfma_f32_16x16x32_bf16 v[74:77], v[164:167], v[220:223], v[74:77]
	v_mfma_f32_16x16x32_bf16 v[66:69], v[172:175], v[220:223], v[66:69]
	s_setprio 0
	s_setprio 1
	v_mfma_f32_16x16x32_bf16 v[126:129], v[176:179], v[192:195], v[126:129]
	v_mfma_f32_16x16x32_bf16 v[122:125], v[184:187], v[192:195], v[122:125]
	v_mfma_f32_16x16x32_bf16 v[110:113], v[176:179], v[200:203], v[110:113]
	v_mfma_f32_16x16x32_bf16 v[102:105], v[184:187], v[200:203], v[102:105]
	v_mfma_f32_16x16x32_bf16 v[94:97], v[176:179], v[208:211], v[94:97]
	v_mfma_f32_16x16x32_bf16 v[86:89], v[184:187], v[208:211], v[86:89]
	v_mfma_f32_16x16x32_bf16 v[78:81], v[176:179], v[216:219], v[78:81]
	v_mfma_f32_16x16x32_bf16 v[70:73], v[184:187], v[216:219], v[70:73]
	v_mfma_f32_16x16x32_bf16 v[126:129], v[180:183], v[196:199], v[126:129]
	v_mfma_f32_16x16x32_bf16 v[122:125], v[188:191], v[196:199], v[122:125]
	v_mfma_f32_16x16x32_bf16 v[110:113], v[180:183], v[204:207], v[110:113]
	v_mfma_f32_16x16x32_bf16 v[102:105], v[188:191], v[204:207], v[102:105]
	v_mfma_f32_16x16x32_bf16 v[94:97], v[180:183], v[212:215], v[94:97]
	v_mfma_f32_16x16x32_bf16 v[86:89], v[188:191], v[212:215], v[86:89]
	v_mfma_f32_16x16x32_bf16 v[78:81], v[180:183], v[220:223], v[78:81]
	v_mfma_f32_16x16x32_bf16 v[70:73], v[188:191], v[220:223], v[70:73]
	s_setprio 0
	s_barrier
	s_add_i32 s52, s74, s54
	v_lshl_add_u64 v[148:149], v[148:149], 0, s[14:15]
	s_mov_b32 m0, s52
	ds_read_b128 v[192:195], v157 offset:49152
	ds_read_b128 v[196:199], v157 offset:50176
	ds_read_b128 v[200:203], v157 offset:51200
	ds_read_b128 v[204:207], v157 offset:52224
	ds_read_b128 v[208:211], v157 offset:53248
	ds_read_b128 v[212:215], v157 offset:54272
	ds_read_b128 v[216:219], v157 offset:55296
	ds_read_b128 v[220:223], v157 offset:56320
	global_load_lds_dwordx4 v[148:149], off
	s_add_i32 m0, s52, 0x2000
	s_add_u32 s50, s50, 0x40080
	v_lshl_add_u64 v[148:149], v[224:225], 0, s[14:15]
	s_addc_u32 s51, s51, 0
	s_add_i32 s52, s75, s54
	global_load_lds_dwordx4 v[148:149], off
	v_lshl_add_u64 v[148:149], s[50:51], 0, v[134:135]
	s_mov_b32 m0, s52
	s_nop 0
	global_load_lds_dwordx4 v[148:149], off
	v_lshl_add_u64 v[148:149], s[50:51], 0, v[130:131]
	s_add_i32 m0, s52, 0x2000
	s_nop 0
	global_load_lds_dwordx4 v[148:149], off
	v_lshl_add_u64 v[148:149], v[226:227], 0, s[14:15]
	s_mov_b32 m0, s62
	s_nop 0
	global_load_lds_dwordx4 v[148:149], off
	v_lshl_add_u64 v[148:149], v[228:229], 0, s[14:15]
	s_mov_b32 m0, s63
	s_nop 0
	global_load_lds_dwordx4 v[148:149], off
	s_waitcnt vmcnt(8)
	s_waitcnt lgkmcnt(0)
	s_setprio 1
	s_barrier
	v_mfma_f32_16x16x32_bf16 v[58:61], v[160:163], v[192:195], v[58:61]
	v_mfma_f32_16x16x32_bf16 v[50:53], v[168:171], v[192:195], v[50:53]
	v_mfma_f32_16x16x32_bf16 v[42:45], v[160:163], v[200:203], v[42:45]
	v_mfma_f32_16x16x32_bf16 v[34:37], v[168:171], v[200:203], v[34:37]
	v_mfma_f32_16x16x32_bf16 v[26:29], v[160:163], v[208:211], v[26:29]
	v_mfma_f32_16x16x32_bf16 v[18:21], v[168:171], v[208:211], v[18:21]
	v_mfma_f32_16x16x32_bf16 v[10:13], v[160:163], v[216:219], v[10:13]
	v_mfma_f32_16x16x32_bf16 v[6:9], v[168:171], v[216:219], v[6:9]
	v_mfma_f32_16x16x32_bf16 v[58:61], v[164:167], v[196:199], v[58:61]
	v_mfma_f32_16x16x32_bf16 v[50:53], v[172:175], v[196:199], v[50:53]
	v_mfma_f32_16x16x32_bf16 v[42:45], v[164:167], v[204:207], v[42:45]
	v_mfma_f32_16x16x32_bf16 v[34:37], v[172:175], v[204:207], v[34:37]
	v_mfma_f32_16x16x32_bf16 v[26:29], v[164:167], v[212:215], v[26:29]
	v_mfma_f32_16x16x32_bf16 v[18:21], v[172:175], v[212:215], v[18:21]
	v_mfma_f32_16x16x32_bf16 v[10:13], v[164:167], v[220:223], v[10:13]
	v_mfma_f32_16x16x32_bf16 v[6:9], v[172:175], v[220:223], v[6:9]
	s_setprio 0
	s_setprio 1
	v_mfma_f32_16x16x32_bf16 v[62:65], v[176:179], v[192:195], v[62:65]
	v_mfma_f32_16x16x32_bf16 v[54:57], v[184:187], v[192:195], v[54:57]
	v_mfma_f32_16x16x32_bf16 v[46:49], v[176:179], v[200:203], v[46:49]
	v_mfma_f32_16x16x32_bf16 v[38:41], v[184:187], v[200:203], v[38:41]
	v_mfma_f32_16x16x32_bf16 v[30:33], v[176:179], v[208:211], v[30:33]
	v_mfma_f32_16x16x32_bf16 v[22:25], v[184:187], v[208:211], v[22:25]
	v_mfma_f32_16x16x32_bf16 v[14:17], v[176:179], v[216:219], v[14:17]
	v_mfma_f32_16x16x32_bf16 v[2:5], v[184:187], v[216:219], v[2:5]
	v_mfma_f32_16x16x32_bf16 v[62:65], v[180:183], v[196:199], v[62:65]
	v_mfma_f32_16x16x32_bf16 v[54:57], v[188:191], v[196:199], v[54:57]
	v_mfma_f32_16x16x32_bf16 v[46:49], v[180:183], v[204:207], v[46:49]
	v_mfma_f32_16x16x32_bf16 v[38:41], v[188:191], v[204:207], v[38:41]
	v_mfma_f32_16x16x32_bf16 v[30:33], v[180:183], v[212:215], v[30:33]
	v_mfma_f32_16x16x32_bf16 v[22:25], v[188:191], v[212:215], v[22:25]
	v_mfma_f32_16x16x32_bf16 v[14:17], v[180:183], v[220:223], v[14:17]
	v_mfma_f32_16x16x32_bf16 v[2:5], v[188:191], v[220:223], v[2:5]
	s_setprio 0
	s_add_i32 s73, s73, 2
	s_add_u32 s48, s48, 0x100
	s_addc_u32 s49, s49, 0
	s_add_u32 s71, s71, 0x100
	s_addc_u32 s72, s72, 0
	s_cmp_gt_u32 s73, 13
	s_barrier
	s_cbranch_scc0 .LBB0_840
	s_branch .Lz_post_p6

.LBB0_938:
	s_add_u32 s69, s46, 0x100
	s_addc_u32 s70, s47, 0
	s_mov_b32 s71, -2
	s_waitcnt vmcnt(0)
	ds_read_b128 v[122:125], v245
	ds_read_b128 v[126:129], v245 offset:1024
	ds_read_b128 v[130:133], v245 offset:2048
	ds_read_b128 v[134:137], v245 offset:3072
	ds_read_b128 v[138:141], v246
	ds_read_b128 v[142:145], v246 offset:1024
	ds_read_b128 v[146:149], v246 offset:2048
	ds_read_b128 v[158:161], v246 offset:3072
	s_add_u32 s46, s44, 0x100
	s_addc_u32 s47, s45, 0
	s_cmp_eq_u32 s71, 40
	s_cselect_b32 s51, s9, s47
	s_cselect_b32 s50, s8, s46
	s_cselect_b32 s49, s43, s70
	s_cselect_b32 s48, s42, s69
	v_lshl_add_u64 v[210:211], s[44:45], 0, v[206:207]
	s_add_i32 m0, s53, 0xc000
	ds_read_b128 v[162:165], v247
	ds_read_b128 v[166:169], v247 offset:1024
	ds_read_b128 v[170:173], v247 offset:2048
	ds_read_b128 v[174:177], v247 offset:3072
	ds_read_b128 v[178:181], v247 offset:4096
	ds_read_b128 v[182:185], v247 offset:5120
	ds_read_b128 v[186:189], v247 offset:6144
	ds_read_b128 v[190:193], v247 offset:7168
	global_load_lds_dwordx4 v[210:211], off
	v_lshl_add_u64 v[210:211], s[44:45], 0, v[208:209]
	s_add_i32 m0, s53, 0xe000
	s_nop 0
	global_load_lds_dwordx4 v[210:211], off
	s_waitcnt vmcnt(8)
	s_waitcnt lgkmcnt(0)
	s_setprio 1
	s_barrier
	v_mfma_f32_16x16x32_bf16 v[154:157], v[122:125], v[162:165], 0
	v_mfma_f32_16x16x32_bf16 v[150:153], v[130:133], v[162:165], 0
	v_mfma_f32_16x16x32_bf16 v[110:113], v[122:125], v[170:173], 0
	v_mfma_f32_16x16x32_bf16 v[106:109], v[130:133], v[170:173], 0
	v_mfma_f32_16x16x32_bf16 v[94:97], v[122:125], v[178:181], 0
	v_mfma_f32_16x16x32_bf16 v[90:93], v[130:133], v[178:181], 0
	v_mfma_f32_16x16x32_bf16 v[78:81], v[122:125], v[186:189], 0
	v_mfma_f32_16x16x32_bf16 v[74:77], v[130:133], v[186:189], 0
	v_mfma_f32_16x16x32_bf16 v[154:157], v[126:129], v[166:169], v[154:157]
	v_mfma_f32_16x16x32_bf16 v[150:153], v[134:137], v[166:169], v[150:153]
	v_mfma_f32_16x16x32_bf16 v[110:113], v[126:129], v[174:177], v[110:113]
	v_mfma_f32_16x16x32_bf16 v[106:109], v[134:137], v[174:177], v[106:109]
	v_mfma_f32_16x16x32_bf16 v[94:97], v[126:129], v[182:185], v[94:97]
	v_mfma_f32_16x16x32_bf16 v[90:93], v[134:137], v[182:185], v[90:93]
	v_mfma_f32_16x16x32_bf16 v[78:81], v[126:129], v[190:193], v[78:81]
	v_mfma_f32_16x16x32_bf16 v[74:77], v[134:137], v[190:193], v[74:77]
	s_setprio 0
	s_setprio 1
	v_mfma_f32_16x16x32_bf16 v[118:121], v[138:141], v[162:165], 0
	v_mfma_f32_16x16x32_bf16 v[114:117], v[146:149], v[162:165], 0
	v_mfma_f32_16x16x32_bf16 v[102:105], v[138:141], v[170:173], 0
	v_mfma_f32_16x16x32_bf16 v[98:101], v[146:149], v[170:173], 0
	v_mfma_f32_16x16x32_bf16 v[86:89], v[138:141], v[178:181], 0
	v_mfma_f32_16x16x32_bf16 v[82:85], v[146:149], v[178:181], 0
	v_mfma_f32_16x16x32_bf16 v[70:73], v[138:141], v[186:189], 0
	v_mfma_f32_16x16x32_bf16 v[66:69], v[146:149], v[186:189], 0
	v_mfma_f32_16x16x32_bf16 v[118:121], v[142:145], v[166:169], v[118:121]
	v_mfma_f32_16x16x32_bf16 v[114:117], v[158:161], v[166:169], v[114:117]
	v_mfma_f32_16x16x32_bf16 v[102:105], v[142:145], v[174:177], v[102:105]
	v_mfma_f32_16x16x32_bf16 v[98:101], v[158:161], v[174:177], v[98:101]
	v_mfma_f32_16x16x32_bf16 v[86:89], v[142:145], v[182:185], v[86:89]
	v_mfma_f32_16x16x32_bf16 v[82:85], v[158:161], v[182:185], v[82:85]
	v_mfma_f32_16x16x32_bf16 v[70:73], v[142:145], v[190:193], v[70:73]
	v_mfma_f32_16x16x32_bf16 v[66:69], v[158:161], v[190:193], v[66:69]
	s_setprio 0
	s_barrier
	s_add_i32 s44, s63, s52
	v_lshl_add_u64 v[210:211], s[48:49], 0, v[196:197]
	s_mov_b32 m0, s44
	ds_read_b128 v[162:165], v247 offset:16384
	ds_read_b128 v[166:169], v247 offset:17408
	ds_read_b128 v[170:173], v247 offset:18432
	ds_read_b128 v[174:177], v247 offset:19456
	ds_read_b128 v[178:181], v247 offset:20480
	ds_read_b128 v[182:185], v247 offset:21504
	ds_read_b128 v[186:189], v247 offset:22528
	ds_read_b128 v[190:193], v247 offset:23552
	global_load_lds_dwordx4 v[210:211], off
	s_add_i32 m0, s44, 0x2000
	s_add_u32 s44, s48, 0xb0000
	v_lshl_add_u64 v[212:213], s[48:49], 0, v[200:201]
	s_addc_u32 s45, s49, 0
	s_add_i32 s72, s64, s52
	global_load_lds_dwordx4 v[212:213], off
	v_lshl_add_u64 v[214:215], s[44:45], 0, v[196:197]
	s_mov_b32 m0, s72
	v_lshl_add_u64 v[216:217], s[50:51], 0, v[198:199]
	global_load_lds_dwordx4 v[214:215], off
	v_lshl_add_u64 v[214:215], s[44:45], 0, v[200:201]
	s_add_i32 m0, s72, 0x2000
	s_nop 0
	global_load_lds_dwordx4 v[214:215], off
	v_lshl_add_u64 v[214:215], s[50:51], 0, v[194:195]
	s_mov_b32 m0, s53
	s_nop 0
	global_load_lds_dwordx4 v[214:215], off
	s_mov_b32 m0, s54
	s_nop 0
	global_load_lds_dwordx4 v[216:217], off
	s_waitcnt vmcnt(8)
	s_waitcnt lgkmcnt(0)
	s_setprio 1
	s_barrier
	v_mfma_f32_16x16x32_bf16 v[62:65], v[122:125], v[162:165], 0
	v_mfma_f32_16x16x32_bf16 v[58:61], v[130:133], v[162:165], 0
	v_mfma_f32_16x16x32_bf16 v[46:49], v[122:125], v[170:173], 0
	v_mfma_f32_16x16x32_bf16 v[42:45], v[130:133], v[170:173], 0
	v_mfma_f32_16x16x32_bf16 v[30:33], v[122:125], v[178:181], 0
	v_mfma_f32_16x16x32_bf16 v[26:29], v[130:133], v[178:181], 0
	v_mfma_f32_16x16x32_bf16 v[14:17], v[122:125], v[186:189], 0
	v_mfma_f32_16x16x32_bf16 v[10:13], v[130:133], v[186:189], 0
	v_mfma_f32_16x16x32_bf16 v[62:65], v[126:129], v[166:169], v[62:65]
	v_mfma_f32_16x16x32_bf16 v[58:61], v[134:137], v[166:169], v[58:61]
	v_mfma_f32_16x16x32_bf16 v[46:49], v[126:129], v[174:177], v[46:49]
	v_mfma_f32_16x16x32_bf16 v[42:45], v[134:137], v[174:177], v[42:45]
	v_mfma_f32_16x16x32_bf16 v[30:33], v[126:129], v[182:185], v[30:33]
	v_mfma_f32_16x16x32_bf16 v[26:29], v[134:137], v[182:185], v[26:29]
	v_mfma_f32_16x16x32_bf16 v[14:17], v[126:129], v[190:193], v[14:17]
	v_mfma_f32_16x16x32_bf16 v[10:13], v[134:137], v[190:193], v[10:13]
	s_setprio 0
	s_setprio 1
	v_mfma_f32_16x16x32_bf16 v[54:57], v[138:141], v[162:165], 0
	v_mfma_f32_16x16x32_bf16 v[50:53], v[146:149], v[162:165], 0
	v_mfma_f32_16x16x32_bf16 v[38:41], v[138:141], v[170:173], 0
	v_mfma_f32_16x16x32_bf16 v[34:37], v[146:149], v[170:173], 0
	v_mfma_f32_16x16x32_bf16 v[22:25], v[138:141], v[178:181], 0
	v_mfma_f32_16x16x32_bf16 v[18:21], v[146:149], v[178:181], 0
	v_mfma_f32_16x16x32_bf16 v[6:9], v[138:141], v[186:189], 0
	v_mfma_f32_16x16x32_bf16 v[2:5], v[146:149], v[186:189], 0
	v_mfma_f32_16x16x32_bf16 v[54:57], v[142:145], v[166:169], v[54:57]
	v_mfma_f32_16x16x32_bf16 v[50:53], v[158:161], v[166:169], v[50:53]
	v_mfma_f32_16x16x32_bf16 v[38:41], v[142:145], v[174:177], v[38:41]
	v_mfma_f32_16x16x32_bf16 v[34:37], v[158:161], v[174:177], v[34:37]
	v_mfma_f32_16x16x32_bf16 v[22:25], v[142:145], v[182:185], v[22:25]
	v_mfma_f32_16x16x32_bf16 v[18:21], v[158:161], v[182:185], v[18:21]
	v_mfma_f32_16x16x32_bf16 v[6:9], v[142:145], v[190:193], v[6:9]
	v_mfma_f32_16x16x32_bf16 v[2:5], v[158:161], v[190:193], v[2:5]
	s_setprio 0
	s_barrier
	s_add_i32 s72, 0, 0x18000
	s_add_i32 s73, 0, 0x1c000
	v_add_u32_e32 v134, s72, v244
	v_add_u32_e32 v158, s73, v244
	ds_read_b128 v[122:125], v134
	ds_read_b128 v[126:129], v134 offset:1024
	ds_read_b128 v[130:133], v134 offset:2048
	ds_read_b128 v[134:137], v134 offset:3072
	ds_read_b128 v[138:141], v158
	ds_read_b128 v[142:145], v158 offset:1024
	ds_read_b128 v[146:149], v158 offset:2048
	ds_read_b128 v[158:161], v158 offset:3072
	s_add_u32 s44, s50, 0xb0000
	s_addc_u32 s45, s51, 0
	s_mov_b32 m0, s55
	v_lshl_add_u64 v[218:219], s[44:45], 0, v[194:195]
	ds_read_b128 v[162:165], v247 offset:32768
	ds_read_b128 v[166:169], v247 offset:33792
	ds_read_b128 v[170:173], v247 offset:34816
	ds_read_b128 v[174:177], v247 offset:35840
	ds_read_b128 v[178:181], v247 offset:36864
	ds_read_b128 v[182:185], v247 offset:37888
	ds_read_b128 v[186:189], v247 offset:38912
	ds_read_b128 v[190:193], v247 offset:39936
	global_load_lds_dwordx4 v[218:219], off
	v_lshl_add_u64 v[218:219], s[44:45], 0, v[198:199]
	s_mov_b32 m0, s56
	s_nop 0
	global_load_lds_dwordx4 v[218:219], off
	s_waitcnt vmcnt(8)
	s_waitcnt lgkmcnt(0)
	s_setprio 1
	s_barrier
	v_mfma_f32_16x16x32_bf16 v[154:157], v[122:125], v[162:165], v[154:157]
	v_mfma_f32_16x16x32_bf16 v[150:153], v[130:133], v[162:165], v[150:153]
	v_mfma_f32_16x16x32_bf16 v[110:113], v[122:125], v[170:173], v[110:113]
	v_mfma_f32_16x16x32_bf16 v[106:109], v[130:133], v[170:173], v[106:109]
	v_mfma_f32_16x16x32_bf16 v[94:97], v[122:125], v[178:181], v[94:97]
	v_mfma_f32_16x16x32_bf16 v[90:93], v[130:133], v[178:181], v[90:93]
	v_mfma_f32_16x16x32_bf16 v[78:81], v[122:125], v[186:189], v[78:81]
	v_mfma_f32_16x16x32_bf16 v[74:77], v[130:133], v[186:189], v[74:77]
	v_mfma_f32_16x16x32_bf16 v[154:157], v[126:129], v[166:169], v[154:157]
	v_mfma_f32_16x16x32_bf16 v[150:153], v[134:137], v[166:169], v[150:153]
	v_mfma_f32_16x16x32_bf16 v[110:113], v[126:129], v[174:177], v[110:113]
	v_mfma_f32_16x16x32_bf16 v[106:109], v[134:137], v[174:177], v[106:109]
	v_mfma_f32_16x16x32_bf16 v[94:97], v[126:129], v[182:185], v[94:97]
	v_mfma_f32_16x16x32_bf16 v[90:93], v[134:137], v[182:185], v[90:93]
	v_mfma_f32_16x16x32_bf16 v[78:81], v[126:129], v[190:193], v[78:81]
	v_mfma_f32_16x16x32_bf16 v[74:77], v[134:137], v[190:193], v[74:77]
	s_setprio 0
	s_setprio 1
	v_mfma_f32_16x16x32_bf16 v[118:121], v[138:141], v[162:165], v[118:121]
	v_mfma_f32_16x16x32_bf16 v[114:117], v[146:149], v[162:165], v[114:117]
	v_mfma_f32_16x16x32_bf16 v[102:105], v[138:141], v[170:173], v[102:105]
	v_mfma_f32_16x16x32_bf16 v[98:101], v[146:149], v[170:173], v[98:101]
	v_mfma_f32_16x16x32_bf16 v[86:89], v[138:141], v[178:181], v[86:89]
	v_mfma_f32_16x16x32_bf16 v[82:85], v[146:149], v[178:181], v[82:85]
	v_mfma_f32_16x16x32_bf16 v[70:73], v[138:141], v[186:189], v[70:73]
	v_mfma_f32_16x16x32_bf16 v[66:69], v[146:149], v[186:189], v[66:69]
	v_mfma_f32_16x16x32_bf16 v[118:121], v[142:145], v[166:169], v[118:121]
	v_mfma_f32_16x16x32_bf16 v[114:117], v[158:161], v[166:169], v[114:117]
	v_mfma_f32_16x16x32_bf16 v[102:105], v[142:145], v[174:177], v[102:105]
	v_mfma_f32_16x16x32_bf16 v[98:101], v[158:161], v[174:177], v[98:101]
	v_mfma_f32_16x16x32_bf16 v[86:89], v[142:145], v[182:185], v[86:89]
	v_mfma_f32_16x16x32_bf16 v[82:85], v[158:161], v[182:185], v[82:85]
	v_mfma_f32_16x16x32_bf16 v[70:73], v[142:145], v[190:193], v[70:73]
	v_mfma_f32_16x16x32_bf16 v[66:69], v[158:161], v[190:193], v[66:69]
	s_setprio 0
	s_barrier
	s_add_i32 s44, s72, s52
	v_lshl_add_u64 v[210:211], v[210:211], 0, s[24:25]
	s_mov_b32 m0, s44
	ds_read_b128 v[162:165], v247 offset:49152
	ds_read_b128 v[166:169], v247 offset:50176
	ds_read_b128 v[170:173], v247 offset:51200
	ds_read_b128 v[174:177], v247 offset:52224
	ds_read_b128 v[178:181], v247 offset:53248
	ds_read_b128 v[182:185], v247 offset:54272
	ds_read_b128 v[186:189], v247 offset:55296
	ds_read_b128 v[190:193], v247 offset:56320
	global_load_lds_dwordx4 v[210:211], off
	s_add_i32 m0, s44, 0x2000
	s_add_u32 s44, s48, 0xb0080
	v_lshl_add_u64 v[210:211], v[212:213], 0, s[24:25]
	s_addc_u32 s45, s49, 0
	s_add_i32 s48, s73, s52
	global_load_lds_dwordx4 v[210:211], off
	v_lshl_add_u64 v[210:211], s[44:45], 0, v[196:197]
	s_mov_b32 m0, s48
	s_nop 0
	global_load_lds_dwordx4 v[210:211], off
	v_lshl_add_u64 v[210:211], s[44:45], 0, v[200:201]
	s_add_i32 m0, s48, 0x2000
	s_nop 0
	global_load_lds_dwordx4 v[210:211], off
	v_lshl_add_u64 v[210:211], v[214:215], 0, s[24:25]
	s_mov_b32 m0, s58
	s_nop 0
	global_load_lds_dwordx4 v[210:211], off
	v_lshl_add_u64 v[210:211], v[216:217], 0, s[24:25]
	s_mov_b32 m0, s59
	s_nop 0
	global_load_lds_dwordx4 v[210:211], off
	s_waitcnt vmcnt(8)
	s_waitcnt lgkmcnt(0)
	s_setprio 1
	s_barrier
	v_mfma_f32_16x16x32_bf16 v[62:65], v[122:125], v[162:165], v[62:65]
	v_mfma_f32_16x16x32_bf16 v[58:61], v[130:133], v[162:165], v[58:61]
	v_mfma_f32_16x16x32_bf16 v[46:49], v[122:125], v[170:173], v[46:49]
	v_mfma_f32_16x16x32_bf16 v[42:45], v[130:133], v[170:173], v[42:45]
	v_mfma_f32_16x16x32_bf16 v[30:33], v[122:125], v[178:181], v[30:33]
	v_mfma_f32_16x16x32_bf16 v[26:29], v[130:133], v[178:181], v[26:29]
	v_mfma_f32_16x16x32_bf16 v[14:17], v[122:125], v[186:189], v[14:17]
	v_mfma_f32_16x16x32_bf16 v[10:13], v[130:133], v[186:189], v[10:13]
	v_mfma_f32_16x16x32_bf16 v[62:65], v[126:129], v[166:169], v[62:65]
	v_mfma_f32_16x16x32_bf16 v[58:61], v[134:137], v[166:169], v[58:61]
	v_mfma_f32_16x16x32_bf16 v[46:49], v[126:129], v[174:177], v[46:49]
	v_mfma_f32_16x16x32_bf16 v[42:45], v[134:137], v[174:177], v[42:45]
	v_mfma_f32_16x16x32_bf16 v[30:33], v[126:129], v[182:185], v[30:33]
	v_mfma_f32_16x16x32_bf16 v[26:29], v[134:137], v[182:185], v[26:29]
	v_mfma_f32_16x16x32_bf16 v[14:17], v[126:129], v[190:193], v[14:17]
	v_mfma_f32_16x16x32_bf16 v[10:13], v[134:137], v[190:193], v[10:13]
	s_setprio 0
	s_setprio 1
	v_mfma_f32_16x16x32_bf16 v[54:57], v[138:141], v[162:165], v[54:57]
	v_mfma_f32_16x16x32_bf16 v[50:53], v[146:149], v[162:165], v[50:53]
	v_mfma_f32_16x16x32_bf16 v[38:41], v[138:141], v[170:173], v[38:41]
	v_mfma_f32_16x16x32_bf16 v[34:37], v[146:149], v[170:173], v[34:37]
	v_mfma_f32_16x16x32_bf16 v[22:25], v[138:141], v[178:181], v[22:25]
	v_mfma_f32_16x16x32_bf16 v[18:21], v[146:149], v[178:181], v[18:21]
	v_mfma_f32_16x16x32_bf16 v[6:9], v[138:141], v[186:189], v[6:9]
	v_mfma_f32_16x16x32_bf16 v[2:5], v[146:149], v[186:189], v[2:5]
	v_mfma_f32_16x16x32_bf16 v[54:57], v[142:145], v[166:169], v[54:57]
	v_mfma_f32_16x16x32_bf16 v[50:53], v[158:161], v[166:169], v[50:53]
	v_mfma_f32_16x16x32_bf16 v[38:41], v[142:145], v[174:177], v[38:41]
	v_mfma_f32_16x16x32_bf16 v[34:37], v[158:161], v[174:177], v[34:37]
	v_mfma_f32_16x16x32_bf16 v[22:25], v[142:145], v[182:185], v[22:25]
	v_mfma_f32_16x16x32_bf16 v[18:21], v[158:161], v[182:185], v[18:21]
	v_mfma_f32_16x16x32_bf16 v[6:9], v[142:145], v[190:193], v[6:9]
	v_mfma_f32_16x16x32_bf16 v[2:5], v[158:161], v[190:193], v[2:5]
	s_setprio 0
	s_add_i32 s71, s71, 2
	s_add_u32 s69, s69, 0x100
	s_addc_u32 s70, s70, 0
	s_cmp_gt_u32 s71, 41
	s_mov_b64 s[44:45], s[46:47]
	s_barrier
	s_cbranch_scc0 .LBB0_939
	s_branch .Lz_post_p7

.LBB0_1049:
	s_ashr_i32 s51, s50, 31
	s_lshl_b64 s[52:53], s[50:51], 19
	s_add_u32 s52, s3, s52
	s_addc_u32 s53, s23, s53
	s_and_b64 s[54:55], s[6:7], exec
	s_cselect_b32 s9, s53, s57
	s_cselect_b32 s11, s52, s56
	s_ashr_i32 s49, s48, 31
	s_lshl_b64 s[54:55], s[48:49], 19
	s_add_u32 s54, s29, s54
	s_addc_u32 s55, s31, s55
	s_and_b64 s[60:61], s[6:7], exec
	s_cselect_b32 s49, s55, s59
	s_cselect_b32 s51, s54, s58
	s_add_u32 s56, s56, 0x40080
	s_addc_u32 s57, s57, 0
	s_add_u32 s79, s58, 0x100
	s_addc_u32 s80, s59, 0
	s_mov_b32 s81, -2
	s_waitcnt lgkmcnt(0)
	s_waitcnt vmcnt(0)
	ds_read_b128 v[162:165], v156
	ds_read_b128 v[166:169], v156 offset:1024
	ds_read_b128 v[170:173], v156 offset:2048
	ds_read_b128 v[174:177], v156 offset:3072
	ds_read_b128 v[178:181], v157
	ds_read_b128 v[182:185], v157 offset:1024
	ds_read_b128 v[186:189], v157 offset:2048
	ds_read_b128 v[190:193], v157 offset:3072
	s_add_u32 s58, s56, 0xfffc0080
	s_addc_u32 s59, s57, -1
	s_cmp_eq_u32 s81, 12
	s_cselect_b32 s61, s9, s59
	s_cselect_b32 s60, s11, s58
	s_cselect_b32 s59, s49, s80
	s_cselect_b32 s58, s51, s79
	v_lshl_add_u64 v[150:151], s[56:57], 0, v[142:143]
	s_add_i32 m0, s63, 0xc000
	ds_read_b128 v[194:197], v158
	ds_read_b128 v[198:201], v158 offset:1024
	ds_read_b128 v[202:205], v158 offset:2048
	ds_read_b128 v[206:209], v158 offset:3072
	ds_read_b128 v[210:213], v158 offset:4096
	ds_read_b128 v[214:217], v158 offset:5120
	ds_read_b128 v[218:221], v158 offset:6144
	ds_read_b128 v[222:225], v158 offset:7168
	global_load_lds_dwordx4 v[150:151], off
	v_lshl_add_u64 v[150:151], s[56:57], 0, v[144:145]
	s_add_i32 m0, s63, 0xe000
	s_nop 0
	global_load_lds_dwordx4 v[150:151], off
	s_waitcnt vmcnt(8)
	s_waitcnt lgkmcnt(0)
	s_setprio 1
	s_barrier
	v_mfma_f32_16x16x32_bf16 v[126:129], v[162:165], v[194:197], 0
	v_mfma_f32_16x16x32_bf16 v[122:125], v[170:173], v[194:197], 0
	v_mfma_f32_16x16x32_bf16 v[110:113], v[162:165], v[202:205], 0
	v_mfma_f32_16x16x32_bf16 v[106:109], v[170:173], v[202:205], 0
	v_mfma_f32_16x16x32_bf16 v[94:97], v[162:165], v[210:213], 0
	v_mfma_f32_16x16x32_bf16 v[90:93], v[170:173], v[210:213], 0
	v_mfma_f32_16x16x32_bf16 v[78:81], v[162:165], v[218:221], 0
	v_mfma_f32_16x16x32_bf16 v[74:77], v[170:173], v[218:221], 0
	v_mfma_f32_16x16x32_bf16 v[126:129], v[166:169], v[198:201], v[126:129]
	v_mfma_f32_16x16x32_bf16 v[122:125], v[174:177], v[198:201], v[122:125]
	v_mfma_f32_16x16x32_bf16 v[110:113], v[166:169], v[206:209], v[110:113]
	v_mfma_f32_16x16x32_bf16 v[106:109], v[174:177], v[206:209], v[106:109]
	v_mfma_f32_16x16x32_bf16 v[94:97], v[166:169], v[214:217], v[94:97]
	v_mfma_f32_16x16x32_bf16 v[90:93], v[174:177], v[214:217], v[90:93]
	v_mfma_f32_16x16x32_bf16 v[78:81], v[166:169], v[222:225], v[78:81]
	v_mfma_f32_16x16x32_bf16 v[74:77], v[174:177], v[222:225], v[74:77]
	s_setprio 0
	s_setprio 1
	v_mfma_f32_16x16x32_bf16 v[118:121], v[178:181], v[194:197], 0
	v_mfma_f32_16x16x32_bf16 v[114:117], v[186:189], v[194:197], 0
	v_mfma_f32_16x16x32_bf16 v[102:105], v[178:181], v[202:205], 0
	v_mfma_f32_16x16x32_bf16 v[98:101], v[186:189], v[202:205], 0
	v_mfma_f32_16x16x32_bf16 v[86:89], v[178:181], v[210:213], 0
	v_mfma_f32_16x16x32_bf16 v[82:85], v[186:189], v[210:213], 0
	v_mfma_f32_16x16x32_bf16 v[70:73], v[178:181], v[218:221], 0
	v_mfma_f32_16x16x32_bf16 v[66:69], v[186:189], v[218:221], 0
	v_mfma_f32_16x16x32_bf16 v[118:121], v[182:185], v[198:201], v[118:121]
	v_mfma_f32_16x16x32_bf16 v[114:117], v[190:193], v[198:201], v[114:117]
	v_mfma_f32_16x16x32_bf16 v[102:105], v[182:185], v[206:209], v[102:105]
	v_mfma_f32_16x16x32_bf16 v[98:101], v[190:193], v[206:209], v[98:101]
	v_mfma_f32_16x16x32_bf16 v[86:89], v[182:185], v[214:217], v[86:89]
	v_mfma_f32_16x16x32_bf16 v[82:85], v[190:193], v[214:217], v[82:85]
	v_mfma_f32_16x16x32_bf16 v[70:73], v[182:185], v[222:225], v[70:73]
	v_mfma_f32_16x16x32_bf16 v[66:69], v[190:193], v[222:225], v[66:69]
	s_setprio 0
	s_barrier
	s_add_i32 s82, s73, s62
	v_lshl_add_u64 v[150:151], s[58:59], 0, v[132:133]
	s_mov_b32 m0, s82
	ds_read_b128 v[194:197], v158 offset:16384
	ds_read_b128 v[198:201], v158 offset:17408
	ds_read_b128 v[202:205], v158 offset:18432
	ds_read_b128 v[206:209], v158 offset:19456
	ds_read_b128 v[210:213], v158 offset:20480
	ds_read_b128 v[214:217], v158 offset:21504
	ds_read_b128 v[218:221], v158 offset:22528
	ds_read_b128 v[222:225], v158 offset:23552
	global_load_lds_dwordx4 v[150:151], off
	s_add_i32 m0, s82, 0x2000
	s_add_u32 s82, s58, 0x40000
	v_lshl_add_u64 v[226:227], s[58:59], 0, v[136:137]
	s_addc_u32 s83, s59, 0
	s_add_i32 s84, s74, s62
	global_load_lds_dwordx4 v[226:227], off
	v_lshl_add_u64 v[228:229], s[82:83], 0, v[132:133]
	s_mov_b32 m0, s84
	v_lshl_add_u64 v[230:231], s[60:61], 0, v[134:135]
	global_load_lds_dwordx4 v[228:229], off
	v_lshl_add_u64 v[228:229], s[82:83], 0, v[136:137]
	s_add_i32 m0, s84, 0x2000
	s_nop 0
	global_load_lds_dwordx4 v[228:229], off
	v_lshl_add_u64 v[228:229], s[60:61], 0, v[130:131]
	s_mov_b32 m0, s63
	s_nop 0
	global_load_lds_dwordx4 v[228:229], off
	s_mov_b32 m0, s64
	s_nop 0
	global_load_lds_dwordx4 v[230:231], off
	s_waitcnt vmcnt(8)
	s_waitcnt lgkmcnt(0)
	s_setprio 1
	s_barrier
	v_mfma_f32_16x16x32_bf16 v[62:65], v[162:165], v[194:197], 0
	v_mfma_f32_16x16x32_bf16 v[58:61], v[170:173], v[194:197], 0
	v_mfma_f32_16x16x32_bf16 v[46:49], v[162:165], v[202:205], 0
	v_mfma_f32_16x16x32_bf16 v[42:45], v[170:173], v[202:205], 0
	v_mfma_f32_16x16x32_bf16 v[30:33], v[162:165], v[210:213], 0
	v_mfma_f32_16x16x32_bf16 v[26:29], v[170:173], v[210:213], 0
	v_mfma_f32_16x16x32_bf16 v[14:17], v[162:165], v[218:221], 0
	v_mfma_f32_16x16x32_bf16 v[10:13], v[170:173], v[218:221], 0
	v_mfma_f32_16x16x32_bf16 v[62:65], v[166:169], v[198:201], v[62:65]
	v_mfma_f32_16x16x32_bf16 v[58:61], v[174:177], v[198:201], v[58:61]
	v_mfma_f32_16x16x32_bf16 v[46:49], v[166:169], v[206:209], v[46:49]
	v_mfma_f32_16x16x32_bf16 v[42:45], v[174:177], v[206:209], v[42:45]
	v_mfma_f32_16x16x32_bf16 v[30:33], v[166:169], v[214:217], v[30:33]
	v_mfma_f32_16x16x32_bf16 v[26:29], v[174:177], v[214:217], v[26:29]
	v_mfma_f32_16x16x32_bf16 v[14:17], v[166:169], v[222:225], v[14:17]
	v_mfma_f32_16x16x32_bf16 v[10:13], v[174:177], v[222:225], v[10:13]
	s_setprio 0
	s_setprio 1
	v_mfma_f32_16x16x32_bf16 v[54:57], v[178:181], v[194:197], 0
	v_mfma_f32_16x16x32_bf16 v[50:53], v[186:189], v[194:197], 0
	v_mfma_f32_16x16x32_bf16 v[38:41], v[178:181], v[202:205], 0
	v_mfma_f32_16x16x32_bf16 v[34:37], v[186:189], v[202:205], 0
	v_mfma_f32_16x16x32_bf16 v[22:25], v[178:181], v[210:213], 0
	v_mfma_f32_16x16x32_bf16 v[18:21], v[186:189], v[210:213], 0
	v_mfma_f32_16x16x32_bf16 v[6:9], v[178:181], v[218:221], 0
	v_mfma_f32_16x16x32_bf16 v[2:5], v[186:189], v[218:221], 0
	v_mfma_f32_16x16x32_bf16 v[54:57], v[182:185], v[198:201], v[54:57]
	v_mfma_f32_16x16x32_bf16 v[50:53], v[190:193], v[198:201], v[50:53]
	v_mfma_f32_16x16x32_bf16 v[38:41], v[182:185], v[206:209], v[38:41]
	v_mfma_f32_16x16x32_bf16 v[34:37], v[190:193], v[206:209], v[34:37]
	v_mfma_f32_16x16x32_bf16 v[22:25], v[182:185], v[214:217], v[22:25]
	v_mfma_f32_16x16x32_bf16 v[18:21], v[190:193], v[214:217], v[18:21]
	v_mfma_f32_16x16x32_bf16 v[6:9], v[182:185], v[222:225], v[6:9]
	v_mfma_f32_16x16x32_bf16 v[2:5], v[190:193], v[222:225], v[2:5]
	s_setprio 0
	s_barrier
	s_add_i32 s82, 0, 0x18000
	v_add_u32_e32 v152, s82, v155
	s_add_i32 s83, 0, 0x1c000
	ds_read_b128 v[162:165], v152
	ds_read_b128 v[166:169], v152 offset:1024
	ds_read_b128 v[170:173], v152 offset:2048
	ds_read_b128 v[174:177], v152 offset:3072
	v_add_u32_e32 v152, s83, v155
	ds_read_b128 v[178:181], v152
	ds_read_b128 v[182:185], v152 offset:1024
	ds_read_b128 v[186:189], v152 offset:2048
	ds_read_b128 v[190:193], v152 offset:3072
	s_add_u32 s60, s60, 0x40000
	s_addc_u32 s61, s61, 0
	s_mov_b32 m0, s65
	v_lshl_add_u64 v[232:233], s[60:61], 0, v[130:131]
	ds_read_b128 v[194:197], v158 offset:32768
	ds_read_b128 v[198:201], v158 offset:33792
	ds_read_b128 v[202:205], v158 offset:34816
	ds_read_b128 v[206:209], v158 offset:35840
	ds_read_b128 v[210:213], v158 offset:36864
	ds_read_b128 v[214:217], v158 offset:37888
	ds_read_b128 v[218:221], v158 offset:38912
	ds_read_b128 v[222:225], v158 offset:39936
	global_load_lds_dwordx4 v[232:233], off
	v_lshl_add_u64 v[232:233], s[60:61], 0, v[134:135]
	s_mov_b32 m0, s66
	s_nop 0
	global_load_lds_dwordx4 v[232:233], off
	s_waitcnt vmcnt(8)
	s_waitcnt lgkmcnt(0)
	s_setprio 1
	s_barrier
	v_mfma_f32_16x16x32_bf16 v[126:129], v[162:165], v[194:197], v[126:129]
	v_mfma_f32_16x16x32_bf16 v[122:125], v[170:173], v[194:197], v[122:125]
	v_mfma_f32_16x16x32_bf16 v[110:113], v[162:165], v[202:205], v[110:113]
	v_mfma_f32_16x16x32_bf16 v[106:109], v[170:173], v[202:205], v[106:109]
	v_mfma_f32_16x16x32_bf16 v[94:97], v[162:165], v[210:213], v[94:97]
	v_mfma_f32_16x16x32_bf16 v[90:93], v[170:173], v[210:213], v[90:93]
	v_mfma_f32_16x16x32_bf16 v[78:81], v[162:165], v[218:221], v[78:81]
	v_mfma_f32_16x16x32_bf16 v[74:77], v[170:173], v[218:221], v[74:77]
	v_mfma_f32_16x16x32_bf16 v[126:129], v[166:169], v[198:201], v[126:129]
	v_mfma_f32_16x16x32_bf16 v[122:125], v[174:177], v[198:201], v[122:125]
	v_mfma_f32_16x16x32_bf16 v[110:113], v[166:169], v[206:209], v[110:113]
	v_mfma_f32_16x16x32_bf16 v[106:109], v[174:177], v[206:209], v[106:109]
	v_mfma_f32_16x16x32_bf16 v[94:97], v[166:169], v[214:217], v[94:97]
	v_mfma_f32_16x16x32_bf16 v[90:93], v[174:177], v[214:217], v[90:93]
	v_mfma_f32_16x16x32_bf16 v[78:81], v[166:169], v[222:225], v[78:81]
	v_mfma_f32_16x16x32_bf16 v[74:77], v[174:177], v[222:225], v[74:77]
	s_setprio 0
	s_setprio 1
	v_mfma_f32_16x16x32_bf16 v[118:121], v[178:181], v[194:197], v[118:121]
	v_mfma_f32_16x16x32_bf16 v[114:117], v[186:189], v[194:197], v[114:117]
	v_mfma_f32_16x16x32_bf16 v[102:105], v[178:181], v[202:205], v[102:105]
	v_mfma_f32_16x16x32_bf16 v[98:101], v[186:189], v[202:205], v[98:101]
	v_mfma_f32_16x16x32_bf16 v[86:89], v[178:181], v[210:213], v[86:89]
	v_mfma_f32_16x16x32_bf16 v[82:85], v[186:189], v[210:213], v[82:85]
	v_mfma_f32_16x16x32_bf16 v[70:73], v[178:181], v[218:221], v[70:73]
	v_mfma_f32_16x16x32_bf16 v[66:69], v[186:189], v[218:221], v[66:69]
	v_mfma_f32_16x16x32_bf16 v[118:121], v[182:185], v[198:201], v[118:121]
	v_mfma_f32_16x16x32_bf16 v[114:117], v[190:193], v[198:201], v[114:117]
	v_mfma_f32_16x16x32_bf16 v[102:105], v[182:185], v[206:209], v[102:105]
	v_mfma_f32_16x16x32_bf16 v[98:101], v[190:193], v[206:209], v[98:101]
	v_mfma_f32_16x16x32_bf16 v[86:89], v[182:185], v[214:217], v[86:89]
	v_mfma_f32_16x16x32_bf16 v[82:85], v[190:193], v[214:217], v[82:85]
	v_mfma_f32_16x16x32_bf16 v[70:73], v[182:185], v[222:225], v[70:73]
	v_mfma_f32_16x16x32_bf16 v[66:69], v[190:193], v[222:225], v[66:69]
	s_setprio 0
	s_barrier
	s_add_i32 s60, s82, s62
	v_lshl_add_u64 v[150:151], v[150:151], 0, s[42:43]
	s_mov_b32 m0, s60
	ds_read_b128 v[194:197], v158 offset:49152
	ds_read_b128 v[198:201], v158 offset:50176
	ds_read_b128 v[202:205], v158 offset:51200
	ds_read_b128 v[206:209], v158 offset:52224
	ds_read_b128 v[210:213], v158 offset:53248
	ds_read_b128 v[214:217], v158 offset:54272
	ds_read_b128 v[218:221], v158 offset:55296
	ds_read_b128 v[222:225], v158 offset:56320
	global_load_lds_dwordx4 v[150:151], off
	s_add_i32 m0, s60, 0x2000
	s_add_u32 s58, s58, 0x40080
	v_lshl_add_u64 v[150:151], v[226:227], 0, s[42:43]
	s_addc_u32 s59, s59, 0
	s_add_i32 s60, s83, s62
	global_load_lds_dwordx4 v[150:151], off
	v_lshl_add_u64 v[150:151], s[58:59], 0, v[132:133]
	s_mov_b32 m0, s60
	s_nop 0
	global_load_lds_dwordx4 v[150:151], off
	v_lshl_add_u64 v[150:151], s[58:59], 0, v[136:137]
	s_add_i32 m0, s60, 0x2000
	s_nop 0
	global_load_lds_dwordx4 v[150:151], off
	v_lshl_add_u64 v[150:151], v[228:229], 0, s[42:43]
	s_mov_b32 m0, s68
	s_nop 0
	global_load_lds_dwordx4 v[150:151], off
	v_lshl_add_u64 v[150:151], v[230:231], 0, s[42:43]
	s_mov_b32 m0, s69
	s_nop 0
	global_load_lds_dwordx4 v[150:151], off
	s_waitcnt vmcnt(8)
	s_waitcnt lgkmcnt(0)
	s_setprio 1
	s_barrier
	v_mfma_f32_16x16x32_bf16 v[62:65], v[162:165], v[194:197], v[62:65]
	v_mfma_f32_16x16x32_bf16 v[58:61], v[170:173], v[194:197], v[58:61]
	v_mfma_f32_16x16x32_bf16 v[46:49], v[162:165], v[202:205], v[46:49]
	v_mfma_f32_16x16x32_bf16 v[42:45], v[170:173], v[202:205], v[42:45]
	v_mfma_f32_16x16x32_bf16 v[30:33], v[162:165], v[210:213], v[30:33]
	v_mfma_f32_16x16x32_bf16 v[26:29], v[170:173], v[210:213], v[26:29]
	v_mfma_f32_16x16x32_bf16 v[14:17], v[162:165], v[218:221], v[14:17]
	v_mfma_f32_16x16x32_bf16 v[10:13], v[170:173], v[218:221], v[10:13]
	v_mfma_f32_16x16x32_bf16 v[62:65], v[166:169], v[198:201], v[62:65]
	v_mfma_f32_16x16x32_bf16 v[58:61], v[174:177], v[198:201], v[58:61]
	v_mfma_f32_16x16x32_bf16 v[46:49], v[166:169], v[206:209], v[46:49]
	v_mfma_f32_16x16x32_bf16 v[42:45], v[174:177], v[206:209], v[42:45]
	v_mfma_f32_16x16x32_bf16 v[30:33], v[166:169], v[214:217], v[30:33]
	v_mfma_f32_16x16x32_bf16 v[26:29], v[174:177], v[214:217], v[26:29]
	v_mfma_f32_16x16x32_bf16 v[14:17], v[166:169], v[222:225], v[14:17]
	v_mfma_f32_16x16x32_bf16 v[10:13], v[174:177], v[222:225], v[10:13]
	s_setprio 0
	s_setprio 1
	v_mfma_f32_16x16x32_bf16 v[54:57], v[178:181], v[194:197], v[54:57]
	v_mfma_f32_16x16x32_bf16 v[50:53], v[186:189], v[194:197], v[50:53]
	v_mfma_f32_16x16x32_bf16 v[38:41], v[178:181], v[202:205], v[38:41]
	v_mfma_f32_16x16x32_bf16 v[34:37], v[186:189], v[202:205], v[34:37]
	v_mfma_f32_16x16x32_bf16 v[22:25], v[178:181], v[210:213], v[22:25]
	v_mfma_f32_16x16x32_bf16 v[18:21], v[186:189], v[210:213], v[18:21]
	v_mfma_f32_16x16x32_bf16 v[6:9], v[178:181], v[218:221], v[6:9]
	v_mfma_f32_16x16x32_bf16 v[2:5], v[186:189], v[218:221], v[2:5]
	v_mfma_f32_16x16x32_bf16 v[54:57], v[182:185], v[198:201], v[54:57]
	v_mfma_f32_16x16x32_bf16 v[50:53], v[190:193], v[198:201], v[50:53]
	v_mfma_f32_16x16x32_bf16 v[38:41], v[182:185], v[206:209], v[38:41]
	v_mfma_f32_16x16x32_bf16 v[34:37], v[190:193], v[206:209], v[34:37]
	v_mfma_f32_16x16x32_bf16 v[22:25], v[182:185], v[214:217], v[22:25]
	v_mfma_f32_16x16x32_bf16 v[18:21], v[190:193], v[214:217], v[18:21]
	v_mfma_f32_16x16x32_bf16 v[6:9], v[182:185], v[222:225], v[6:9]
	v_mfma_f32_16x16x32_bf16 v[2:5], v[190:193], v[222:225], v[2:5]
	s_setprio 0
	s_add_i32 s81, s81, 2
	s_add_u32 s56, s56, 0x100
	s_addc_u32 s57, s57, 0
	s_add_u32 s79, s79, 0x100
	s_addc_u32 s80, s80, 0
	s_cmp_gt_u32 s81, 13
	s_barrier
	s_cbranch_scc0 .LBB0_1050
	s_branch .Lz_post_p8a
.LBB0_1050:
	ds_read_b128 v[162:165], v156
	ds_read_b128 v[166:169], v156 offset:1024
	ds_read_b128 v[170:173], v156 offset:2048
	ds_read_b128 v[174:177], v156 offset:3072
	ds_read_b128 v[178:181], v157
	ds_read_b128 v[182:185], v157 offset:1024
	ds_read_b128 v[186:189], v157 offset:2048
	ds_read_b128 v[190:193], v157 offset:3072
	s_add_u32 s58, s56, 0xfffc0080
	s_addc_u32 s59, s57, -1
	s_cmp_eq_u32 s81, 12
	s_cselect_b32 s61, s9, s59
	s_cselect_b32 s60, s11, s58
	s_cselect_b32 s59, s49, s80
	s_cselect_b32 s58, s51, s79
	v_lshl_add_u64 v[150:151], s[56:57], 0, v[142:143]
	s_add_i32 m0, s63, 0xc000
	ds_read_b128 v[194:197], v158
	ds_read_b128 v[198:201], v158 offset:1024
	ds_read_b128 v[202:205], v158 offset:2048
	ds_read_b128 v[206:209], v158 offset:3072
	ds_read_b128 v[210:213], v158 offset:4096
	ds_read_b128 v[214:217], v158 offset:5120
	ds_read_b128 v[218:221], v158 offset:6144
	ds_read_b128 v[222:225], v158 offset:7168
	global_load_lds_dwordx4 v[150:151], off
	v_lshl_add_u64 v[150:151], s[56:57], 0, v[144:145]
	s_add_i32 m0, s63, 0xe000
	s_nop 0
	global_load_lds_dwordx4 v[150:151], off
	s_waitcnt vmcnt(8)
	s_waitcnt lgkmcnt(0)
	s_setprio 1
	s_barrier
	v_mfma_f32_16x16x32_bf16 v[126:129], v[162:165], v[194:197], v[126:129]
	v_mfma_f32_16x16x32_bf16 v[122:125], v[170:173], v[194:197], v[122:125]
	v_mfma_f32_16x16x32_bf16 v[110:113], v[162:165], v[202:205], v[110:113]
	v_mfma_f32_16x16x32_bf16 v[106:109], v[170:173], v[202:205], v[106:109]
	v_mfma_f32_16x16x32_bf16 v[94:97], v[162:165], v[210:213], v[94:97]
	v_mfma_f32_16x16x32_bf16 v[90:93], v[170:173], v[210:213], v[90:93]
	v_mfma_f32_16x16x32_bf16 v[78:81], v[162:165], v[218:221], v[78:81]
	v_mfma_f32_16x16x32_bf16 v[74:77], v[170:173], v[218:221], v[74:77]
	v_mfma_f32_16x16x32_bf16 v[126:129], v[166:169], v[198:201], v[126:129]
	v_mfma_f32_16x16x32_bf16 v[122:125], v[174:177], v[198:201], v[122:125]
	v_mfma_f32_16x16x32_bf16 v[110:113], v[166:169], v[206:209], v[110:113]
	v_mfma_f32_16x16x32_bf16 v[106:109], v[174:177], v[206:209], v[106:109]
	v_mfma_f32_16x16x32_bf16 v[94:97], v[166:169], v[214:217], v[94:97]
	v_mfma_f32_16x16x32_bf16 v[90:93], v[174:177], v[214:217], v[90:93]
	v_mfma_f32_16x16x32_bf16 v[78:81], v[166:169], v[222:225], v[78:81]
	v_mfma_f32_16x16x32_bf16 v[74:77], v[174:177], v[222:225], v[74:77]
	s_setprio 0
	s_setprio 1
	v_mfma_f32_16x16x32_bf16 v[118:121], v[178:181], v[194:197], v[118:121]
	v_mfma_f32_16x16x32_bf16 v[114:117], v[186:189], v[194:197], v[114:117]
	v_mfma_f32_16x16x32_bf16 v[102:105], v[178:181], v[202:205], v[102:105]
	v_mfma_f32_16x16x32_bf16 v[98:101], v[186:189], v[202:205], v[98:101]
	v_mfma_f32_16x16x32_bf16 v[86:89], v[178:181], v[210:213], v[86:89]
	v_mfma_f32_16x16x32_bf16 v[82:85], v[186:189], v[210:213], v[82:85]
	v_mfma_f32_16x16x32_bf16 v[70:73], v[178:181], v[218:221], v[70:73]
	v_mfma_f32_16x16x32_bf16 v[66:69], v[186:189], v[218:221], v[66:69]
	v_mfma_f32_16x16x32_bf16 v[118:121], v[182:185], v[198:201], v[118:121]
	v_mfma_f32_16x16x32_bf16 v[114:117], v[190:193], v[198:201], v[114:117]
	v_mfma_f32_16x16x32_bf16 v[102:105], v[182:185], v[206:209], v[102:105]
	v_mfma_f32_16x16x32_bf16 v[98:101], v[190:193], v[206:209], v[98:101]
	v_mfma_f32_16x16x32_bf16 v[86:89], v[182:185], v[214:217], v[86:89]
	v_mfma_f32_16x16x32_bf16 v[82:85], v[190:193], v[214:217], v[82:85]
	v_mfma_f32_16x16x32_bf16 v[70:73], v[182:185], v[222:225], v[70:73]
	v_mfma_f32_16x16x32_bf16 v[66:69], v[190:193], v[222:225], v[66:69]
	s_setprio 0
	s_barrier
	s_add_i32 s82, s73, s62
	v_lshl_add_u64 v[150:151], s[58:59], 0, v[132:133]
	s_mov_b32 m0, s82
	ds_read_b128 v[194:197], v158 offset:16384
	ds_read_b128 v[198:201], v158 offset:17408
	ds_read_b128 v[202:205], v158 offset:18432
	ds_read_b128 v[206:209], v158 offset:19456
	ds_read_b128 v[210:213], v158 offset:20480
	ds_read_b128 v[214:217], v158 offset:21504
	ds_read_b128 v[218:221], v158 offset:22528
	ds_read_b128 v[222:225], v158 offset:23552
	global_load_lds_dwordx4 v[150:151], off
	s_add_i32 m0, s82, 0x2000
	s_add_u32 s82, s58, 0x40000
	v_lshl_add_u64 v[226:227], s[58:59], 0, v[136:137]
	s_addc_u32 s83, s59, 0
	s_add_i32 s84, s74, s62
	global_load_lds_dwordx4 v[226:227], off
	v_lshl_add_u64 v[228:229], s[82:83], 0, v[132:133]
	s_mov_b32 m0, s84
	v_lshl_add_u64 v[230:231], s[60:61], 0, v[134:135]
	global_load_lds_dwordx4 v[228:229], off
	v_lshl_add_u64 v[228:229], s[82:83], 0, v[136:137]
	s_add_i32 m0, s84, 0x2000
	s_nop 0
	global_load_lds_dwordx4 v[228:229], off
	v_lshl_add_u64 v[228:229], s[60:61], 0, v[130:131]
	s_mov_b32 m0, s63
	s_nop 0
	global_load_lds_dwordx4 v[228:229], off
	s_mov_b32 m0, s64
	s_nop 0
	global_load_lds_dwordx4 v[230:231], off
	s_waitcnt vmcnt(8)
	s_waitcnt lgkmcnt(0)
	s_setprio 1
	s_barrier
	v_mfma_f32_16x16x32_bf16 v[62:65], v[162:165], v[194:197], v[62:65]
	v_mfma_f32_16x16x32_bf16 v[58:61], v[170:173], v[194:197], v[58:61]
	v_mfma_f32_16x16x32_bf16 v[46:49], v[162:165], v[202:205], v[46:49]
	v_mfma_f32_16x16x32_bf16 v[42:45], v[170:173], v[202:205], v[42:45]
	v_mfma_f32_16x16x32_bf16 v[30:33], v[162:165], v[210:213], v[30:33]
	v_mfma_f32_16x16x32_bf16 v[26:29], v[170:173], v[210:213], v[26:29]
	v_mfma_f32_16x16x32_bf16 v[14:17], v[162:165], v[218:221], v[14:17]
	v_mfma_f32_16x16x32_bf16 v[10:13], v[170:173], v[218:221], v[10:13]
	v_mfma_f32_16x16x32_bf16 v[62:65], v[166:169], v[198:201], v[62:65]
	v_mfma_f32_16x16x32_bf16 v[58:61], v[174:177], v[198:201], v[58:61]
	v_mfma_f32_16x16x32_bf16 v[46:49], v[166:169], v[206:209], v[46:49]
	v_mfma_f32_16x16x32_bf16 v[42:45], v[174:177], v[206:209], v[42:45]
	v_mfma_f32_16x16x32_bf16 v[30:33], v[166:169], v[214:217], v[30:33]
	v_mfma_f32_16x16x32_bf16 v[26:29], v[174:177], v[214:217], v[26:29]
	v_mfma_f32_16x16x32_bf16 v[14:17], v[166:169], v[222:225], v[14:17]
	v_mfma_f32_16x16x32_bf16 v[10:13], v[174:177], v[222:225], v[10:13]
	s_setprio 0
	s_setprio 1
	v_mfma_f32_16x16x32_bf16 v[54:57], v[178:181], v[194:197], v[54:57]
	v_mfma_f32_16x16x32_bf16 v[50:53], v[186:189], v[194:197], v[50:53]
	v_mfma_f32_16x16x32_bf16 v[38:41], v[178:181], v[202:205], v[38:41]
	v_mfma_f32_16x16x32_bf16 v[34:37], v[186:189], v[202:205], v[34:37]
	v_mfma_f32_16x16x32_bf16 v[22:25], v[178:181], v[210:213], v[22:25]
	v_mfma_f32_16x16x32_bf16 v[18:21], v[186:189], v[210:213], v[18:21]
	v_mfma_f32_16x16x32_bf16 v[6:9], v[178:181], v[218:221], v[6:9]
	v_mfma_f32_16x16x32_bf16 v[2:5], v[186:189], v[218:221], v[2:5]
	v_mfma_f32_16x16x32_bf16 v[54:57], v[182:185], v[198:201], v[54:57]
	v_mfma_f32_16x16x32_bf16 v[50:53], v[190:193], v[198:201], v[50:53]
	v_mfma_f32_16x16x32_bf16 v[38:41], v[182:185], v[206:209], v[38:41]
	v_mfma_f32_16x16x32_bf16 v[34:37], v[190:193], v[206:209], v[34:37]
	v_mfma_f32_16x16x32_bf16 v[22:25], v[182:185], v[214:217], v[22:25]
	v_mfma_f32_16x16x32_bf16 v[18:21], v[190:193], v[214:217], v[18:21]
	v_mfma_f32_16x16x32_bf16 v[6:9], v[182:185], v[222:225], v[6:9]
	v_mfma_f32_16x16x32_bf16 v[2:5], v[190:193], v[222:225], v[2:5]
	s_setprio 0
	s_barrier
	s_add_i32 s82, 0, 0x18000
	v_add_u32_e32 v152, s82, v155
	s_add_i32 s83, 0, 0x1c000
	ds_read_b128 v[162:165], v152
	ds_read_b128 v[166:169], v152 offset:1024
	ds_read_b128 v[170:173], v152 offset:2048
	ds_read_b128 v[174:177], v152 offset:3072
	v_add_u32_e32 v152, s83, v155
	ds_read_b128 v[178:181], v152
	ds_read_b128 v[182:185], v152 offset:1024
	ds_read_b128 v[186:189], v152 offset:2048
	ds_read_b128 v[190:193], v152 offset:3072
	s_add_u32 s60, s60, 0x40000
	s_addc_u32 s61, s61, 0
	s_mov_b32 m0, s65
	v_lshl_add_u64 v[232:233], s[60:61], 0, v[130:131]
	ds_read_b128 v[194:197], v158 offset:32768
	ds_read_b128 v[198:201], v158 offset:33792
	ds_read_b128 v[202:205], v158 offset:34816
	ds_read_b128 v[206:209], v158 offset:35840
	ds_read_b128 v[210:213], v158 offset:36864
	ds_read_b128 v[214:217], v158 offset:37888
	ds_read_b128 v[218:221], v158 offset:38912
	ds_read_b128 v[222:225], v158 offset:39936
	global_load_lds_dwordx4 v[232:233], off
	v_lshl_add_u64 v[232:233], s[60:61], 0, v[134:135]
	s_mov_b32 m0, s66
	s_nop 0
	global_load_lds_dwordx4 v[232:233], off
	s_waitcnt vmcnt(8)
	s_waitcnt lgkmcnt(0)
	s_setprio 1
	s_barrier
	v_mfma_f32_16x16x32_bf16 v[126:129], v[162:165], v[194:197], v[126:129]
	v_mfma_f32_16x16x32_bf16 v[122:125], v[170:173], v[194:197], v[122:125]
	v_mfma_f32_16x16x32_bf16 v[110:113], v[162:165], v[202:205], v[110:113]
	v_mfma_f32_16x16x32_bf16 v[106:109], v[170:173], v[202:205], v[106:109]
	v_mfma_f32_16x16x32_bf16 v[94:97], v[162:165], v[210:213], v[94:97]
	v_mfma_f32_16x16x32_bf16 v[90:93], v[170:173], v[210:213], v[90:93]
	v_mfma_f32_16x16x32_bf16 v[78:81], v[162:165], v[218:221], v[78:81]
	v_mfma_f32_16x16x32_bf16 v[74:77], v[170:173], v[218:221], v[74:77]
	v_mfma_f32_16x16x32_bf16 v[126:129], v[166:169], v[198:201], v[126:129]
	v_mfma_f32_16x16x32_bf16 v[122:125], v[174:177], v[198:201], v[122:125]
	v_mfma_f32_16x16x32_bf16 v[110:113], v[166:169], v[206:209], v[110:113]
	v_mfma_f32_16x16x32_bf16 v[106:109], v[174:177], v[206:209], v[106:109]
	v_mfma_f32_16x16x32_bf16 v[94:97], v[166:169], v[214:217], v[94:97]
	v_mfma_f32_16x16x32_bf16 v[90:93], v[174:177], v[214:217], v[90:93]
	v_mfma_f32_16x16x32_bf16 v[78:81], v[166:169], v[222:225], v[78:81]
	v_mfma_f32_16x16x32_bf16 v[74:77], v[174:177], v[222:225], v[74:77]
	s_setprio 0
	s_setprio 1
	v_mfma_f32_16x16x32_bf16 v[118:121], v[178:181], v[194:197], v[118:121]
	v_mfma_f32_16x16x32_bf16 v[114:117], v[186:189], v[194:197], v[114:117]
	v_mfma_f32_16x16x32_bf16 v[102:105], v[178:181], v[202:205], v[102:105]
	v_mfma_f32_16x16x32_bf16 v[98:101], v[186:189], v[202:205], v[98:101]
	v_mfma_f32_16x16x32_bf16 v[86:89], v[178:181], v[210:213], v[86:89]
	v_mfma_f32_16x16x32_bf16 v[82:85], v[186:189], v[210:213], v[82:85]
	v_mfma_f32_16x16x32_bf16 v[70:73], v[178:181], v[218:221], v[70:73]
	v_mfma_f32_16x16x32_bf16 v[66:69], v[186:189], v[218:221], v[66:69]
	v_mfma_f32_16x16x32_bf16 v[118:121], v[182:185], v[198:201], v[118:121]
	v_mfma_f32_16x16x32_bf16 v[114:117], v[190:193], v[198:201], v[114:117]
	v_mfma_f32_16x16x32_bf16 v[102:105], v[182:185], v[206:209], v[102:105]
	v_mfma_f32_16x16x32_bf16 v[98:101], v[190:193], v[206:209], v[98:101]
	v_mfma_f32_16x16x32_bf16 v[86:89], v[182:185], v[214:217], v[86:89]
	v_mfma_f32_16x16x32_bf16 v[82:85], v[190:193], v[214:217], v[82:85]
	v_mfma_f32_16x16x32_bf16 v[70:73], v[182:185], v[222:225], v[70:73]
	v_mfma_f32_16x16x32_bf16 v[66:69], v[190:193], v[222:225], v[66:69]
	s_setprio 0
	s_barrier
	s_add_i32 s60, s82, s62
	v_lshl_add_u64 v[150:151], v[150:151], 0, s[42:43]
	s_mov_b32 m0, s60
	ds_read_b128 v[194:197], v158 offset:49152
	ds_read_b128 v[198:201], v158 offset:50176
	ds_read_b128 v[202:205], v158 offset:51200
	ds_read_b128 v[206:209], v158 offset:52224
	ds_read_b128 v[210:213], v158 offset:53248
	ds_read_b128 v[214:217], v158 offset:54272
	ds_read_b128 v[218:221], v158 offset:55296
	ds_read_b128 v[222:225], v158 offset:56320
	global_load_lds_dwordx4 v[150:151], off
	s_add_i32 m0, s60, 0x2000
	s_add_u32 s58, s58, 0x40080
	v_lshl_add_u64 v[150:151], v[226:227], 0, s[42:43]
	s_addc_u32 s59, s59, 0
	s_add_i32 s60, s83, s62
	global_load_lds_dwordx4 v[150:151], off
	v_lshl_add_u64 v[150:151], s[58:59], 0, v[132:133]
	s_mov_b32 m0, s60
	s_nop 0
	global_load_lds_dwordx4 v[150:151], off
	v_lshl_add_u64 v[150:151], s[58:59], 0, v[136:137]
	s_add_i32 m0, s60, 0x2000
	s_nop 0
	global_load_lds_dwordx4 v[150:151], off
	v_lshl_add_u64 v[150:151], v[228:229], 0, s[42:43]
	s_mov_b32 m0, s68
	s_nop 0
	global_load_lds_dwordx4 v[150:151], off
	v_lshl_add_u64 v[150:151], v[230:231], 0, s[42:43]
	s_mov_b32 m0, s69
	s_nop 0
	global_load_lds_dwordx4 v[150:151], off
	s_waitcnt vmcnt(8)
	s_waitcnt lgkmcnt(0)
	s_setprio 1
	s_barrier
	v_mfma_f32_16x16x32_bf16 v[62:65], v[162:165], v[194:197], v[62:65]
	v_mfma_f32_16x16x32_bf16 v[58:61], v[170:173], v[194:197], v[58:61]
	v_mfma_f32_16x16x32_bf16 v[46:49], v[162:165], v[202:205], v[46:49]
	v_mfma_f32_16x16x32_bf16 v[42:45], v[170:173], v[202:205], v[42:45]
	v_mfma_f32_16x16x32_bf16 v[30:33], v[162:165], v[210:213], v[30:33]
	v_mfma_f32_16x16x32_bf16 v[26:29], v[170:173], v[210:213], v[26:29]
	v_mfma_f32_16x16x32_bf16 v[14:17], v[162:165], v[218:221], v[14:17]
	v_mfma_f32_16x16x32_bf16 v[10:13], v[170:173], v[218:221], v[10:13]
	v_mfma_f32_16x16x32_bf16 v[62:65], v[166:169], v[198:201], v[62:65]
	v_mfma_f32_16x16x32_bf16 v[58:61], v[174:177], v[198:201], v[58:61]
	v_mfma_f32_16x16x32_bf16 v[46:49], v[166:169], v[206:209], v[46:49]
	v_mfma_f32_16x16x32_bf16 v[42:45], v[174:177], v[206:209], v[42:45]
	v_mfma_f32_16x16x32_bf16 v[30:33], v[166:169], v[214:217], v[30:33]
	v_mfma_f32_16x16x32_bf16 v[26:29], v[174:177], v[214:217], v[26:29]
	v_mfma_f32_16x16x32_bf16 v[14:17], v[166:169], v[222:225], v[14:17]
	v_mfma_f32_16x16x32_bf16 v[10:13], v[174:177], v[222:225], v[10:13]
	s_setprio 0
	s_setprio 1
	v_mfma_f32_16x16x32_bf16 v[54:57], v[178:181], v[194:197], v[54:57]
	v_mfma_f32_16x16x32_bf16 v[50:53], v[186:189], v[194:197], v[50:53]
	v_mfma_f32_16x16x32_bf16 v[38:41], v[178:181], v[202:205], v[38:41]
	v_mfma_f32_16x16x32_bf16 v[34:37], v[186:189], v[202:205], v[34:37]
	v_mfma_f32_16x16x32_bf16 v[22:25], v[178:181], v[210:213], v[22:25]
	v_mfma_f32_16x16x32_bf16 v[18:21], v[186:189], v[210:213], v[18:21]
	v_mfma_f32_16x16x32_bf16 v[6:9], v[178:181], v[218:221], v[6:9]
	v_mfma_f32_16x16x32_bf16 v[2:5], v[186:189], v[218:221], v[2:5]
	v_mfma_f32_16x16x32_bf16 v[54:57], v[182:185], v[198:201], v[54:57]
	v_mfma_f32_16x16x32_bf16 v[50:53], v[190:193], v[198:201], v[50:53]
	v_mfma_f32_16x16x32_bf16 v[38:41], v[182:185], v[206:209], v[38:41]
	v_mfma_f32_16x16x32_bf16 v[34:37], v[190:193], v[206:209], v[34:37]
	v_mfma_f32_16x16x32_bf16 v[22:25], v[182:185], v[214:217], v[22:25]
	v_mfma_f32_16x16x32_bf16 v[18:21], v[190:193], v[214:217], v[18:21]
	v_mfma_f32_16x16x32_bf16 v[6:9], v[182:185], v[222:225], v[6:9]
	v_mfma_f32_16x16x32_bf16 v[2:5], v[190:193], v[222:225], v[2:5]
	s_setprio 0
	s_add_i32 s81, s81, 2
	s_add_u32 s56, s56, 0x100
	s_addc_u32 s57, s57, 0
	s_add_u32 s79, s79, 0x100
	s_addc_u32 s80, s80, 0
	s_cmp_gt_u32 s81, 13
	s_barrier
	s_cbranch_scc0 .LBB0_1050

.LBB0_1356:
	s_ashr_i32 s45, s44, 31
	s_lshl_b64 s[46:47], s[44:45], 19
	s_add_u32 s46, s3, s46
	s_addc_u32 s47, s23, s47
	s_and_b64 s[48:49], s[6:7], exec
	s_cselect_b32 s45, s47, s55
	s_cselect_b32 s51, s46, s54
	s_ashr_i32 s43, s42, 31
	s_lshl_b64 s[48:49], s[42:43], 19
	s_add_u32 s48, s29, s48
	s_addc_u32 s49, s31, s49
	s_and_b64 s[58:59], s[6:7], exec
	s_cselect_b32 s43, s49, s57
	s_cselect_b32 s53, s48, s56
	s_add_u32 s54, s54, 0x40080
	s_addc_u32 s55, s55, 0
	s_add_u32 s74, s56, 0x100
	s_addc_u32 s75, s57, 0
	s_mov_b32 s76, -2
	s_waitcnt lgkmcnt(0)
	s_waitcnt vmcnt(0)
	ds_read_b128 v[158:161], v152
	ds_read_b128 v[162:165], v152 offset:1024
	ds_read_b128 v[166:169], v152 offset:2048
	ds_read_b128 v[170:173], v152 offset:3072
	ds_read_b128 v[174:177], v153
	ds_read_b128 v[178:181], v153 offset:1024
	ds_read_b128 v[182:185], v153 offset:2048
	ds_read_b128 v[186:189], v153 offset:3072
	s_add_u32 s56, s54, 0xfffc0080
	s_addc_u32 s57, s55, -1
	s_cmp_eq_u32 s76, 12
	s_cselect_b32 s59, s45, s57
	s_cselect_b32 s58, s51, s56
	s_cselect_b32 s57, s43, s75
	s_cselect_b32 s56, s53, s74
	v_lshl_add_u64 v[148:149], s[54:55], 0, v[140:141]
	s_add_i32 m0, s61, 0xc000
	ds_read_b128 v[190:193], v154
	ds_read_b128 v[194:197], v154 offset:1024
	ds_read_b128 v[198:201], v154 offset:2048
	ds_read_b128 v[202:205], v154 offset:3072
	ds_read_b128 v[206:209], v154 offset:4096
	ds_read_b128 v[210:213], v154 offset:5120
	ds_read_b128 v[214:217], v154 offset:6144
	ds_read_b128 v[218:221], v154 offset:7168
	global_load_lds_dwordx4 v[148:149], off
	v_lshl_add_u64 v[148:149], s[54:55], 0, v[142:143]
	s_add_i32 m0, s61, 0xe000
	s_nop 0
	global_load_lds_dwordx4 v[148:149], off
	s_waitcnt vmcnt(8)
	s_waitcnt lgkmcnt(0)
	s_setprio 1
	s_barrier
	v_mfma_f32_16x16x32_bf16 v[126:129], v[158:161], v[190:193], 0
	v_mfma_f32_16x16x32_bf16 v[122:125], v[166:169], v[190:193], 0
	v_mfma_f32_16x16x32_bf16 v[110:113], v[158:161], v[198:201], 0
	v_mfma_f32_16x16x32_bf16 v[106:109], v[166:169], v[198:201], 0
	v_mfma_f32_16x16x32_bf16 v[94:97], v[158:161], v[206:209], 0
	v_mfma_f32_16x16x32_bf16 v[90:93], v[166:169], v[206:209], 0
	v_mfma_f32_16x16x32_bf16 v[78:81], v[158:161], v[214:217], 0
	v_mfma_f32_16x16x32_bf16 v[74:77], v[166:169], v[214:217], 0
	v_mfma_f32_16x16x32_bf16 v[126:129], v[162:165], v[194:197], v[126:129]
	v_mfma_f32_16x16x32_bf16 v[122:125], v[170:173], v[194:197], v[122:125]
	v_mfma_f32_16x16x32_bf16 v[110:113], v[162:165], v[202:205], v[110:113]
	v_mfma_f32_16x16x32_bf16 v[106:109], v[170:173], v[202:205], v[106:109]
	v_mfma_f32_16x16x32_bf16 v[94:97], v[162:165], v[210:213], v[94:97]
	v_mfma_f32_16x16x32_bf16 v[90:93], v[170:173], v[210:213], v[90:93]
	v_mfma_f32_16x16x32_bf16 v[78:81], v[162:165], v[218:221], v[78:81]
	v_mfma_f32_16x16x32_bf16 v[74:77], v[170:173], v[218:221], v[74:77]
	s_setprio 0
	s_setprio 1
	v_mfma_f32_16x16x32_bf16 v[118:121], v[174:177], v[190:193], 0
	v_mfma_f32_16x16x32_bf16 v[114:117], v[182:185], v[190:193], 0
	v_mfma_f32_16x16x32_bf16 v[102:105], v[174:177], v[198:201], 0
	v_mfma_f32_16x16x32_bf16 v[98:101], v[182:185], v[198:201], 0
	v_mfma_f32_16x16x32_bf16 v[86:89], v[174:177], v[206:209], 0
	v_mfma_f32_16x16x32_bf16 v[82:85], v[182:185], v[206:209], 0
	v_mfma_f32_16x16x32_bf16 v[70:73], v[174:177], v[214:217], 0
	v_mfma_f32_16x16x32_bf16 v[66:69], v[182:185], v[214:217], 0
	v_mfma_f32_16x16x32_bf16 v[118:121], v[178:181], v[194:197], v[118:121]
	v_mfma_f32_16x16x32_bf16 v[114:117], v[186:189], v[194:197], v[114:117]
	v_mfma_f32_16x16x32_bf16 v[102:105], v[178:181], v[202:205], v[102:105]
	v_mfma_f32_16x16x32_bf16 v[98:101], v[186:189], v[202:205], v[98:101]
	v_mfma_f32_16x16x32_bf16 v[86:89], v[178:181], v[210:213], v[86:89]
	v_mfma_f32_16x16x32_bf16 v[82:85], v[186:189], v[210:213], v[82:85]
	v_mfma_f32_16x16x32_bf16 v[70:73], v[178:181], v[218:221], v[70:73]
	v_mfma_f32_16x16x32_bf16 v[66:69], v[186:189], v[218:221], v[66:69]
	s_setprio 0
	s_barrier
	s_add_i32 s77, s71, s60
	v_lshl_add_u64 v[148:149], s[56:57], 0, v[132:133]
	s_mov_b32 m0, s77
	ds_read_b128 v[190:193], v154 offset:16384
	ds_read_b128 v[194:197], v154 offset:17408
	ds_read_b128 v[198:201], v154 offset:18432
	ds_read_b128 v[202:205], v154 offset:19456
	ds_read_b128 v[206:209], v154 offset:20480
	ds_read_b128 v[210:213], v154 offset:21504
	ds_read_b128 v[214:217], v154 offset:22528
	ds_read_b128 v[218:221], v154 offset:23552
	global_load_lds_dwordx4 v[148:149], off
	s_add_i32 m0, s77, 0x2000
	s_add_u32 s78, s56, 0x40000
	v_lshl_add_u64 v[222:223], s[56:57], 0, v[136:137]
	s_addc_u32 s79, s57, 0
	s_add_i32 s77, s72, s60
	global_load_lds_dwordx4 v[222:223], off
	v_lshl_add_u64 v[224:225], s[78:79], 0, v[132:133]
	s_mov_b32 m0, s77
	v_lshl_add_u64 v[226:227], s[58:59], 0, v[134:135]
	global_load_lds_dwordx4 v[224:225], off
	v_lshl_add_u64 v[224:225], s[78:79], 0, v[136:137]
	s_add_i32 m0, s77, 0x2000
	s_nop 0
	global_load_lds_dwordx4 v[224:225], off
	v_lshl_add_u64 v[224:225], s[58:59], 0, v[130:131]
	s_mov_b32 m0, s61
	s_nop 0
	global_load_lds_dwordx4 v[224:225], off
	s_mov_b32 m0, s62
	s_nop 0
	global_load_lds_dwordx4 v[226:227], off
	s_waitcnt vmcnt(8)
	s_waitcnt lgkmcnt(0)
	s_setprio 1
	s_barrier
	v_mfma_f32_16x16x32_bf16 v[62:65], v[158:161], v[190:193], 0
	v_mfma_f32_16x16x32_bf16 v[58:61], v[166:169], v[190:193], 0
	v_mfma_f32_16x16x32_bf16 v[46:49], v[158:161], v[198:201], 0
	v_mfma_f32_16x16x32_bf16 v[42:45], v[166:169], v[198:201], 0
	v_mfma_f32_16x16x32_bf16 v[30:33], v[158:161], v[206:209], 0
	v_mfma_f32_16x16x32_bf16 v[26:29], v[166:169], v[206:209], 0
	v_mfma_f32_16x16x32_bf16 v[14:17], v[158:161], v[214:217], 0
	v_mfma_f32_16x16x32_bf16 v[10:13], v[166:169], v[214:217], 0
	v_mfma_f32_16x16x32_bf16 v[62:65], v[162:165], v[194:197], v[62:65]
	v_mfma_f32_16x16x32_bf16 v[58:61], v[170:173], v[194:197], v[58:61]
	v_mfma_f32_16x16x32_bf16 v[46:49], v[162:165], v[202:205], v[46:49]
	v_mfma_f32_16x16x32_bf16 v[42:45], v[170:173], v[202:205], v[42:45]
	v_mfma_f32_16x16x32_bf16 v[30:33], v[162:165], v[210:213], v[30:33]
	v_mfma_f32_16x16x32_bf16 v[26:29], v[170:173], v[210:213], v[26:29]
	v_mfma_f32_16x16x32_bf16 v[14:17], v[162:165], v[218:221], v[14:17]
	v_mfma_f32_16x16x32_bf16 v[10:13], v[170:173], v[218:221], v[10:13]
	s_setprio 0
	s_setprio 1
	v_mfma_f32_16x16x32_bf16 v[54:57], v[174:177], v[190:193], 0
	v_mfma_f32_16x16x32_bf16 v[50:53], v[182:185], v[190:193], 0
	v_mfma_f32_16x16x32_bf16 v[38:41], v[174:177], v[198:201], 0
	v_mfma_f32_16x16x32_bf16 v[34:37], v[182:185], v[198:201], 0
	v_mfma_f32_16x16x32_bf16 v[22:25], v[174:177], v[206:209], 0
	v_mfma_f32_16x16x32_bf16 v[18:21], v[182:185], v[206:209], 0
	v_mfma_f32_16x16x32_bf16 v[6:9], v[174:177], v[214:217], 0
	v_mfma_f32_16x16x32_bf16 v[2:5], v[182:185], v[214:217], 0
	v_mfma_f32_16x16x32_bf16 v[54:57], v[178:181], v[194:197], v[54:57]
	v_mfma_f32_16x16x32_bf16 v[50:53], v[186:189], v[194:197], v[50:53]
	v_mfma_f32_16x16x32_bf16 v[38:41], v[178:181], v[202:205], v[38:41]
	v_mfma_f32_16x16x32_bf16 v[34:37], v[186:189], v[202:205], v[34:37]
	v_mfma_f32_16x16x32_bf16 v[22:25], v[178:181], v[210:213], v[22:25]
	v_mfma_f32_16x16x32_bf16 v[18:21], v[186:189], v[210:213], v[18:21]
	v_mfma_f32_16x16x32_bf16 v[6:9], v[178:181], v[218:221], v[6:9]
	v_mfma_f32_16x16x32_bf16 v[2:5], v[186:189], v[218:221], v[2:5]
	s_setprio 0
	s_barrier
	s_add_i32 s77, 0, 0x18000
	v_add_u32_e32 v157, s77, v151
	s_add_i32 s78, 0, 0x1c000
	ds_read_b128 v[158:161], v157
	ds_read_b128 v[162:165], v157 offset:1024
	ds_read_b128 v[166:169], v157 offset:2048
	ds_read_b128 v[170:173], v157 offset:3072
	v_add_u32_e32 v157, s78, v151
	ds_read_b128 v[174:177], v157
	ds_read_b128 v[178:181], v157 offset:1024
	ds_read_b128 v[182:185], v157 offset:2048
	ds_read_b128 v[186:189], v157 offset:3072
	s_add_u32 s58, s58, 0x40000
	s_addc_u32 s59, s59, 0
	s_mov_b32 m0, s63
	v_lshl_add_u64 v[228:229], s[58:59], 0, v[130:131]
	ds_read_b128 v[190:193], v154 offset:32768
	ds_read_b128 v[194:197], v154 offset:33792
	ds_read_b128 v[198:201], v154 offset:34816
	ds_read_b128 v[202:205], v154 offset:35840
	ds_read_b128 v[206:209], v154 offset:36864
	ds_read_b128 v[210:213], v154 offset:37888
	ds_read_b128 v[214:217], v154 offset:38912
	ds_read_b128 v[218:221], v154 offset:39936
	global_load_lds_dwordx4 v[228:229], off
	v_lshl_add_u64 v[228:229], s[58:59], 0, v[134:135]
	s_mov_b32 m0, s64
	s_nop 0
	global_load_lds_dwordx4 v[228:229], off
	s_waitcnt vmcnt(8)
	s_waitcnt lgkmcnt(0)
	s_setprio 1
	s_barrier
	v_mfma_f32_16x16x32_bf16 v[126:129], v[158:161], v[190:193], v[126:129]
	v_mfma_f32_16x16x32_bf16 v[122:125], v[166:169], v[190:193], v[122:125]
	v_mfma_f32_16x16x32_bf16 v[110:113], v[158:161], v[198:201], v[110:113]
	v_mfma_f32_16x16x32_bf16 v[106:109], v[166:169], v[198:201], v[106:109]
	v_mfma_f32_16x16x32_bf16 v[94:97], v[158:161], v[206:209], v[94:97]
	v_mfma_f32_16x16x32_bf16 v[90:93], v[166:169], v[206:209], v[90:93]
	v_mfma_f32_16x16x32_bf16 v[78:81], v[158:161], v[214:217], v[78:81]
	v_mfma_f32_16x16x32_bf16 v[74:77], v[166:169], v[214:217], v[74:77]
	v_mfma_f32_16x16x32_bf16 v[126:129], v[162:165], v[194:197], v[126:129]
	v_mfma_f32_16x16x32_bf16 v[122:125], v[170:173], v[194:197], v[122:125]
	v_mfma_f32_16x16x32_bf16 v[110:113], v[162:165], v[202:205], v[110:113]
	v_mfma_f32_16x16x32_bf16 v[106:109], v[170:173], v[202:205], v[106:109]
	v_mfma_f32_16x16x32_bf16 v[94:97], v[162:165], v[210:213], v[94:97]
	v_mfma_f32_16x16x32_bf16 v[90:93], v[170:173], v[210:213], v[90:93]
	v_mfma_f32_16x16x32_bf16 v[78:81], v[162:165], v[218:221], v[78:81]
	v_mfma_f32_16x16x32_bf16 v[74:77], v[170:173], v[218:221], v[74:77]
	s_setprio 0
	s_setprio 1
	v_mfma_f32_16x16x32_bf16 v[118:121], v[174:177], v[190:193], v[118:121]
	v_mfma_f32_16x16x32_bf16 v[114:117], v[182:185], v[190:193], v[114:117]
	v_mfma_f32_16x16x32_bf16 v[102:105], v[174:177], v[198:201], v[102:105]
	v_mfma_f32_16x16x32_bf16 v[98:101], v[182:185], v[198:201], v[98:101]
	v_mfma_f32_16x16x32_bf16 v[86:89], v[174:177], v[206:209], v[86:89]
	v_mfma_f32_16x16x32_bf16 v[82:85], v[182:185], v[206:209], v[82:85]
	v_mfma_f32_16x16x32_bf16 v[70:73], v[174:177], v[214:217], v[70:73]
	v_mfma_f32_16x16x32_bf16 v[66:69], v[182:185], v[214:217], v[66:69]
	v_mfma_f32_16x16x32_bf16 v[118:121], v[178:181], v[194:197], v[118:121]
	v_mfma_f32_16x16x32_bf16 v[114:117], v[186:189], v[194:197], v[114:117]
	v_mfma_f32_16x16x32_bf16 v[102:105], v[178:181], v[202:205], v[102:105]
	v_mfma_f32_16x16x32_bf16 v[98:101], v[186:189], v[202:205], v[98:101]
	v_mfma_f32_16x16x32_bf16 v[86:89], v[178:181], v[210:213], v[86:89]
	v_mfma_f32_16x16x32_bf16 v[82:85], v[186:189], v[210:213], v[82:85]
	v_mfma_f32_16x16x32_bf16 v[70:73], v[178:181], v[218:221], v[70:73]
	v_mfma_f32_16x16x32_bf16 v[66:69], v[186:189], v[218:221], v[66:69]
	s_setprio 0
	s_barrier
	s_add_i32 s58, s77, s60
	v_lshl_add_u64 v[148:149], v[148:149], 0, s[24:25]
	s_mov_b32 m0, s58
	ds_read_b128 v[190:193], v154 offset:49152
	ds_read_b128 v[194:197], v154 offset:50176
	ds_read_b128 v[198:201], v154 offset:51200
	ds_read_b128 v[202:205], v154 offset:52224
	ds_read_b128 v[206:209], v154 offset:53248
	ds_read_b128 v[210:213], v154 offset:54272
	ds_read_b128 v[214:217], v154 offset:55296
	ds_read_b128 v[218:221], v154 offset:56320
	global_load_lds_dwordx4 v[148:149], off
	s_add_i32 m0, s58, 0x2000
	s_add_u32 s56, s56, 0x40080
	v_lshl_add_u64 v[148:149], v[222:223], 0, s[24:25]
	s_addc_u32 s57, s57, 0
	s_add_i32 s58, s78, s60
	global_load_lds_dwordx4 v[148:149], off
	v_lshl_add_u64 v[148:149], s[56:57], 0, v[132:133]
	s_mov_b32 m0, s58
	s_nop 0
	global_load_lds_dwordx4 v[148:149], off
	v_lshl_add_u64 v[148:149], s[56:57], 0, v[136:137]
	s_add_i32 m0, s58, 0x2000
	s_nop 0
	global_load_lds_dwordx4 v[148:149], off
	v_lshl_add_u64 v[148:149], v[224:225], 0, s[24:25]
	s_mov_b32 m0, s66
	s_nop 0
	global_load_lds_dwordx4 v[148:149], off
	v_lshl_add_u64 v[148:149], v[226:227], 0, s[24:25]
	s_mov_b32 m0, s67
	s_nop 0
	global_load_lds_dwordx4 v[148:149], off
	s_waitcnt vmcnt(8)
	s_waitcnt lgkmcnt(0)
	s_setprio 1
	s_barrier
	v_mfma_f32_16x16x32_bf16 v[62:65], v[158:161], v[190:193], v[62:65]
	v_mfma_f32_16x16x32_bf16 v[58:61], v[166:169], v[190:193], v[58:61]
	v_mfma_f32_16x16x32_bf16 v[46:49], v[158:161], v[198:201], v[46:49]
	v_mfma_f32_16x16x32_bf16 v[42:45], v[166:169], v[198:201], v[42:45]
	v_mfma_f32_16x16x32_bf16 v[30:33], v[158:161], v[206:209], v[30:33]
	v_mfma_f32_16x16x32_bf16 v[26:29], v[166:169], v[206:209], v[26:29]
	v_mfma_f32_16x16x32_bf16 v[14:17], v[158:161], v[214:217], v[14:17]
	v_mfma_f32_16x16x32_bf16 v[10:13], v[166:169], v[214:217], v[10:13]
	v_mfma_f32_16x16x32_bf16 v[62:65], v[162:165], v[194:197], v[62:65]
	v_mfma_f32_16x16x32_bf16 v[58:61], v[170:173], v[194:197], v[58:61]
	v_mfma_f32_16x16x32_bf16 v[46:49], v[162:165], v[202:205], v[46:49]
	v_mfma_f32_16x16x32_bf16 v[42:45], v[170:173], v[202:205], v[42:45]
	v_mfma_f32_16x16x32_bf16 v[30:33], v[162:165], v[210:213], v[30:33]
	v_mfma_f32_16x16x32_bf16 v[26:29], v[170:173], v[210:213], v[26:29]
	v_mfma_f32_16x16x32_bf16 v[14:17], v[162:165], v[218:221], v[14:17]
	v_mfma_f32_16x16x32_bf16 v[10:13], v[170:173], v[218:221], v[10:13]
	s_setprio 0
	s_setprio 1
	v_mfma_f32_16x16x32_bf16 v[54:57], v[174:177], v[190:193], v[54:57]
	v_mfma_f32_16x16x32_bf16 v[50:53], v[182:185], v[190:193], v[50:53]
	v_mfma_f32_16x16x32_bf16 v[38:41], v[174:177], v[198:201], v[38:41]
	v_mfma_f32_16x16x32_bf16 v[34:37], v[182:185], v[198:201], v[34:37]
	v_mfma_f32_16x16x32_bf16 v[22:25], v[174:177], v[206:209], v[22:25]
	v_mfma_f32_16x16x32_bf16 v[18:21], v[182:185], v[206:209], v[18:21]
	v_mfma_f32_16x16x32_bf16 v[6:9], v[174:177], v[214:217], v[6:9]
	v_mfma_f32_16x16x32_bf16 v[2:5], v[182:185], v[214:217], v[2:5]
	v_mfma_f32_16x16x32_bf16 v[54:57], v[178:181], v[194:197], v[54:57]
	v_mfma_f32_16x16x32_bf16 v[50:53], v[186:189], v[194:197], v[50:53]
	v_mfma_f32_16x16x32_bf16 v[38:41], v[178:181], v[202:205], v[38:41]
	v_mfma_f32_16x16x32_bf16 v[34:37], v[186:189], v[202:205], v[34:37]
	v_mfma_f32_16x16x32_bf16 v[22:25], v[178:181], v[210:213], v[22:25]
	v_mfma_f32_16x16x32_bf16 v[18:21], v[186:189], v[210:213], v[18:21]
	v_mfma_f32_16x16x32_bf16 v[6:9], v[178:181], v[218:221], v[6:9]
	v_mfma_f32_16x16x32_bf16 v[2:5], v[186:189], v[218:221], v[2:5]
	s_setprio 0
	s_add_i32 s76, s76, 2
	s_add_u32 s54, s54, 0x100
	s_addc_u32 s55, s55, 0
	s_add_u32 s74, s74, 0x100
	s_addc_u32 s75, s75, 0
	s_cmp_gt_u32 s76, 13
	s_barrier
	s_cbranch_scc0 .LBB0_1357
	s_branch .Lz_post_p10
.LBB0_1357:
	ds_read_b128 v[158:161], v152
	ds_read_b128 v[162:165], v152 offset:1024
	ds_read_b128 v[166:169], v152 offset:2048
	ds_read_b128 v[170:173], v152 offset:3072
	ds_read_b128 v[174:177], v153
	ds_read_b128 v[178:181], v153 offset:1024
	ds_read_b128 v[182:185], v153 offset:2048
	ds_read_b128 v[186:189], v153 offset:3072
	s_add_u32 s56, s54, 0xfffc0080
	s_addc_u32 s57, s55, -1
	s_cmp_eq_u32 s76, 12
	s_cselect_b32 s59, s45, s57
	s_cselect_b32 s58, s51, s56
	s_cselect_b32 s57, s43, s75
	s_cselect_b32 s56, s53, s74
	v_lshl_add_u64 v[148:149], s[54:55], 0, v[140:141]
	s_add_i32 m0, s61, 0xc000
	ds_read_b128 v[190:193], v154
	ds_read_b128 v[194:197], v154 offset:1024
	ds_read_b128 v[198:201], v154 offset:2048
	ds_read_b128 v[202:205], v154 offset:3072
	ds_read_b128 v[206:209], v154 offset:4096
	ds_read_b128 v[210:213], v154 offset:5120
	ds_read_b128 v[214:217], v154 offset:6144
	ds_read_b128 v[218:221], v154 offset:7168
	global_load_lds_dwordx4 v[148:149], off
	v_lshl_add_u64 v[148:149], s[54:55], 0, v[142:143]
	s_add_i32 m0, s61, 0xe000
	s_nop 0
	global_load_lds_dwordx4 v[148:149], off
	s_waitcnt vmcnt(8)
	s_waitcnt lgkmcnt(0)
	s_setprio 1
	s_barrier
	v_mfma_f32_16x16x32_bf16 v[126:129], v[158:161], v[190:193], v[126:129]
	v_mfma_f32_16x16x32_bf16 v[122:125], v[166:169], v[190:193], v[122:125]
	v_mfma_f32_16x16x32_bf16 v[110:113], v[158:161], v[198:201], v[110:113]
	v_mfma_f32_16x16x32_bf16 v[106:109], v[166:169], v[198:201], v[106:109]
	v_mfma_f32_16x16x32_bf16 v[94:97], v[158:161], v[206:209], v[94:97]
	v_mfma_f32_16x16x32_bf16 v[90:93], v[166:169], v[206:209], v[90:93]
	v_mfma_f32_16x16x32_bf16 v[78:81], v[158:161], v[214:217], v[78:81]
	v_mfma_f32_16x16x32_bf16 v[74:77], v[166:169], v[214:217], v[74:77]
	v_mfma_f32_16x16x32_bf16 v[126:129], v[162:165], v[194:197], v[126:129]
	v_mfma_f32_16x16x32_bf16 v[122:125], v[170:173], v[194:197], v[122:125]
	v_mfma_f32_16x16x32_bf16 v[110:113], v[162:165], v[202:205], v[110:113]
	v_mfma_f32_16x16x32_bf16 v[106:109], v[170:173], v[202:205], v[106:109]
	v_mfma_f32_16x16x32_bf16 v[94:97], v[162:165], v[210:213], v[94:97]
	v_mfma_f32_16x16x32_bf16 v[90:93], v[170:173], v[210:213], v[90:93]
	v_mfma_f32_16x16x32_bf16 v[78:81], v[162:165], v[218:221], v[78:81]
	v_mfma_f32_16x16x32_bf16 v[74:77], v[170:173], v[218:221], v[74:77]
	s_setprio 0
	s_setprio 1
	v_mfma_f32_16x16x32_bf16 v[118:121], v[174:177], v[190:193], v[118:121]
	v_mfma_f32_16x16x32_bf16 v[114:117], v[182:185], v[190:193], v[114:117]
	v_mfma_f32_16x16x32_bf16 v[102:105], v[174:177], v[198:201], v[102:105]
	v_mfma_f32_16x16x32_bf16 v[98:101], v[182:185], v[198:201], v[98:101]
	v_mfma_f32_16x16x32_bf16 v[86:89], v[174:177], v[206:209], v[86:89]
	v_mfma_f32_16x16x32_bf16 v[82:85], v[182:185], v[206:209], v[82:85]
	v_mfma_f32_16x16x32_bf16 v[70:73], v[174:177], v[214:217], v[70:73]
	v_mfma_f32_16x16x32_bf16 v[66:69], v[182:185], v[214:217], v[66:69]
	v_mfma_f32_16x16x32_bf16 v[118:121], v[178:181], v[194:197], v[118:121]
	v_mfma_f32_16x16x32_bf16 v[114:117], v[186:189], v[194:197], v[114:117]
	v_mfma_f32_16x16x32_bf16 v[102:105], v[178:181], v[202:205], v[102:105]
	v_mfma_f32_16x16x32_bf16 v[98:101], v[186:189], v[202:205], v[98:101]
	v_mfma_f32_16x16x32_bf16 v[86:89], v[178:181], v[210:213], v[86:89]
	v_mfma_f32_16x16x32_bf16 v[82:85], v[186:189], v[210:213], v[82:85]
	v_mfma_f32_16x16x32_bf16 v[70:73], v[178:181], v[218:221], v[70:73]
	v_mfma_f32_16x16x32_bf16 v[66:69], v[186:189], v[218:221], v[66:69]
	s_setprio 0
	s_barrier
	s_add_i32 s77, s71, s60
	v_lshl_add_u64 v[148:149], s[56:57], 0, v[132:133]
	s_mov_b32 m0, s77
	ds_read_b128 v[190:193], v154 offset:16384
	ds_read_b128 v[194:197], v154 offset:17408
	ds_read_b128 v[198:201], v154 offset:18432
	ds_read_b128 v[202:205], v154 offset:19456
	ds_read_b128 v[206:209], v154 offset:20480
	ds_read_b128 v[210:213], v154 offset:21504
	ds_read_b128 v[214:217], v154 offset:22528
	ds_read_b128 v[218:221], v154 offset:23552
	global_load_lds_dwordx4 v[148:149], off
	s_add_i32 m0, s77, 0x2000
	s_add_u32 s78, s56, 0x40000
	v_lshl_add_u64 v[222:223], s[56:57], 0, v[136:137]
	s_addc_u32 s79, s57, 0
	s_add_i32 s77, s72, s60
	global_load_lds_dwordx4 v[222:223], off
	v_lshl_add_u64 v[224:225], s[78:79], 0, v[132:133]
	s_mov_b32 m0, s77
	v_lshl_add_u64 v[226:227], s[58:59], 0, v[134:135]
	global_load_lds_dwordx4 v[224:225], off
	v_lshl_add_u64 v[224:225], s[78:79], 0, v[136:137]
	s_add_i32 m0, s77, 0x2000
	s_nop 0
	global_load_lds_dwordx4 v[224:225], off
	v_lshl_add_u64 v[224:225], s[58:59], 0, v[130:131]
	s_mov_b32 m0, s61
	s_nop 0
	global_load_lds_dwordx4 v[224:225], off
	s_mov_b32 m0, s62
	s_nop 0
	global_load_lds_dwordx4 v[226:227], off
	s_waitcnt vmcnt(8)
	s_waitcnt lgkmcnt(0)
	s_setprio 1
	s_barrier
	v_mfma_f32_16x16x32_bf16 v[62:65], v[158:161], v[190:193], v[62:65]
	v_mfma_f32_16x16x32_bf16 v[58:61], v[166:169], v[190:193], v[58:61]
	v_mfma_f32_16x16x32_bf16 v[46:49], v[158:161], v[198:201], v[46:49]
	v_mfma_f32_16x16x32_bf16 v[42:45], v[166:169], v[198:201], v[42:45]
	v_mfma_f32_16x16x32_bf16 v[30:33], v[158:161], v[206:209], v[30:33]
	v_mfma_f32_16x16x32_bf16 v[26:29], v[166:169], v[206:209], v[26:29]
	v_mfma_f32_16x16x32_bf16 v[14:17], v[158:161], v[214:217], v[14:17]
	v_mfma_f32_16x16x32_bf16 v[10:13], v[166:169], v[214:217], v[10:13]
	v_mfma_f32_16x16x32_bf16 v[62:65], v[162:165], v[194:197], v[62:65]
	v_mfma_f32_16x16x32_bf16 v[58:61], v[170:173], v[194:197], v[58:61]
	v_mfma_f32_16x16x32_bf16 v[46:49], v[162:165], v[202:205], v[46:49]
	v_mfma_f32_16x16x32_bf16 v[42:45], v[170:173], v[202:205], v[42:45]
	v_mfma_f32_16x16x32_bf16 v[30:33], v[162:165], v[210:213], v[30:33]
	v_mfma_f32_16x16x32_bf16 v[26:29], v[170:173], v[210:213], v[26:29]
	v_mfma_f32_16x16x32_bf16 v[14:17], v[162:165], v[218:221], v[14:17]
	v_mfma_f32_16x16x32_bf16 v[10:13], v[170:173], v[218:221], v[10:13]
	s_setprio 0
	s_setprio 1
	v_mfma_f32_16x16x32_bf16 v[54:57], v[174:177], v[190:193], v[54:57]
	v_mfma_f32_16x16x32_bf16 v[50:53], v[182:185], v[190:193], v[50:53]
	v_mfma_f32_16x16x32_bf16 v[38:41], v[174:177], v[198:201], v[38:41]
	v_mfma_f32_16x16x32_bf16 v[34:37], v[182:185], v[198:201], v[34:37]
	v_mfma_f32_16x16x32_bf16 v[22:25], v[174:177], v[206:209], v[22:25]
	v_mfma_f32_16x16x32_bf16 v[18:21], v[182:185], v[206:209], v[18:21]
	v_mfma_f32_16x16x32_bf16 v[6:9], v[174:177], v[214:217], v[6:9]
	v_mfma_f32_16x16x32_bf16 v[2:5], v[182:185], v[214:217], v[2:5]
	v_mfma_f32_16x16x32_bf16 v[54:57], v[178:181], v[194:197], v[54:57]
	v_mfma_f32_16x16x32_bf16 v[50:53], v[186:189], v[194:197], v[50:53]
	v_mfma_f32_16x16x32_bf16 v[38:41], v[178:181], v[202:205], v[38:41]
	v_mfma_f32_16x16x32_bf16 v[34:37], v[186:189], v[202:205], v[34:37]
	v_mfma_f32_16x16x32_bf16 v[22:25], v[178:181], v[210:213], v[22:25]
	v_mfma_f32_16x16x32_bf16 v[18:21], v[186:189], v[210:213], v[18:21]
	v_mfma_f32_16x16x32_bf16 v[6:9], v[178:181], v[218:221], v[6:9]
	v_mfma_f32_16x16x32_bf16 v[2:5], v[186:189], v[218:221], v[2:5]
	s_setprio 0
	s_barrier
	s_add_i32 s77, 0, 0x18000
	v_add_u32_e32 v157, s77, v151
	s_add_i32 s78, 0, 0x1c000
	ds_read_b128 v[158:161], v157
	ds_read_b128 v[162:165], v157 offset:1024
	ds_read_b128 v[166:169], v157 offset:2048
	ds_read_b128 v[170:173], v157 offset:3072
	v_add_u32_e32 v157, s78, v151
	ds_read_b128 v[174:177], v157
	ds_read_b128 v[178:181], v157 offset:1024
	ds_read_b128 v[182:185], v157 offset:2048
	ds_read_b128 v[186:189], v157 offset:3072
	s_add_u32 s58, s58, 0x40000
	s_addc_u32 s59, s59, 0
	s_mov_b32 m0, s63
	v_lshl_add_u64 v[228:229], s[58:59], 0, v[130:131]
	ds_read_b128 v[190:193], v154 offset:32768
	ds_read_b128 v[194:197], v154 offset:33792
	ds_read_b128 v[198:201], v154 offset:34816
	ds_read_b128 v[202:205], v154 offset:35840
	ds_read_b128 v[206:209], v154 offset:36864
	ds_read_b128 v[210:213], v154 offset:37888
	ds_read_b128 v[214:217], v154 offset:38912
	ds_read_b128 v[218:221], v154 offset:39936
	global_load_lds_dwordx4 v[228:229], off
	v_lshl_add_u64 v[228:229], s[58:59], 0, v[134:135]
	s_mov_b32 m0, s64
	s_nop 0
	global_load_lds_dwordx4 v[228:229], off
	s_waitcnt vmcnt(8)
	s_waitcnt lgkmcnt(0)
	s_setprio 1
	s_barrier
	v_mfma_f32_16x16x32_bf16 v[126:129], v[158:161], v[190:193], v[126:129]
	v_mfma_f32_16x16x32_bf16 v[122:125], v[166:169], v[190:193], v[122:125]
	v_mfma_f32_16x16x32_bf16 v[110:113], v[158:161], v[198:201], v[110:113]
	v_mfma_f32_16x16x32_bf16 v[106:109], v[166:169], v[198:201], v[106:109]
	v_mfma_f32_16x16x32_bf16 v[94:97], v[158:161], v[206:209], v[94:97]
	v_mfma_f32_16x16x32_bf16 v[90:93], v[166:169], v[206:209], v[90:93]
	v_mfma_f32_16x16x32_bf16 v[78:81], v[158:161], v[214:217], v[78:81]
	v_mfma_f32_16x16x32_bf16 v[74:77], v[166:169], v[214:217], v[74:77]
	v_mfma_f32_16x16x32_bf16 v[126:129], v[162:165], v[194:197], v[126:129]
	v_mfma_f32_16x16x32_bf16 v[122:125], v[170:173], v[194:197], v[122:125]
	v_mfma_f32_16x16x32_bf16 v[110:113], v[162:165], v[202:205], v[110:113]
	v_mfma_f32_16x16x32_bf16 v[106:109], v[170:173], v[202:205], v[106:109]
	v_mfma_f32_16x16x32_bf16 v[94:97], v[162:165], v[210:213], v[94:97]
	v_mfma_f32_16x16x32_bf16 v[90:93], v[170:173], v[210:213], v[90:93]
	v_mfma_f32_16x16x32_bf16 v[78:81], v[162:165], v[218:221], v[78:81]
	v_mfma_f32_16x16x32_bf16 v[74:77], v[170:173], v[218:221], v[74:77]
	s_setprio 0
	s_setprio 1
	v_mfma_f32_16x16x32_bf16 v[118:121], v[174:177], v[190:193], v[118:121]
	v_mfma_f32_16x16x32_bf16 v[114:117], v[182:185], v[190:193], v[114:117]
	v_mfma_f32_16x16x32_bf16 v[102:105], v[174:177], v[198:201], v[102:105]
	v_mfma_f32_16x16x32_bf16 v[98:101], v[182:185], v[198:201], v[98:101]
	v_mfma_f32_16x16x32_bf16 v[86:89], v[174:177], v[206:209], v[86:89]
	v_mfma_f32_16x16x32_bf16 v[82:85], v[182:185], v[206:209], v[82:85]
	v_mfma_f32_16x16x32_bf16 v[70:73], v[174:177], v[214:217], v[70:73]
	v_mfma_f32_16x16x32_bf16 v[66:69], v[182:185], v[214:217], v[66:69]
	v_mfma_f32_16x16x32_bf16 v[118:121], v[178:181], v[194:197], v[118:121]
	v_mfma_f32_16x16x32_bf16 v[114:117], v[186:189], v[194:197], v[114:117]
	v_mfma_f32_16x16x32_bf16 v[102:105], v[178:181], v[202:205], v[102:105]
	v_mfma_f32_16x16x32_bf16 v[98:101], v[186:189], v[202:205], v[98:101]
	v_mfma_f32_16x16x32_bf16 v[86:89], v[178:181], v[210:213], v[86:89]
	v_mfma_f32_16x16x32_bf16 v[82:85], v[186:189], v[210:213], v[82:85]
	v_mfma_f32_16x16x32_bf16 v[70:73], v[178:181], v[218:221], v[70:73]
	v_mfma_f32_16x16x32_bf16 v[66:69], v[186:189], v[218:221], v[66:69]
	s_setprio 0
	s_barrier
	s_add_i32 s58, s77, s60
	v_lshl_add_u64 v[148:149], v[148:149], 0, s[24:25]
	s_mov_b32 m0, s58
	ds_read_b128 v[190:193], v154 offset:49152
	ds_read_b128 v[194:197], v154 offset:50176
	ds_read_b128 v[198:201], v154 offset:51200
	ds_read_b128 v[202:205], v154 offset:52224
	ds_read_b128 v[206:209], v154 offset:53248
	ds_read_b128 v[210:213], v154 offset:54272
	ds_read_b128 v[214:217], v154 offset:55296
	ds_read_b128 v[218:221], v154 offset:56320
	global_load_lds_dwordx4 v[148:149], off
	s_add_i32 m0, s58, 0x2000
	s_add_u32 s56, s56, 0x40080
	v_lshl_add_u64 v[148:149], v[222:223], 0, s[24:25]
	s_addc_u32 s57, s57, 0
	s_add_i32 s58, s78, s60
	global_load_lds_dwordx4 v[148:149], off
	v_lshl_add_u64 v[148:149], s[56:57], 0, v[132:133]
	s_mov_b32 m0, s58
	s_nop 0
	global_load_lds_dwordx4 v[148:149], off
	v_lshl_add_u64 v[148:149], s[56:57], 0, v[136:137]
	s_add_i32 m0, s58, 0x2000
	s_nop 0
	global_load_lds_dwordx4 v[148:149], off
	v_lshl_add_u64 v[148:149], v[224:225], 0, s[24:25]
	s_mov_b32 m0, s66
	s_nop 0
	global_load_lds_dwordx4 v[148:149], off
	v_lshl_add_u64 v[148:149], v[226:227], 0, s[24:25]
	s_mov_b32 m0, s67
	s_nop 0
	global_load_lds_dwordx4 v[148:149], off
	s_waitcnt vmcnt(8)
	s_waitcnt lgkmcnt(0)
	s_setprio 1
	s_barrier
	v_mfma_f32_16x16x32_bf16 v[62:65], v[158:161], v[190:193], v[62:65]
	v_mfma_f32_16x16x32_bf16 v[58:61], v[166:169], v[190:193], v[58:61]
	v_mfma_f32_16x16x32_bf16 v[46:49], v[158:161], v[198:201], v[46:49]
	v_mfma_f32_16x16x32_bf16 v[42:45], v[166:169], v[198:201], v[42:45]
	v_mfma_f32_16x16x32_bf16 v[30:33], v[158:161], v[206:209], v[30:33]
	v_mfma_f32_16x16x32_bf16 v[26:29], v[166:169], v[206:209], v[26:29]
	v_mfma_f32_16x16x32_bf16 v[14:17], v[158:161], v[214:217], v[14:17]
	v_mfma_f32_16x16x32_bf16 v[10:13], v[166:169], v[214:217], v[10:13]
	v_mfma_f32_16x16x32_bf16 v[62:65], v[162:165], v[194:197], v[62:65]
	v_mfma_f32_16x16x32_bf16 v[58:61], v[170:173], v[194:197], v[58:61]
	v_mfma_f32_16x16x32_bf16 v[46:49], v[162:165], v[202:205], v[46:49]
	v_mfma_f32_16x16x32_bf16 v[42:45], v[170:173], v[202:205], v[42:45]
	v_mfma_f32_16x16x32_bf16 v[30:33], v[162:165], v[210:213], v[30:33]
	v_mfma_f32_16x16x32_bf16 v[26:29], v[170:173], v[210:213], v[26:29]
	v_mfma_f32_16x16x32_bf16 v[14:17], v[162:165], v[218:221], v[14:17]
	v_mfma_f32_16x16x32_bf16 v[10:13], v[170:173], v[218:221], v[10:13]
	s_setprio 0
	s_setprio 1
	v_mfma_f32_16x16x32_bf16 v[54:57], v[174:177], v[190:193], v[54:57]
	v_mfma_f32_16x16x32_bf16 v[50:53], v[182:185], v[190:193], v[50:53]
	v_mfma_f32_16x16x32_bf16 v[38:41], v[174:177], v[198:201], v[38:41]
	v_mfma_f32_16x16x32_bf16 v[34:37], v[182:185], v[198:201], v[34:37]
	v_mfma_f32_16x16x32_bf16 v[22:25], v[174:177], v[206:209], v[22:25]
	v_mfma_f32_16x16x32_bf16 v[18:21], v[182:185], v[206:209], v[18:21]
	v_mfma_f32_16x16x32_bf16 v[6:9], v[174:177], v[214:217], v[6:9]
	v_mfma_f32_16x16x32_bf16 v[2:5], v[182:185], v[214:217], v[2:5]
	v_mfma_f32_16x16x32_bf16 v[54:57], v[178:181], v[194:197], v[54:57]
	v_mfma_f32_16x16x32_bf16 v[50:53], v[186:189], v[194:197], v[50:53]
	v_mfma_f32_16x16x32_bf16 v[38:41], v[178:181], v[202:205], v[38:41]
	v_mfma_f32_16x16x32_bf16 v[34:37], v[186:189], v[202:205], v[34:37]
	v_mfma_f32_16x16x32_bf16 v[22:25], v[178:181], v[210:213], v[22:25]
	v_mfma_f32_16x16x32_bf16 v[18:21], v[186:189], v[210:213], v[18:21]
	v_mfma_f32_16x16x32_bf16 v[6:9], v[178:181], v[218:221], v[6:9]
	v_mfma_f32_16x16x32_bf16 v[2:5], v[186:189], v[218:221], v[2:5]
	s_setprio 0
	s_add_i32 s76, s76, 2
	s_add_u32 s54, s54, 0x100
	s_addc_u32 s55, s55, 0
	s_add_u32 s74, s74, 0x100
	s_addc_u32 s75, s75, 0
	s_cmp_gt_u32 s76, 13
	s_barrier
	s_cbranch_scc0 .LBB0_1357

.LBB0_1485:
	s_add_u32 s10, s52, 0x100
	s_addc_u32 s79, s53, 0
	s_mov_b32 s80, -2
	s_waitcnt vmcnt(0)
	ds_read_b128 v[152:155], v157
	ds_read_b128 v[162:165], v157 offset:1024
	ds_read_b128 v[166:169], v157 offset:2048
	ds_read_b128 v[170:173], v157 offset:3072
	ds_read_b128 v[174:177], v158
	ds_read_b128 v[178:181], v158 offset:1024
	ds_read_b128 v[182:185], v158 offset:2048
	ds_read_b128 v[186:189], v158 offset:3072
	s_add_u32 s6, s50, 0x100
	s_addc_u32 s7, s51, 0
	s_cmp_eq_u32 s80, 8
	s_cselect_b32 s55, s47, s7
	s_cselect_b32 s54, s46, s6
	s_cselect_b32 s53, s49, s79
	s_cselect_b32 s52, s48, s10
	v_lshl_add_u64 v[222:223], s[50:51], 0, v[144:145]
	s_add_i32 m0, s57, 0xc000
	ds_read_b128 v[190:193], v159
	ds_read_b128 v[194:197], v159 offset:1024
	ds_read_b128 v[198:201], v159 offset:2048
	ds_read_b128 v[202:205], v159 offset:3072
	ds_read_b128 v[206:209], v159 offset:4096
	ds_read_b128 v[210:213], v159 offset:5120
	ds_read_b128 v[214:217], v159 offset:6144
	ds_read_b128 v[218:221], v159 offset:7168
	global_load_lds_dwordx4 v[222:223], off
	v_lshl_add_u64 v[222:223], s[50:51], 0, v[146:147]
	s_add_i32 m0, s57, 0xe000
	s_nop 0
	global_load_lds_dwordx4 v[222:223], off
	s_waitcnt vmcnt(8)
	s_waitcnt lgkmcnt(0)
	s_setprio 1
	s_barrier
	v_mfma_f32_16x16x32_bf16 v[126:129], v[152:155], v[190:193], 0
	v_mfma_f32_16x16x32_bf16 v[122:125], v[166:169], v[190:193], 0
	v_mfma_f32_16x16x32_bf16 v[110:113], v[152:155], v[198:201], 0
	v_mfma_f32_16x16x32_bf16 v[106:109], v[166:169], v[198:201], 0
	v_mfma_f32_16x16x32_bf16 v[94:97], v[152:155], v[206:209], 0
	v_mfma_f32_16x16x32_bf16 v[90:93], v[166:169], v[206:209], 0
	v_mfma_f32_16x16x32_bf16 v[78:81], v[152:155], v[214:217], 0
	v_mfma_f32_16x16x32_bf16 v[74:77], v[166:169], v[214:217], 0
	v_mfma_f32_16x16x32_bf16 v[126:129], v[162:165], v[194:197], v[126:129]
	v_mfma_f32_16x16x32_bf16 v[122:125], v[170:173], v[194:197], v[122:125]
	v_mfma_f32_16x16x32_bf16 v[110:113], v[162:165], v[202:205], v[110:113]
	v_mfma_f32_16x16x32_bf16 v[106:109], v[170:173], v[202:205], v[106:109]
	v_mfma_f32_16x16x32_bf16 v[94:97], v[162:165], v[210:213], v[94:97]
	v_mfma_f32_16x16x32_bf16 v[90:93], v[170:173], v[210:213], v[90:93]
	v_mfma_f32_16x16x32_bf16 v[78:81], v[162:165], v[218:221], v[78:81]
	v_mfma_f32_16x16x32_bf16 v[74:77], v[170:173], v[218:221], v[74:77]
	s_setprio 0
	s_setprio 1
	v_mfma_f32_16x16x32_bf16 v[118:121], v[174:177], v[190:193], 0
	v_mfma_f32_16x16x32_bf16 v[114:117], v[182:185], v[190:193], 0
	v_mfma_f32_16x16x32_bf16 v[102:105], v[174:177], v[198:201], 0
	v_mfma_f32_16x16x32_bf16 v[98:101], v[182:185], v[198:201], 0
	v_mfma_f32_16x16x32_bf16 v[86:89], v[174:177], v[206:209], 0
	v_mfma_f32_16x16x32_bf16 v[82:85], v[182:185], v[206:209], 0
	v_mfma_f32_16x16x32_bf16 v[70:73], v[174:177], v[214:217], 0
	v_mfma_f32_16x16x32_bf16 v[66:69], v[182:185], v[214:217], 0
	v_mfma_f32_16x16x32_bf16 v[118:121], v[178:181], v[194:197], v[118:121]
	v_mfma_f32_16x16x32_bf16 v[114:117], v[186:189], v[194:197], v[114:117]
	v_mfma_f32_16x16x32_bf16 v[102:105], v[178:181], v[202:205], v[102:105]
	v_mfma_f32_16x16x32_bf16 v[98:101], v[186:189], v[202:205], v[98:101]
	v_mfma_f32_16x16x32_bf16 v[86:89], v[178:181], v[210:213], v[86:89]
	v_mfma_f32_16x16x32_bf16 v[82:85], v[186:189], v[210:213], v[82:85]
	v_mfma_f32_16x16x32_bf16 v[70:73], v[178:181], v[218:221], v[70:73]
	v_mfma_f32_16x16x32_bf16 v[66:69], v[186:189], v[218:221], v[66:69]
	s_setprio 0
	s_barrier
	s_add_i32 s50, s68, s56
	v_lshl_add_u64 v[222:223], s[52:53], 0, v[132:133]
	s_mov_b32 m0, s50
	ds_read_b128 v[190:193], v159 offset:16384
	ds_read_b128 v[194:197], v159 offset:17408
	ds_read_b128 v[198:201], v159 offset:18432
	ds_read_b128 v[202:205], v159 offset:19456
	ds_read_b128 v[206:209], v159 offset:20480
	ds_read_b128 v[210:213], v159 offset:21504
	ds_read_b128 v[214:217], v159 offset:22528
	ds_read_b128 v[218:221], v159 offset:23552
	global_load_lds_dwordx4 v[222:223], off
	s_add_i32 m0, s50, 0x2000
	s_add_u32 s50, s52, 0x30000
	v_lshl_add_u64 v[224:225], s[52:53], 0, v[136:137]
	s_addc_u32 s51, s53, 0
	s_add_i32 s81, s69, s56
	global_load_lds_dwordx4 v[224:225], off
	v_lshl_add_u64 v[226:227], s[50:51], 0, v[132:133]
	s_mov_b32 m0, s81
	v_lshl_add_u64 v[228:229], s[54:55], 0, v[134:135]
	global_load_lds_dwordx4 v[226:227], off
	v_lshl_add_u64 v[226:227], s[50:51], 0, v[136:137]
	s_add_i32 m0, s81, 0x2000
	s_nop 0
	global_load_lds_dwordx4 v[226:227], off
	v_lshl_add_u64 v[226:227], s[54:55], 0, v[130:131]
	s_mov_b32 m0, s57
	s_nop 0
	global_load_lds_dwordx4 v[226:227], off
	s_mov_b32 m0, s58
	s_nop 0
	global_load_lds_dwordx4 v[228:229], off
	s_waitcnt vmcnt(8)
	s_waitcnt lgkmcnt(0)
	s_setprio 1
	s_barrier
	v_mfma_f32_16x16x32_bf16 v[62:65], v[152:155], v[190:193], 0
	v_mfma_f32_16x16x32_bf16 v[58:61], v[166:169], v[190:193], 0
	v_mfma_f32_16x16x32_bf16 v[46:49], v[152:155], v[198:201], 0
	v_mfma_f32_16x16x32_bf16 v[42:45], v[166:169], v[198:201], 0
	v_mfma_f32_16x16x32_bf16 v[30:33], v[152:155], v[206:209], 0
	v_mfma_f32_16x16x32_bf16 v[26:29], v[166:169], v[206:209], 0
	v_mfma_f32_16x16x32_bf16 v[14:17], v[152:155], v[214:217], 0
	v_mfma_f32_16x16x32_bf16 v[10:13], v[166:169], v[214:217], 0
	v_mfma_f32_16x16x32_bf16 v[62:65], v[162:165], v[194:197], v[62:65]
	v_mfma_f32_16x16x32_bf16 v[58:61], v[170:173], v[194:197], v[58:61]
	v_mfma_f32_16x16x32_bf16 v[46:49], v[162:165], v[202:205], v[46:49]
	v_mfma_f32_16x16x32_bf16 v[42:45], v[170:173], v[202:205], v[42:45]
	v_mfma_f32_16x16x32_bf16 v[30:33], v[162:165], v[210:213], v[30:33]
	v_mfma_f32_16x16x32_bf16 v[26:29], v[170:173], v[210:213], v[26:29]
	v_mfma_f32_16x16x32_bf16 v[14:17], v[162:165], v[218:221], v[14:17]
	v_mfma_f32_16x16x32_bf16 v[10:13], v[170:173], v[218:221], v[10:13]
	s_setprio 0
	s_setprio 1
	v_mfma_f32_16x16x32_bf16 v[54:57], v[174:177], v[190:193], 0
	v_mfma_f32_16x16x32_bf16 v[50:53], v[182:185], v[190:193], 0
	v_mfma_f32_16x16x32_bf16 v[38:41], v[174:177], v[198:201], 0
	v_mfma_f32_16x16x32_bf16 v[34:37], v[182:185], v[198:201], 0
	v_mfma_f32_16x16x32_bf16 v[22:25], v[174:177], v[206:209], 0
	v_mfma_f32_16x16x32_bf16 v[18:21], v[182:185], v[206:209], 0
	v_mfma_f32_16x16x32_bf16 v[6:9], v[174:177], v[214:217], 0
	v_mfma_f32_16x16x32_bf16 v[2:5], v[182:185], v[214:217], 0
	v_mfma_f32_16x16x32_bf16 v[54:57], v[178:181], v[194:197], v[54:57]
	v_mfma_f32_16x16x32_bf16 v[50:53], v[186:189], v[194:197], v[50:53]
	v_mfma_f32_16x16x32_bf16 v[38:41], v[178:181], v[202:205], v[38:41]
	v_mfma_f32_16x16x32_bf16 v[34:37], v[186:189], v[202:205], v[34:37]
	v_mfma_f32_16x16x32_bf16 v[22:25], v[178:181], v[210:213], v[22:25]
	v_mfma_f32_16x16x32_bf16 v[18:21], v[186:189], v[210:213], v[18:21]
	v_mfma_f32_16x16x32_bf16 v[6:9], v[178:181], v[218:221], v[6:9]
	v_mfma_f32_16x16x32_bf16 v[2:5], v[186:189], v[218:221], v[2:5]
	s_setprio 0
	s_barrier
	s_add_i32 s81, 0, 0x18000
	v_add_u32_e32 v138, s81, v143
	s_add_i32 s82, 0, 0x1c000
	ds_read_b128 v[152:155], v138
	ds_read_b128 v[162:165], v138 offset:1024
	ds_read_b128 v[166:169], v138 offset:2048
	ds_read_b128 v[170:173], v138 offset:3072
	v_add_u32_e32 v138, s82, v143
	ds_read_b128 v[174:177], v138
	ds_read_b128 v[178:181], v138 offset:1024
	ds_read_b128 v[182:185], v138 offset:2048
	ds_read_b128 v[186:189], v138 offset:3072
	s_add_u32 s50, s54, 0x30000
	s_addc_u32 s51, s55, 0
	s_mov_b32 m0, s59
	v_lshl_add_u64 v[230:231], s[50:51], 0, v[130:131]
	ds_read_b128 v[190:193], v159 offset:32768
	ds_read_b128 v[194:197], v159 offset:33792
	ds_read_b128 v[198:201], v159 offset:34816
	ds_read_b128 v[202:205], v159 offset:35840
	ds_read_b128 v[206:209], v159 offset:36864
	ds_read_b128 v[210:213], v159 offset:37888
	ds_read_b128 v[214:217], v159 offset:38912
	ds_read_b128 v[218:221], v159 offset:39936
	global_load_lds_dwordx4 v[230:231], off
	v_lshl_add_u64 v[230:231], s[50:51], 0, v[134:135]
	s_mov_b32 m0, s60
	s_nop 0
	global_load_lds_dwordx4 v[230:231], off
	s_waitcnt vmcnt(8)
	s_waitcnt lgkmcnt(0)
	s_setprio 1
	s_barrier
	v_mfma_f32_16x16x32_bf16 v[126:129], v[152:155], v[190:193], v[126:129]
	v_mfma_f32_16x16x32_bf16 v[122:125], v[166:169], v[190:193], v[122:125]
	v_mfma_f32_16x16x32_bf16 v[110:113], v[152:155], v[198:201], v[110:113]
	v_mfma_f32_16x16x32_bf16 v[106:109], v[166:169], v[198:201], v[106:109]
	v_mfma_f32_16x16x32_bf16 v[94:97], v[152:155], v[206:209], v[94:97]
	v_mfma_f32_16x16x32_bf16 v[90:93], v[166:169], v[206:209], v[90:93]
	v_mfma_f32_16x16x32_bf16 v[78:81], v[152:155], v[214:217], v[78:81]
	v_mfma_f32_16x16x32_bf16 v[74:77], v[166:169], v[214:217], v[74:77]
	v_mfma_f32_16x16x32_bf16 v[126:129], v[162:165], v[194:197], v[126:129]
	v_mfma_f32_16x16x32_bf16 v[122:125], v[170:173], v[194:197], v[122:125]
	v_mfma_f32_16x16x32_bf16 v[110:113], v[162:165], v[202:205], v[110:113]
	v_mfma_f32_16x16x32_bf16 v[106:109], v[170:173], v[202:205], v[106:109]
	v_mfma_f32_16x16x32_bf16 v[94:97], v[162:165], v[210:213], v[94:97]
	v_mfma_f32_16x16x32_bf16 v[90:93], v[170:173], v[210:213], v[90:93]
	v_mfma_f32_16x16x32_bf16 v[78:81], v[162:165], v[218:221], v[78:81]
	v_mfma_f32_16x16x32_bf16 v[74:77], v[170:173], v[218:221], v[74:77]
	s_setprio 0
	s_setprio 1
	v_mfma_f32_16x16x32_bf16 v[118:121], v[174:177], v[190:193], v[118:121]
	v_mfma_f32_16x16x32_bf16 v[114:117], v[182:185], v[190:193], v[114:117]
	v_mfma_f32_16x16x32_bf16 v[102:105], v[174:177], v[198:201], v[102:105]
	v_mfma_f32_16x16x32_bf16 v[98:101], v[182:185], v[198:201], v[98:101]
	v_mfma_f32_16x16x32_bf16 v[86:89], v[174:177], v[206:209], v[86:89]
	v_mfma_f32_16x16x32_bf16 v[82:85], v[182:185], v[206:209], v[82:85]
	v_mfma_f32_16x16x32_bf16 v[70:73], v[174:177], v[214:217], v[70:73]
	v_mfma_f32_16x16x32_bf16 v[66:69], v[182:185], v[214:217], v[66:69]
	v_mfma_f32_16x16x32_bf16 v[118:121], v[178:181], v[194:197], v[118:121]
	v_mfma_f32_16x16x32_bf16 v[114:117], v[186:189], v[194:197], v[114:117]
	v_mfma_f32_16x16x32_bf16 v[102:105], v[178:181], v[202:205], v[102:105]
	v_mfma_f32_16x16x32_bf16 v[98:101], v[186:189], v[202:205], v[98:101]
	v_mfma_f32_16x16x32_bf16 v[86:89], v[178:181], v[210:213], v[86:89]
	v_mfma_f32_16x16x32_bf16 v[82:85], v[186:189], v[210:213], v[82:85]
	v_mfma_f32_16x16x32_bf16 v[70:73], v[178:181], v[218:221], v[70:73]
	v_mfma_f32_16x16x32_bf16 v[66:69], v[186:189], v[218:221], v[66:69]
	s_setprio 0
	s_barrier
	s_add_i32 s50, s81, s56
	v_lshl_add_u64 v[222:223], v[222:223], 0, s[42:43]
	s_mov_b32 m0, s50
	ds_read_b128 v[190:193], v159 offset:49152
	ds_read_b128 v[194:197], v159 offset:50176
	ds_read_b128 v[198:201], v159 offset:51200
	ds_read_b128 v[202:205], v159 offset:52224
	ds_read_b128 v[206:209], v159 offset:53248
	ds_read_b128 v[210:213], v159 offset:54272
	ds_read_b128 v[214:217], v159 offset:55296
	ds_read_b128 v[218:221], v159 offset:56320
	global_load_lds_dwordx4 v[222:223], off
	s_add_i32 m0, s50, 0x2000
	s_add_u32 s50, s52, 0x30080
	v_lshl_add_u64 v[222:223], v[224:225], 0, s[42:43]
	s_addc_u32 s51, s53, 0
	s_add_i32 s52, s82, s56
	global_load_lds_dwordx4 v[222:223], off
	v_lshl_add_u64 v[222:223], s[50:51], 0, v[132:133]
	s_mov_b32 m0, s52
	s_nop 0
	global_load_lds_dwordx4 v[222:223], off
	v_lshl_add_u64 v[222:223], s[50:51], 0, v[136:137]
	s_add_i32 m0, s52, 0x2000
	s_nop 0
	global_load_lds_dwordx4 v[222:223], off
	v_lshl_add_u64 v[222:223], v[226:227], 0, s[42:43]
	s_mov_b32 m0, s61
	s_nop 0
	global_load_lds_dwordx4 v[222:223], off
	v_lshl_add_u64 v[222:223], v[228:229], 0, s[42:43]
	s_mov_b32 m0, s62
	s_nop 0
	global_load_lds_dwordx4 v[222:223], off
	s_waitcnt vmcnt(8)
	s_waitcnt lgkmcnt(0)
	s_setprio 1
	s_barrier
	v_mfma_f32_16x16x32_bf16 v[62:65], v[152:155], v[190:193], v[62:65]
	v_mfma_f32_16x16x32_bf16 v[58:61], v[166:169], v[190:193], v[58:61]
	v_mfma_f32_16x16x32_bf16 v[46:49], v[152:155], v[198:201], v[46:49]
	v_mfma_f32_16x16x32_bf16 v[42:45], v[166:169], v[198:201], v[42:45]
	v_mfma_f32_16x16x32_bf16 v[30:33], v[152:155], v[206:209], v[30:33]
	v_mfma_f32_16x16x32_bf16 v[26:29], v[166:169], v[206:209], v[26:29]
	v_mfma_f32_16x16x32_bf16 v[14:17], v[152:155], v[214:217], v[14:17]
	v_mfma_f32_16x16x32_bf16 v[10:13], v[166:169], v[214:217], v[10:13]
	v_mfma_f32_16x16x32_bf16 v[62:65], v[162:165], v[194:197], v[62:65]
	v_mfma_f32_16x16x32_bf16 v[58:61], v[170:173], v[194:197], v[58:61]
	v_mfma_f32_16x16x32_bf16 v[46:49], v[162:165], v[202:205], v[46:49]
	v_mfma_f32_16x16x32_bf16 v[42:45], v[170:173], v[202:205], v[42:45]
	v_mfma_f32_16x16x32_bf16 v[30:33], v[162:165], v[210:213], v[30:33]
	v_mfma_f32_16x16x32_bf16 v[26:29], v[170:173], v[210:213], v[26:29]
	v_mfma_f32_16x16x32_bf16 v[14:17], v[162:165], v[218:221], v[14:17]
	v_mfma_f32_16x16x32_bf16 v[10:13], v[170:173], v[218:221], v[10:13]
	s_setprio 0
	s_setprio 1
	v_mfma_f32_16x16x32_bf16 v[54:57], v[174:177], v[190:193], v[54:57]
	v_mfma_f32_16x16x32_bf16 v[50:53], v[182:185], v[190:193], v[50:53]
	v_mfma_f32_16x16x32_bf16 v[38:41], v[174:177], v[198:201], v[38:41]
	v_mfma_f32_16x16x32_bf16 v[34:37], v[182:185], v[198:201], v[34:37]
	v_mfma_f32_16x16x32_bf16 v[22:25], v[174:177], v[206:209], v[22:25]
	v_mfma_f32_16x16x32_bf16 v[18:21], v[182:185], v[206:209], v[18:21]
	v_mfma_f32_16x16x32_bf16 v[6:9], v[174:177], v[214:217], v[6:9]
	v_mfma_f32_16x16x32_bf16 v[2:5], v[182:185], v[214:217], v[2:5]
	v_mfma_f32_16x16x32_bf16 v[54:57], v[178:181], v[194:197], v[54:57]
	v_mfma_f32_16x16x32_bf16 v[50:53], v[186:189], v[194:197], v[50:53]
	v_mfma_f32_16x16x32_bf16 v[38:41], v[178:181], v[202:205], v[38:41]
	v_mfma_f32_16x16x32_bf16 v[34:37], v[186:189], v[202:205], v[34:37]
	v_mfma_f32_16x16x32_bf16 v[22:25], v[178:181], v[210:213], v[22:25]
	v_mfma_f32_16x16x32_bf16 v[18:21], v[186:189], v[210:213], v[18:21]
	v_mfma_f32_16x16x32_bf16 v[6:9], v[178:181], v[218:221], v[6:9]
	v_mfma_f32_16x16x32_bf16 v[2:5], v[186:189], v[218:221], v[2:5]
	s_setprio 0
	s_add_i32 s80, s80, 2
	s_add_u32 s10, s10, 0x100
	s_addc_u32 s79, s79, 0
	s_cmp_gt_u32 s80, 9
	s_mov_b64 s[50:51], s[6:7]
	s_barrier
	s_cbranch_scc0 .LBB0_1486
	s_branch .Lz_post_p11
.LBB0_1486:
	ds_read_b128 v[152:155], v157
	ds_read_b128 v[162:165], v157 offset:1024
	ds_read_b128 v[166:169], v157 offset:2048
	ds_read_b128 v[170:173], v157 offset:3072
	ds_read_b128 v[174:177], v158
	ds_read_b128 v[178:181], v158 offset:1024
	ds_read_b128 v[182:185], v158 offset:2048
	ds_read_b128 v[186:189], v158 offset:3072
	s_add_u32 s6, s50, 0x100
	s_addc_u32 s7, s51, 0
	s_cmp_eq_u32 s80, 8
	s_cselect_b32 s55, s47, s7
	s_cselect_b32 s54, s46, s6
	s_cselect_b32 s53, s49, s79
	s_cselect_b32 s52, s48, s10
	v_lshl_add_u64 v[222:223], s[50:51], 0, v[144:145]
	s_add_i32 m0, s57, 0xc000
	ds_read_b128 v[190:193], v159
	ds_read_b128 v[194:197], v159 offset:1024
	ds_read_b128 v[198:201], v159 offset:2048
	ds_read_b128 v[202:205], v159 offset:3072
	ds_read_b128 v[206:209], v159 offset:4096
	ds_read_b128 v[210:213], v159 offset:5120
	ds_read_b128 v[214:217], v159 offset:6144
	ds_read_b128 v[218:221], v159 offset:7168
	global_load_lds_dwordx4 v[222:223], off
	v_lshl_add_u64 v[222:223], s[50:51], 0, v[146:147]
	s_add_i32 m0, s57, 0xe000
	s_nop 0
	global_load_lds_dwordx4 v[222:223], off
	s_waitcnt vmcnt(8)
	s_waitcnt lgkmcnt(0)
	s_setprio 1
	s_barrier
	v_mfma_f32_16x16x32_bf16 v[126:129], v[152:155], v[190:193], v[126:129]
	v_mfma_f32_16x16x32_bf16 v[122:125], v[166:169], v[190:193], v[122:125]
	v_mfma_f32_16x16x32_bf16 v[110:113], v[152:155], v[198:201], v[110:113]
	v_mfma_f32_16x16x32_bf16 v[106:109], v[166:169], v[198:201], v[106:109]
	v_mfma_f32_16x16x32_bf16 v[94:97], v[152:155], v[206:209], v[94:97]
	v_mfma_f32_16x16x32_bf16 v[90:93], v[166:169], v[206:209], v[90:93]
	v_mfma_f32_16x16x32_bf16 v[78:81], v[152:155], v[214:217], v[78:81]
	v_mfma_f32_16x16x32_bf16 v[74:77], v[166:169], v[214:217], v[74:77]
	v_mfma_f32_16x16x32_bf16 v[126:129], v[162:165], v[194:197], v[126:129]
	v_mfma_f32_16x16x32_bf16 v[122:125], v[170:173], v[194:197], v[122:125]
	v_mfma_f32_16x16x32_bf16 v[110:113], v[162:165], v[202:205], v[110:113]
	v_mfma_f32_16x16x32_bf16 v[106:109], v[170:173], v[202:205], v[106:109]
	v_mfma_f32_16x16x32_bf16 v[94:97], v[162:165], v[210:213], v[94:97]
	v_mfma_f32_16x16x32_bf16 v[90:93], v[170:173], v[210:213], v[90:93]
	v_mfma_f32_16x16x32_bf16 v[78:81], v[162:165], v[218:221], v[78:81]
	v_mfma_f32_16x16x32_bf16 v[74:77], v[170:173], v[218:221], v[74:77]
	s_setprio 0
	s_setprio 1
	v_mfma_f32_16x16x32_bf16 v[118:121], v[174:177], v[190:193], v[118:121]
	v_mfma_f32_16x16x32_bf16 v[114:117], v[182:185], v[190:193], v[114:117]
	v_mfma_f32_16x16x32_bf16 v[102:105], v[174:177], v[198:201], v[102:105]
	v_mfma_f32_16x16x32_bf16 v[98:101], v[182:185], v[198:201], v[98:101]
	v_mfma_f32_16x16x32_bf16 v[86:89], v[174:177], v[206:209], v[86:89]
	v_mfma_f32_16x16x32_bf16 v[82:85], v[182:185], v[206:209], v[82:85]
	v_mfma_f32_16x16x32_bf16 v[70:73], v[174:177], v[214:217], v[70:73]
	v_mfma_f32_16x16x32_bf16 v[66:69], v[182:185], v[214:217], v[66:69]
	v_mfma_f32_16x16x32_bf16 v[118:121], v[178:181], v[194:197], v[118:121]
	v_mfma_f32_16x16x32_bf16 v[114:117], v[186:189], v[194:197], v[114:117]
	v_mfma_f32_16x16x32_bf16 v[102:105], v[178:181], v[202:205], v[102:105]
	v_mfma_f32_16x16x32_bf16 v[98:101], v[186:189], v[202:205], v[98:101]
	v_mfma_f32_16x16x32_bf16 v[86:89], v[178:181], v[210:213], v[86:89]
	v_mfma_f32_16x16x32_bf16 v[82:85], v[186:189], v[210:213], v[82:85]
	v_mfma_f32_16x16x32_bf16 v[70:73], v[178:181], v[218:221], v[70:73]
	v_mfma_f32_16x16x32_bf16 v[66:69], v[186:189], v[218:221], v[66:69]
	s_setprio 0
	s_barrier
	s_add_i32 s50, s68, s56
	v_lshl_add_u64 v[222:223], s[52:53], 0, v[132:133]
	s_mov_b32 m0, s50
	ds_read_b128 v[190:193], v159 offset:16384
	ds_read_b128 v[194:197], v159 offset:17408
	ds_read_b128 v[198:201], v159 offset:18432
	ds_read_b128 v[202:205], v159 offset:19456
	ds_read_b128 v[206:209], v159 offset:20480
	ds_read_b128 v[210:213], v159 offset:21504
	ds_read_b128 v[214:217], v159 offset:22528
	ds_read_b128 v[218:221], v159 offset:23552
	global_load_lds_dwordx4 v[222:223], off
	s_add_i32 m0, s50, 0x2000
	s_add_u32 s50, s52, 0x30000
	v_lshl_add_u64 v[224:225], s[52:53], 0, v[136:137]
	s_addc_u32 s51, s53, 0
	s_add_i32 s81, s69, s56
	global_load_lds_dwordx4 v[224:225], off
	v_lshl_add_u64 v[226:227], s[50:51], 0, v[132:133]
	s_mov_b32 m0, s81
	v_lshl_add_u64 v[228:229], s[54:55], 0, v[134:135]
	global_load_lds_dwordx4 v[226:227], off
	v_lshl_add_u64 v[226:227], s[50:51], 0, v[136:137]
	s_add_i32 m0, s81, 0x2000
	s_nop 0
	global_load_lds_dwordx4 v[226:227], off
	v_lshl_add_u64 v[226:227], s[54:55], 0, v[130:131]
	s_mov_b32 m0, s57
	s_nop 0
	global_load_lds_dwordx4 v[226:227], off
	s_mov_b32 m0, s58
	s_nop 0
	global_load_lds_dwordx4 v[228:229], off
	s_waitcnt vmcnt(8)
	s_waitcnt lgkmcnt(0)
	s_setprio 1
	s_barrier
	v_mfma_f32_16x16x32_bf16 v[62:65], v[152:155], v[190:193], v[62:65]
	v_mfma_f32_16x16x32_bf16 v[58:61], v[166:169], v[190:193], v[58:61]
	v_mfma_f32_16x16x32_bf16 v[46:49], v[152:155], v[198:201], v[46:49]
	v_mfma_f32_16x16x32_bf16 v[42:45], v[166:169], v[198:201], v[42:45]
	v_mfma_f32_16x16x32_bf16 v[30:33], v[152:155], v[206:209], v[30:33]
	v_mfma_f32_16x16x32_bf16 v[26:29], v[166:169], v[206:209], v[26:29]
	v_mfma_f32_16x16x32_bf16 v[14:17], v[152:155], v[214:217], v[14:17]
	v_mfma_f32_16x16x32_bf16 v[10:13], v[166:169], v[214:217], v[10:13]
	v_mfma_f32_16x16x32_bf16 v[62:65], v[162:165], v[194:197], v[62:65]
	v_mfma_f32_16x16x32_bf16 v[58:61], v[170:173], v[194:197], v[58:61]
	v_mfma_f32_16x16x32_bf16 v[46:49], v[162:165], v[202:205], v[46:49]
	v_mfma_f32_16x16x32_bf16 v[42:45], v[170:173], v[202:205], v[42:45]
	v_mfma_f32_16x16x32_bf16 v[30:33], v[162:165], v[210:213], v[30:33]
	v_mfma_f32_16x16x32_bf16 v[26:29], v[170:173], v[210:213], v[26:29]
	v_mfma_f32_16x16x32_bf16 v[14:17], v[162:165], v[218:221], v[14:17]
	v_mfma_f32_16x16x32_bf16 v[10:13], v[170:173], v[218:221], v[10:13]
	s_setprio 0
	s_setprio 1
	v_mfma_f32_16x16x32_bf16 v[54:57], v[174:177], v[190:193], v[54:57]
	v_mfma_f32_16x16x32_bf16 v[50:53], v[182:185], v[190:193], v[50:53]
	v_mfma_f32_16x16x32_bf16 v[38:41], v[174:177], v[198:201], v[38:41]
	v_mfma_f32_16x16x32_bf16 v[34:37], v[182:185], v[198:201], v[34:37]
	v_mfma_f32_16x16x32_bf16 v[22:25], v[174:177], v[206:209], v[22:25]
	v_mfma_f32_16x16x32_bf16 v[18:21], v[182:185], v[206:209], v[18:21]
	v_mfma_f32_16x16x32_bf16 v[6:9], v[174:177], v[214:217], v[6:9]
	v_mfma_f32_16x16x32_bf16 v[2:5], v[182:185], v[214:217], v[2:5]
	v_mfma_f32_16x16x32_bf16 v[54:57], v[178:181], v[194:197], v[54:57]
	v_mfma_f32_16x16x32_bf16 v[50:53], v[186:189], v[194:197], v[50:53]
	v_mfma_f32_16x16x32_bf16 v[38:41], v[178:181], v[202:205], v[38:41]
	v_mfma_f32_16x16x32_bf16 v[34:37], v[186:189], v[202:205], v[34:37]
	v_mfma_f32_16x16x32_bf16 v[22:25], v[178:181], v[210:213], v[22:25]
	v_mfma_f32_16x16x32_bf16 v[18:21], v[186:189], v[210:213], v[18:21]
	v_mfma_f32_16x16x32_bf16 v[6:9], v[178:181], v[218:221], v[6:9]
	v_mfma_f32_16x16x32_bf16 v[2:5], v[186:189], v[218:221], v[2:5]
	s_setprio 0
	s_barrier
	s_add_i32 s81, 0, 0x18000
	v_add_u32_e32 v138, s81, v143
	s_add_i32 s82, 0, 0x1c000
	ds_read_b128 v[152:155], v138
	ds_read_b128 v[162:165], v138 offset:1024
	ds_read_b128 v[166:169], v138 offset:2048
	ds_read_b128 v[170:173], v138 offset:3072
	v_add_u32_e32 v138, s82, v143
	ds_read_b128 v[174:177], v138
	ds_read_b128 v[178:181], v138 offset:1024
	ds_read_b128 v[182:185], v138 offset:2048
	ds_read_b128 v[186:189], v138 offset:3072
	s_add_u32 s50, s54, 0x30000
	s_addc_u32 s51, s55, 0
	s_mov_b32 m0, s59
	v_lshl_add_u64 v[230:231], s[50:51], 0, v[130:131]
	ds_read_b128 v[190:193], v159 offset:32768
	ds_read_b128 v[194:197], v159 offset:33792
	ds_read_b128 v[198:201], v159 offset:34816
	ds_read_b128 v[202:205], v159 offset:35840
	ds_read_b128 v[206:209], v159 offset:36864
	ds_read_b128 v[210:213], v159 offset:37888
	ds_read_b128 v[214:217], v159 offset:38912
	ds_read_b128 v[218:221], v159 offset:39936
	global_load_lds_dwordx4 v[230:231], off
	v_lshl_add_u64 v[230:231], s[50:51], 0, v[134:135]
	s_mov_b32 m0, s60
	s_nop 0
	global_load_lds_dwordx4 v[230:231], off
	s_waitcnt vmcnt(8)
	s_waitcnt lgkmcnt(0)
	s_setprio 1
	s_barrier
	v_mfma_f32_16x16x32_bf16 v[126:129], v[152:155], v[190:193], v[126:129]
	v_mfma_f32_16x16x32_bf16 v[122:125], v[166:169], v[190:193], v[122:125]
	v_mfma_f32_16x16x32_bf16 v[110:113], v[152:155], v[198:201], v[110:113]
	v_mfma_f32_16x16x32_bf16 v[106:109], v[166:169], v[198:201], v[106:109]
	v_mfma_f32_16x16x32_bf16 v[94:97], v[152:155], v[206:209], v[94:97]
	v_mfma_f32_16x16x32_bf16 v[90:93], v[166:169], v[206:209], v[90:93]
	v_mfma_f32_16x16x32_bf16 v[78:81], v[152:155], v[214:217], v[78:81]
	v_mfma_f32_16x16x32_bf16 v[74:77], v[166:169], v[214:217], v[74:77]
	v_mfma_f32_16x16x32_bf16 v[126:129], v[162:165], v[194:197], v[126:129]
	v_mfma_f32_16x16x32_bf16 v[122:125], v[170:173], v[194:197], v[122:125]
	v_mfma_f32_16x16x32_bf16 v[110:113], v[162:165], v[202:205], v[110:113]
	v_mfma_f32_16x16x32_bf16 v[106:109], v[170:173], v[202:205], v[106:109]
	v_mfma_f32_16x16x32_bf16 v[94:97], v[162:165], v[210:213], v[94:97]
	v_mfma_f32_16x16x32_bf16 v[90:93], v[170:173], v[210:213], v[90:93]
	v_mfma_f32_16x16x32_bf16 v[78:81], v[162:165], v[218:221], v[78:81]
	v_mfma_f32_16x16x32_bf16 v[74:77], v[170:173], v[218:221], v[74:77]
	s_setprio 0
	s_setprio 1
	v_mfma_f32_16x16x32_bf16 v[118:121], v[174:177], v[190:193], v[118:121]
	v_mfma_f32_16x16x32_bf16 v[114:117], v[182:185], v[190:193], v[114:117]
	v_mfma_f32_16x16x32_bf16 v[102:105], v[174:177], v[198:201], v[102:105]
	v_mfma_f32_16x16x32_bf16 v[98:101], v[182:185], v[198:201], v[98:101]
	v_mfma_f32_16x16x32_bf16 v[86:89], v[174:177], v[206:209], v[86:89]
	v_mfma_f32_16x16x32_bf16 v[82:85], v[182:185], v[206:209], v[82:85]
	v_mfma_f32_16x16x32_bf16 v[70:73], v[174:177], v[214:217], v[70:73]
	v_mfma_f32_16x16x32_bf16 v[66:69], v[182:185], v[214:217], v[66:69]
	v_mfma_f32_16x16x32_bf16 v[118:121], v[178:181], v[194:197], v[118:121]
	v_mfma_f32_16x16x32_bf16 v[114:117], v[186:189], v[194:197], v[114:117]
	v_mfma_f32_16x16x32_bf16 v[102:105], v[178:181], v[202:205], v[102:105]
	v_mfma_f32_16x16x32_bf16 v[98:101], v[186:189], v[202:205], v[98:101]
	v_mfma_f32_16x16x32_bf16 v[86:89], v[178:181], v[210:213], v[86:89]
	v_mfma_f32_16x16x32_bf16 v[82:85], v[186:189], v[210:213], v[82:85]
	v_mfma_f32_16x16x32_bf16 v[70:73], v[178:181], v[218:221], v[70:73]
	v_mfma_f32_16x16x32_bf16 v[66:69], v[186:189], v[218:221], v[66:69]
	s_setprio 0
	s_barrier
	s_add_i32 s50, s81, s56
	v_lshl_add_u64 v[222:223], v[222:223], 0, s[42:43]
	s_mov_b32 m0, s50
	ds_read_b128 v[190:193], v159 offset:49152
	ds_read_b128 v[194:197], v159 offset:50176
	ds_read_b128 v[198:201], v159 offset:51200
	ds_read_b128 v[202:205], v159 offset:52224
	ds_read_b128 v[206:209], v159 offset:53248
	ds_read_b128 v[210:213], v159 offset:54272
	ds_read_b128 v[214:217], v159 offset:55296
	ds_read_b128 v[218:221], v159 offset:56320
	global_load_lds_dwordx4 v[222:223], off
	s_add_i32 m0, s50, 0x2000
	s_add_u32 s50, s52, 0x30080
	v_lshl_add_u64 v[222:223], v[224:225], 0, s[42:43]
	s_addc_u32 s51, s53, 0
	s_add_i32 s52, s82, s56
	global_load_lds_dwordx4 v[222:223], off
	v_lshl_add_u64 v[222:223], s[50:51], 0, v[132:133]
	s_mov_b32 m0, s52
	s_nop 0
	global_load_lds_dwordx4 v[222:223], off
	v_lshl_add_u64 v[222:223], s[50:51], 0, v[136:137]
	s_add_i32 m0, s52, 0x2000
	s_nop 0
	global_load_lds_dwordx4 v[222:223], off
	v_lshl_add_u64 v[222:223], v[226:227], 0, s[42:43]
	s_mov_b32 m0, s61
	s_nop 0
	global_load_lds_dwordx4 v[222:223], off
	v_lshl_add_u64 v[222:223], v[228:229], 0, s[42:43]
	s_mov_b32 m0, s62
	s_nop 0
	global_load_lds_dwordx4 v[222:223], off
	s_waitcnt vmcnt(8)
	s_waitcnt lgkmcnt(0)
	s_setprio 1
	s_barrier
	v_mfma_f32_16x16x32_bf16 v[62:65], v[152:155], v[190:193], v[62:65]
	v_mfma_f32_16x16x32_bf16 v[58:61], v[166:169], v[190:193], v[58:61]
	v_mfma_f32_16x16x32_bf16 v[46:49], v[152:155], v[198:201], v[46:49]
	v_mfma_f32_16x16x32_bf16 v[42:45], v[166:169], v[198:201], v[42:45]
	v_mfma_f32_16x16x32_bf16 v[30:33], v[152:155], v[206:209], v[30:33]
	v_mfma_f32_16x16x32_bf16 v[26:29], v[166:169], v[206:209], v[26:29]
	v_mfma_f32_16x16x32_bf16 v[14:17], v[152:155], v[214:217], v[14:17]
	v_mfma_f32_16x16x32_bf16 v[10:13], v[166:169], v[214:217], v[10:13]
	v_mfma_f32_16x16x32_bf16 v[62:65], v[162:165], v[194:197], v[62:65]
	v_mfma_f32_16x16x32_bf16 v[58:61], v[170:173], v[194:197], v[58:61]
	v_mfma_f32_16x16x32_bf16 v[46:49], v[162:165], v[202:205], v[46:49]
	v_mfma_f32_16x16x32_bf16 v[42:45], v[170:173], v[202:205], v[42:45]
	v_mfma_f32_16x16x32_bf16 v[30:33], v[162:165], v[210:213], v[30:33]
	v_mfma_f32_16x16x32_bf16 v[26:29], v[170:173], v[210:213], v[26:29]
	v_mfma_f32_16x16x32_bf16 v[14:17], v[162:165], v[218:221], v[14:17]
	v_mfma_f32_16x16x32_bf16 v[10:13], v[170:173], v[218:221], v[10:13]
	s_setprio 0
	s_setprio 1
	v_mfma_f32_16x16x32_bf16 v[54:57], v[174:177], v[190:193], v[54:57]
	v_mfma_f32_16x16x32_bf16 v[50:53], v[182:185], v[190:193], v[50:53]
	v_mfma_f32_16x16x32_bf16 v[38:41], v[174:177], v[198:201], v[38:41]
	v_mfma_f32_16x16x32_bf16 v[34:37], v[182:185], v[198:201], v[34:37]
	v_mfma_f32_16x16x32_bf16 v[22:25], v[174:177], v[206:209], v[22:25]
	v_mfma_f32_16x16x32_bf16 v[18:21], v[182:185], v[206:209], v[18:21]
	v_mfma_f32_16x16x32_bf16 v[6:9], v[174:177], v[214:217], v[6:9]
	v_mfma_f32_16x16x32_bf16 v[2:5], v[182:185], v[214:217], v[2:5]
	v_mfma_f32_16x16x32_bf16 v[54:57], v[178:181], v[194:197], v[54:57]
	v_mfma_f32_16x16x32_bf16 v[50:53], v[186:189], v[194:197], v[50:53]
	v_mfma_f32_16x16x32_bf16 v[38:41], v[178:181], v[202:205], v[38:41]
	v_mfma_f32_16x16x32_bf16 v[34:37], v[186:189], v[202:205], v[34:37]
	v_mfma_f32_16x16x32_bf16 v[22:25], v[178:181], v[210:213], v[22:25]
	v_mfma_f32_16x16x32_bf16 v[18:21], v[186:189], v[210:213], v[18:21]
	v_mfma_f32_16x16x32_bf16 v[6:9], v[178:181], v[218:221], v[6:9]
	v_mfma_f32_16x16x32_bf16 v[2:5], v[186:189], v[218:221], v[2:5]
	s_setprio 0
	s_add_i32 s80, s80, 2
	s_add_u32 s10, s10, 0x100
	s_addc_u32 s79, s79, 0
	s_cmp_gt_u32 s80, 9
	s_mov_b64 s[50:51], s[6:7]
	s_barrier
	s_cbranch_scc0 .LBB0_1486

.LBB0_1908:
	s_add_u32 s69, s46, 0x100
	s_addc_u32 s70, s47, 0
	s_mov_b32 s71, -2
	s_waitcnt lgkmcnt(0)
	s_waitcnt vmcnt(0)
	ds_read_b128 v[114:117], v225
	ds_read_b128 v[126:129], v225 offset:1024
	ds_read_b128 v[138:141], v225 offset:2048
	ds_read_b128 v[142:145], v225 offset:3072
	ds_read_b128 v[146:149], v226
	ds_read_b128 v[150:153], v226 offset:1024
	ds_read_b128 v[154:157], v226 offset:2048
	ds_read_b128 v[158:161], v226 offset:3072
	s_add_u32 s46, s44, 0x100
	s_addc_u32 s47, s45, 0
	s_cmp_eq_u32 s71, 40
	s_cselect_b32 s51, s9, s47
	s_cselect_b32 s50, s8, s46
	s_cselect_b32 s49, s43, s70
	s_cselect_b32 s48, s42, s69
	v_lshl_add_u64 v[214:215], s[44:45], 0, v[198:199]
	s_add_i32 m0, s53, 0xc000
	ds_read_b128 v[162:165], v227
	ds_read_b128 v[166:169], v227 offset:1024
	ds_read_b128 v[170:173], v227 offset:2048
	ds_read_b128 v[174:177], v227 offset:3072
	ds_read_b128 v[178:181], v227 offset:4096
	ds_read_b128 v[182:185], v227 offset:5120
	ds_read_b128 v[206:209], v227 offset:6144
	ds_read_b128 v[210:213], v227 offset:7168
	global_load_lds_dwordx4 v[214:215], off
	v_lshl_add_u64 v[214:215], s[44:45], 0, v[200:201]
	s_add_i32 m0, s53, 0xe000
	s_nop 0
	global_load_lds_dwordx4 v[214:215], off
	s_waitcnt vmcnt(8)
	s_waitcnt lgkmcnt(0)
	s_setprio 1
	s_barrier
	v_mfma_f32_16x16x32_bf16 v[134:137], v[114:117], v[162:165], 0
	v_mfma_f32_16x16x32_bf16 v[130:133], v[138:141], v[162:165], 0
	v_mfma_f32_16x16x32_bf16 v[110:113], v[114:117], v[170:173], 0
	v_mfma_f32_16x16x32_bf16 v[106:109], v[138:141], v[170:173], 0
	v_mfma_f32_16x16x32_bf16 v[94:97], v[114:117], v[178:181], 0
	v_mfma_f32_16x16x32_bf16 v[90:93], v[138:141], v[178:181], 0
	v_mfma_f32_16x16x32_bf16 v[78:81], v[114:117], v[206:209], 0
	v_mfma_f32_16x16x32_bf16 v[74:77], v[138:141], v[206:209], 0
	v_mfma_f32_16x16x32_bf16 v[134:137], v[126:129], v[166:169], v[134:137]
	v_mfma_f32_16x16x32_bf16 v[130:133], v[142:145], v[166:169], v[130:133]
	v_mfma_f32_16x16x32_bf16 v[110:113], v[126:129], v[174:177], v[110:113]
	v_mfma_f32_16x16x32_bf16 v[106:109], v[142:145], v[174:177], v[106:109]
	v_mfma_f32_16x16x32_bf16 v[94:97], v[126:129], v[182:185], v[94:97]
	v_mfma_f32_16x16x32_bf16 v[90:93], v[142:145], v[182:185], v[90:93]
	v_mfma_f32_16x16x32_bf16 v[78:81], v[126:129], v[210:213], v[78:81]
	v_mfma_f32_16x16x32_bf16 v[74:77], v[142:145], v[210:213], v[74:77]
	s_setprio 0
	s_setprio 1
	v_mfma_f32_16x16x32_bf16 v[122:125], v[146:149], v[162:165], 0
	v_mfma_f32_16x16x32_bf16 v[118:121], v[154:157], v[162:165], 0
	v_mfma_f32_16x16x32_bf16 v[102:105], v[146:149], v[170:173], 0
	v_mfma_f32_16x16x32_bf16 v[98:101], v[154:157], v[170:173], 0
	v_mfma_f32_16x16x32_bf16 v[86:89], v[146:149], v[178:181], 0
	v_mfma_f32_16x16x32_bf16 v[82:85], v[154:157], v[178:181], 0
	v_mfma_f32_16x16x32_bf16 v[70:73], v[146:149], v[206:209], 0
	v_mfma_f32_16x16x32_bf16 v[66:69], v[154:157], v[206:209], 0
	v_mfma_f32_16x16x32_bf16 v[122:125], v[150:153], v[166:169], v[122:125]
	v_mfma_f32_16x16x32_bf16 v[118:121], v[158:161], v[166:169], v[118:121]
	v_mfma_f32_16x16x32_bf16 v[102:105], v[150:153], v[174:177], v[102:105]
	v_mfma_f32_16x16x32_bf16 v[98:101], v[158:161], v[174:177], v[98:101]
	v_mfma_f32_16x16x32_bf16 v[86:89], v[150:153], v[182:185], v[86:89]
	v_mfma_f32_16x16x32_bf16 v[82:85], v[158:161], v[182:185], v[82:85]
	v_mfma_f32_16x16x32_bf16 v[70:73], v[150:153], v[210:213], v[70:73]
	v_mfma_f32_16x16x32_bf16 v[66:69], v[158:161], v[210:213], v[66:69]
	s_setprio 0
	s_barrier
	s_add_i32 s44, s63, s52
	v_lshl_add_u64 v[214:215], s[48:49], 0, v[188:189]
	s_mov_b32 m0, s44
	ds_read_b128 v[162:165], v227 offset:16384
	ds_read_b128 v[166:169], v227 offset:17408
	ds_read_b128 v[170:173], v227 offset:18432
	ds_read_b128 v[174:177], v227 offset:19456
	ds_read_b128 v[178:181], v227 offset:20480
	ds_read_b128 v[182:185], v227 offset:21504
	ds_read_b128 v[206:209], v227 offset:22528
	ds_read_b128 v[210:213], v227 offset:23552
	global_load_lds_dwordx4 v[214:215], off
	s_add_i32 m0, s44, 0x2000
	s_add_u32 s44, s48, 0xb0000
	v_lshl_add_u64 v[216:217], s[48:49], 0, v[192:193]
	s_addc_u32 s45, s49, 0
	s_add_i32 s72, s64, s52
	global_load_lds_dwordx4 v[216:217], off
	v_lshl_add_u64 v[218:219], s[44:45], 0, v[188:189]
	s_mov_b32 m0, s72
	v_lshl_add_u64 v[220:221], s[50:51], 0, v[190:191]
	global_load_lds_dwordx4 v[218:219], off
	v_lshl_add_u64 v[218:219], s[44:45], 0, v[192:193]
	s_add_i32 m0, s72, 0x2000
	s_nop 0
	global_load_lds_dwordx4 v[218:219], off
	v_lshl_add_u64 v[218:219], s[50:51], 0, v[186:187]
	s_mov_b32 m0, s53
	s_nop 0
	global_load_lds_dwordx4 v[218:219], off
	s_mov_b32 m0, s54
	s_nop 0
	global_load_lds_dwordx4 v[220:221], off
	s_waitcnt vmcnt(8)
	s_waitcnt lgkmcnt(0)
	s_setprio 1
	s_barrier
	v_mfma_f32_16x16x32_bf16 v[62:65], v[114:117], v[162:165], 0
	v_mfma_f32_16x16x32_bf16 v[58:61], v[138:141], v[162:165], 0
	v_mfma_f32_16x16x32_bf16 v[46:49], v[114:117], v[170:173], 0
	v_mfma_f32_16x16x32_bf16 v[42:45], v[138:141], v[170:173], 0
	v_mfma_f32_16x16x32_bf16 v[30:33], v[114:117], v[178:181], 0
	v_mfma_f32_16x16x32_bf16 v[26:29], v[138:141], v[178:181], 0
	v_mfma_f32_16x16x32_bf16 v[14:17], v[114:117], v[206:209], 0
	v_mfma_f32_16x16x32_bf16 v[10:13], v[138:141], v[206:209], 0
	v_mfma_f32_16x16x32_bf16 v[62:65], v[126:129], v[166:169], v[62:65]
	v_mfma_f32_16x16x32_bf16 v[58:61], v[142:145], v[166:169], v[58:61]
	v_mfma_f32_16x16x32_bf16 v[46:49], v[126:129], v[174:177], v[46:49]
	v_mfma_f32_16x16x32_bf16 v[42:45], v[142:145], v[174:177], v[42:45]
	v_mfma_f32_16x16x32_bf16 v[30:33], v[126:129], v[182:185], v[30:33]
	v_mfma_f32_16x16x32_bf16 v[26:29], v[142:145], v[182:185], v[26:29]
	v_mfma_f32_16x16x32_bf16 v[14:17], v[126:129], v[210:213], v[14:17]
	v_mfma_f32_16x16x32_bf16 v[10:13], v[142:145], v[210:213], v[10:13]
	s_setprio 0
	s_setprio 1
	v_mfma_f32_16x16x32_bf16 v[54:57], v[146:149], v[162:165], 0
	v_mfma_f32_16x16x32_bf16 v[50:53], v[154:157], v[162:165], 0
	v_mfma_f32_16x16x32_bf16 v[38:41], v[146:149], v[170:173], 0
	v_mfma_f32_16x16x32_bf16 v[34:37], v[154:157], v[170:173], 0
	v_mfma_f32_16x16x32_bf16 v[22:25], v[146:149], v[178:181], 0
	v_mfma_f32_16x16x32_bf16 v[18:21], v[154:157], v[178:181], 0
	v_mfma_f32_16x16x32_bf16 v[6:9], v[146:149], v[206:209], 0
	v_mfma_f32_16x16x32_bf16 v[2:5], v[154:157], v[206:209], 0
	v_mfma_f32_16x16x32_bf16 v[54:57], v[150:153], v[166:169], v[54:57]
	v_mfma_f32_16x16x32_bf16 v[50:53], v[158:161], v[166:169], v[50:53]
	v_mfma_f32_16x16x32_bf16 v[38:41], v[150:153], v[174:177], v[38:41]
	v_mfma_f32_16x16x32_bf16 v[34:37], v[158:161], v[174:177], v[34:37]
	v_mfma_f32_16x16x32_bf16 v[22:25], v[150:153], v[182:185], v[22:25]
	v_mfma_f32_16x16x32_bf16 v[18:21], v[158:161], v[182:185], v[18:21]
	v_mfma_f32_16x16x32_bf16 v[6:9], v[150:153], v[210:213], v[6:9]
	v_mfma_f32_16x16x32_bf16 v[2:5], v[158:161], v[210:213], v[2:5]
	s_setprio 0
	s_barrier
	s_add_i32 s72, 0, 0x18000
	s_add_i32 s73, 0, 0x1c000
	v_add_u32_e32 v142, s72, v224
	v_add_u32_e32 v158, s73, v224
	ds_read_b128 v[114:117], v142
	ds_read_b128 v[126:129], v142 offset:1024
	ds_read_b128 v[138:141], v142 offset:2048
	ds_read_b128 v[142:145], v142 offset:3072
	ds_read_b128 v[146:149], v158
	ds_read_b128 v[150:153], v158 offset:1024
	ds_read_b128 v[154:157], v158 offset:2048
	ds_read_b128 v[158:161], v158 offset:3072
	s_add_u32 s44, s50, 0xb0000
	s_addc_u32 s45, s51, 0
	s_mov_b32 m0, s55
	v_lshl_add_u64 v[222:223], s[44:45], 0, v[186:187]
	ds_read_b128 v[162:165], v227 offset:32768
	ds_read_b128 v[166:169], v227 offset:33792
	ds_read_b128 v[170:173], v227 offset:34816
	ds_read_b128 v[174:177], v227 offset:35840
	ds_read_b128 v[178:181], v227 offset:36864
	ds_read_b128 v[182:185], v227 offset:37888
	ds_read_b128 v[206:209], v227 offset:38912
	ds_read_b128 v[210:213], v227 offset:39936
	global_load_lds_dwordx4 v[222:223], off
	v_lshl_add_u64 v[222:223], s[44:45], 0, v[190:191]
	s_mov_b32 m0, s56
	s_nop 0
	global_load_lds_dwordx4 v[222:223], off
	s_waitcnt vmcnt(8)
	s_waitcnt lgkmcnt(0)
	s_setprio 1
	s_barrier
	v_mfma_f32_16x16x32_bf16 v[134:137], v[114:117], v[162:165], v[134:137]
	v_mfma_f32_16x16x32_bf16 v[130:133], v[138:141], v[162:165], v[130:133]
	v_mfma_f32_16x16x32_bf16 v[110:113], v[114:117], v[170:173], v[110:113]
	v_mfma_f32_16x16x32_bf16 v[106:109], v[138:141], v[170:173], v[106:109]
	v_mfma_f32_16x16x32_bf16 v[94:97], v[114:117], v[178:181], v[94:97]
	v_mfma_f32_16x16x32_bf16 v[90:93], v[138:141], v[178:181], v[90:93]
	v_mfma_f32_16x16x32_bf16 v[78:81], v[114:117], v[206:209], v[78:81]
	v_mfma_f32_16x16x32_bf16 v[74:77], v[138:141], v[206:209], v[74:77]
	v_mfma_f32_16x16x32_bf16 v[134:137], v[126:129], v[166:169], v[134:137]
	v_mfma_f32_16x16x32_bf16 v[130:133], v[142:145], v[166:169], v[130:133]
	v_mfma_f32_16x16x32_bf16 v[110:113], v[126:129], v[174:177], v[110:113]
	v_mfma_f32_16x16x32_bf16 v[106:109], v[142:145], v[174:177], v[106:109]
	v_mfma_f32_16x16x32_bf16 v[94:97], v[126:129], v[182:185], v[94:97]
	v_mfma_f32_16x16x32_bf16 v[90:93], v[142:145], v[182:185], v[90:93]
	v_mfma_f32_16x16x32_bf16 v[78:81], v[126:129], v[210:213], v[78:81]
	v_mfma_f32_16x16x32_bf16 v[74:77], v[142:145], v[210:213], v[74:77]
	s_setprio 0
	s_setprio 1
	v_mfma_f32_16x16x32_bf16 v[122:125], v[146:149], v[162:165], v[122:125]
	v_mfma_f32_16x16x32_bf16 v[118:121], v[154:157], v[162:165], v[118:121]
	v_mfma_f32_16x16x32_bf16 v[102:105], v[146:149], v[170:173], v[102:105]
	v_mfma_f32_16x16x32_bf16 v[98:101], v[154:157], v[170:173], v[98:101]
	v_mfma_f32_16x16x32_bf16 v[86:89], v[146:149], v[178:181], v[86:89]
	v_mfma_f32_16x16x32_bf16 v[82:85], v[154:157], v[178:181], v[82:85]
	v_mfma_f32_16x16x32_bf16 v[70:73], v[146:149], v[206:209], v[70:73]
	v_mfma_f32_16x16x32_bf16 v[66:69], v[154:157], v[206:209], v[66:69]
	v_mfma_f32_16x16x32_bf16 v[122:125], v[150:153], v[166:169], v[122:125]
	v_mfma_f32_16x16x32_bf16 v[118:121], v[158:161], v[166:169], v[118:121]
	v_mfma_f32_16x16x32_bf16 v[102:105], v[150:153], v[174:177], v[102:105]
	v_mfma_f32_16x16x32_bf16 v[98:101], v[158:161], v[174:177], v[98:101]
	v_mfma_f32_16x16x32_bf16 v[86:89], v[150:153], v[182:185], v[86:89]
	v_mfma_f32_16x16x32_bf16 v[82:85], v[158:161], v[182:185], v[82:85]
	v_mfma_f32_16x16x32_bf16 v[70:73], v[150:153], v[210:213], v[70:73]
	v_mfma_f32_16x16x32_bf16 v[66:69], v[158:161], v[210:213], v[66:69]
	s_setprio 0
	s_barrier
	s_add_i32 s44, s72, s52
	v_lshl_add_u64 v[214:215], v[214:215], 0, s[24:25]
	s_mov_b32 m0, s44
	ds_read_b128 v[162:165], v227 offset:49152
	ds_read_b128 v[166:169], v227 offset:50176
	ds_read_b128 v[170:173], v227 offset:51200
	ds_read_b128 v[174:177], v227 offset:52224
	ds_read_b128 v[178:181], v227 offset:53248
	ds_read_b128 v[182:185], v227 offset:54272
	ds_read_b128 v[206:209], v227 offset:55296
	ds_read_b128 v[210:213], v227 offset:56320
	global_load_lds_dwordx4 v[214:215], off
	s_add_i32 m0, s44, 0x2000
	s_add_u32 s44, s48, 0xb0080
	v_lshl_add_u64 v[214:215], v[216:217], 0, s[24:25]
	s_addc_u32 s45, s49, 0
	s_add_i32 s48, s73, s52
	global_load_lds_dwordx4 v[214:215], off
	v_lshl_add_u64 v[214:215], s[44:45], 0, v[188:189]
	s_mov_b32 m0, s48
	s_nop 0
	global_load_lds_dwordx4 v[214:215], off
	v_lshl_add_u64 v[214:215], s[44:45], 0, v[192:193]
	s_add_i32 m0, s48, 0x2000
	s_nop 0
	global_load_lds_dwordx4 v[214:215], off
	v_lshl_add_u64 v[214:215], v[218:219], 0, s[24:25]
	s_mov_b32 m0, s58
	s_nop 0
	global_load_lds_dwordx4 v[214:215], off
	v_lshl_add_u64 v[214:215], v[220:221], 0, s[24:25]
	s_mov_b32 m0, s59
	s_nop 0
	global_load_lds_dwordx4 v[214:215], off
	s_waitcnt vmcnt(8)
	s_waitcnt lgkmcnt(0)
	s_setprio 1
	s_barrier
	v_mfma_f32_16x16x32_bf16 v[62:65], v[114:117], v[162:165], v[62:65]
	v_mfma_f32_16x16x32_bf16 v[58:61], v[138:141], v[162:165], v[58:61]
	v_mfma_f32_16x16x32_bf16 v[46:49], v[114:117], v[170:173], v[46:49]
	v_mfma_f32_16x16x32_bf16 v[42:45], v[138:141], v[170:173], v[42:45]
	v_mfma_f32_16x16x32_bf16 v[30:33], v[114:117], v[178:181], v[30:33]
	v_mfma_f32_16x16x32_bf16 v[26:29], v[138:141], v[178:181], v[26:29]
	v_mfma_f32_16x16x32_bf16 v[14:17], v[114:117], v[206:209], v[14:17]
	v_mfma_f32_16x16x32_bf16 v[10:13], v[138:141], v[206:209], v[10:13]
	v_mfma_f32_16x16x32_bf16 v[62:65], v[126:129], v[166:169], v[62:65]
	v_mfma_f32_16x16x32_bf16 v[58:61], v[142:145], v[166:169], v[58:61]
	v_mfma_f32_16x16x32_bf16 v[46:49], v[126:129], v[174:177], v[46:49]
	v_mfma_f32_16x16x32_bf16 v[42:45], v[142:145], v[174:177], v[42:45]
	v_mfma_f32_16x16x32_bf16 v[30:33], v[126:129], v[182:185], v[30:33]
	v_mfma_f32_16x16x32_bf16 v[26:29], v[142:145], v[182:185], v[26:29]
	v_mfma_f32_16x16x32_bf16 v[14:17], v[126:129], v[210:213], v[14:17]
	v_mfma_f32_16x16x32_bf16 v[10:13], v[142:145], v[210:213], v[10:13]
	s_setprio 0
	s_setprio 1
	v_mfma_f32_16x16x32_bf16 v[54:57], v[146:149], v[162:165], v[54:57]
	v_mfma_f32_16x16x32_bf16 v[50:53], v[154:157], v[162:165], v[50:53]
	v_mfma_f32_16x16x32_bf16 v[38:41], v[146:149], v[170:173], v[38:41]
	v_mfma_f32_16x16x32_bf16 v[34:37], v[154:157], v[170:173], v[34:37]
	v_mfma_f32_16x16x32_bf16 v[22:25], v[146:149], v[178:181], v[22:25]
	v_mfma_f32_16x16x32_bf16 v[18:21], v[154:157], v[178:181], v[18:21]
	v_mfma_f32_16x16x32_bf16 v[6:9], v[146:149], v[206:209], v[6:9]
	v_mfma_f32_16x16x32_bf16 v[2:5], v[154:157], v[206:209], v[2:5]
	v_mfma_f32_16x16x32_bf16 v[54:57], v[150:153], v[166:169], v[54:57]
	v_mfma_f32_16x16x32_bf16 v[50:53], v[158:161], v[166:169], v[50:53]
	v_mfma_f32_16x16x32_bf16 v[38:41], v[150:153], v[174:177], v[38:41]
	v_mfma_f32_16x16x32_bf16 v[34:37], v[158:161], v[174:177], v[34:37]
	v_mfma_f32_16x16x32_bf16 v[22:25], v[150:153], v[182:185], v[22:25]
	v_mfma_f32_16x16x32_bf16 v[18:21], v[158:161], v[182:185], v[18:21]
	v_mfma_f32_16x16x32_bf16 v[6:9], v[150:153], v[210:213], v[6:9]
	v_mfma_f32_16x16x32_bf16 v[2:5], v[158:161], v[210:213], v[2:5]
	s_setprio 0
	s_add_i32 s71, s71, 2
	s_add_u32 s69, s69, 0x100
	s_addc_u32 s70, s70, 0
	s_cmp_gt_u32 s71, 41
	s_mov_b64 s[44:45], s[46:47]
	s_barrier
	s_cbranch_scc0 .LBB0_1909
	s_branch .Lz_post_p15
.LBB0_1909:
	ds_read_b128 v[114:117], v225
	ds_read_b128 v[126:129], v225 offset:1024
	ds_read_b128 v[138:141], v225 offset:2048
	ds_read_b128 v[142:145], v225 offset:3072
	ds_read_b128 v[146:149], v226
	ds_read_b128 v[150:153], v226 offset:1024
	ds_read_b128 v[154:157], v226 offset:2048
	ds_read_b128 v[158:161], v226 offset:3072
	s_add_u32 s46, s44, 0x100
	s_addc_u32 s47, s45, 0
	s_cmp_eq_u32 s71, 40
	s_cselect_b32 s51, s9, s47
	s_cselect_b32 s50, s8, s46
	s_cselect_b32 s49, s43, s70
	s_cselect_b32 s48, s42, s69
	v_lshl_add_u64 v[214:215], s[44:45], 0, v[198:199]
	s_add_i32 m0, s53, 0xc000
	ds_read_b128 v[162:165], v227
	ds_read_b128 v[166:169], v227 offset:1024
	ds_read_b128 v[170:173], v227 offset:2048
	ds_read_b128 v[174:177], v227 offset:3072
	ds_read_b128 v[178:181], v227 offset:4096
	ds_read_b128 v[182:185], v227 offset:5120
	ds_read_b128 v[206:209], v227 offset:6144
	ds_read_b128 v[210:213], v227 offset:7168
	global_load_lds_dwordx4 v[214:215], off
	v_lshl_add_u64 v[214:215], s[44:45], 0, v[200:201]
	s_add_i32 m0, s53, 0xe000
	s_nop 0
	global_load_lds_dwordx4 v[214:215], off
	s_waitcnt vmcnt(8)
	s_waitcnt lgkmcnt(0)
	s_setprio 1
	s_barrier
	v_mfma_f32_16x16x32_bf16 v[134:137], v[114:117], v[162:165], v[134:137]
	v_mfma_f32_16x16x32_bf16 v[130:133], v[138:141], v[162:165], v[130:133]
	v_mfma_f32_16x16x32_bf16 v[110:113], v[114:117], v[170:173], v[110:113]
	v_mfma_f32_16x16x32_bf16 v[106:109], v[138:141], v[170:173], v[106:109]
	v_mfma_f32_16x16x32_bf16 v[94:97], v[114:117], v[178:181], v[94:97]
	v_mfma_f32_16x16x32_bf16 v[90:93], v[138:141], v[178:181], v[90:93]
	v_mfma_f32_16x16x32_bf16 v[78:81], v[114:117], v[206:209], v[78:81]
	v_mfma_f32_16x16x32_bf16 v[74:77], v[138:141], v[206:209], v[74:77]
	v_mfma_f32_16x16x32_bf16 v[134:137], v[126:129], v[166:169], v[134:137]
	v_mfma_f32_16x16x32_bf16 v[130:133], v[142:145], v[166:169], v[130:133]
	v_mfma_f32_16x16x32_bf16 v[110:113], v[126:129], v[174:177], v[110:113]
	v_mfma_f32_16x16x32_bf16 v[106:109], v[142:145], v[174:177], v[106:109]
	v_mfma_f32_16x16x32_bf16 v[94:97], v[126:129], v[182:185], v[94:97]
	v_mfma_f32_16x16x32_bf16 v[90:93], v[142:145], v[182:185], v[90:93]
	v_mfma_f32_16x16x32_bf16 v[78:81], v[126:129], v[210:213], v[78:81]
	v_mfma_f32_16x16x32_bf16 v[74:77], v[142:145], v[210:213], v[74:77]
	s_setprio 0
	s_setprio 1
	v_mfma_f32_16x16x32_bf16 v[122:125], v[146:149], v[162:165], v[122:125]
	v_mfma_f32_16x16x32_bf16 v[118:121], v[154:157], v[162:165], v[118:121]
	v_mfma_f32_16x16x32_bf16 v[102:105], v[146:149], v[170:173], v[102:105]
	v_mfma_f32_16x16x32_bf16 v[98:101], v[154:157], v[170:173], v[98:101]
	v_mfma_f32_16x16x32_bf16 v[86:89], v[146:149], v[178:181], v[86:89]
	v_mfma_f32_16x16x32_bf16 v[82:85], v[154:157], v[178:181], v[82:85]
	v_mfma_f32_16x16x32_bf16 v[70:73], v[146:149], v[206:209], v[70:73]
	v_mfma_f32_16x16x32_bf16 v[66:69], v[154:157], v[206:209], v[66:69]
	v_mfma_f32_16x16x32_bf16 v[122:125], v[150:153], v[166:169], v[122:125]
	v_mfma_f32_16x16x32_bf16 v[118:121], v[158:161], v[166:169], v[118:121]
	v_mfma_f32_16x16x32_bf16 v[102:105], v[150:153], v[174:177], v[102:105]
	v_mfma_f32_16x16x32_bf16 v[98:101], v[158:161], v[174:177], v[98:101]
	v_mfma_f32_16x16x32_bf16 v[86:89], v[150:153], v[182:185], v[86:89]
	v_mfma_f32_16x16x32_bf16 v[82:85], v[158:161], v[182:185], v[82:85]
	v_mfma_f32_16x16x32_bf16 v[70:73], v[150:153], v[210:213], v[70:73]
	v_mfma_f32_16x16x32_bf16 v[66:69], v[158:161], v[210:213], v[66:69]
	s_setprio 0
	s_barrier
	s_add_i32 s44, s63, s52
	v_lshl_add_u64 v[214:215], s[48:49], 0, v[188:189]
	s_mov_b32 m0, s44
	ds_read_b128 v[162:165], v227 offset:16384
	ds_read_b128 v[166:169], v227 offset:17408
	ds_read_b128 v[170:173], v227 offset:18432
	ds_read_b128 v[174:177], v227 offset:19456
	ds_read_b128 v[178:181], v227 offset:20480
	ds_read_b128 v[182:185], v227 offset:21504
	ds_read_b128 v[206:209], v227 offset:22528
	ds_read_b128 v[210:213], v227 offset:23552
	global_load_lds_dwordx4 v[214:215], off
	s_add_i32 m0, s44, 0x2000
	s_add_u32 s44, s48, 0xb0000
	v_lshl_add_u64 v[216:217], s[48:49], 0, v[192:193]
	s_addc_u32 s45, s49, 0
	s_add_i32 s72, s64, s52
	global_load_lds_dwordx4 v[216:217], off
	v_lshl_add_u64 v[218:219], s[44:45], 0, v[188:189]
	s_mov_b32 m0, s72
	v_lshl_add_u64 v[220:221], s[50:51], 0, v[190:191]
	global_load_lds_dwordx4 v[218:219], off
	v_lshl_add_u64 v[218:219], s[44:45], 0, v[192:193]
	s_add_i32 m0, s72, 0x2000
	s_nop 0
	global_load_lds_dwordx4 v[218:219], off
	v_lshl_add_u64 v[218:219], s[50:51], 0, v[186:187]
	s_mov_b32 m0, s53
	s_nop 0
	global_load_lds_dwordx4 v[218:219], off
	s_mov_b32 m0, s54
	s_nop 0
	global_load_lds_dwordx4 v[220:221], off
	s_waitcnt vmcnt(8)
	s_waitcnt lgkmcnt(0)
	s_setprio 1
	s_barrier
	v_mfma_f32_16x16x32_bf16 v[62:65], v[114:117], v[162:165], v[62:65]
	v_mfma_f32_16x16x32_bf16 v[58:61], v[138:141], v[162:165], v[58:61]
	v_mfma_f32_16x16x32_bf16 v[46:49], v[114:117], v[170:173], v[46:49]
	v_mfma_f32_16x16x32_bf16 v[42:45], v[138:141], v[170:173], v[42:45]
	v_mfma_f32_16x16x32_bf16 v[30:33], v[114:117], v[178:181], v[30:33]
	v_mfma_f32_16x16x32_bf16 v[26:29], v[138:141], v[178:181], v[26:29]
	v_mfma_f32_16x16x32_bf16 v[14:17], v[114:117], v[206:209], v[14:17]
	v_mfma_f32_16x16x32_bf16 v[10:13], v[138:141], v[206:209], v[10:13]
	v_mfma_f32_16x16x32_bf16 v[62:65], v[126:129], v[166:169], v[62:65]
	v_mfma_f32_16x16x32_bf16 v[58:61], v[142:145], v[166:169], v[58:61]
	v_mfma_f32_16x16x32_bf16 v[46:49], v[126:129], v[174:177], v[46:49]
	v_mfma_f32_16x16x32_bf16 v[42:45], v[142:145], v[174:177], v[42:45]
	v_mfma_f32_16x16x32_bf16 v[30:33], v[126:129], v[182:185], v[30:33]
	v_mfma_f32_16x16x32_bf16 v[26:29], v[142:145], v[182:185], v[26:29]
	v_mfma_f32_16x16x32_bf16 v[14:17], v[126:129], v[210:213], v[14:17]
	v_mfma_f32_16x16x32_bf16 v[10:13], v[142:145], v[210:213], v[10:13]
	s_setprio 0
	s_setprio 1
	v_mfma_f32_16x16x32_bf16 v[54:57], v[146:149], v[162:165], v[54:57]
	v_mfma_f32_16x16x32_bf16 v[50:53], v[154:157], v[162:165], v[50:53]
	v_mfma_f32_16x16x32_bf16 v[38:41], v[146:149], v[170:173], v[38:41]
	v_mfma_f32_16x16x32_bf16 v[34:37], v[154:157], v[170:173], v[34:37]
	v_mfma_f32_16x16x32_bf16 v[22:25], v[146:149], v[178:181], v[22:25]
	v_mfma_f32_16x16x32_bf16 v[18:21], v[154:157], v[178:181], v[18:21]
	v_mfma_f32_16x16x32_bf16 v[6:9], v[146:149], v[206:209], v[6:9]
	v_mfma_f32_16x16x32_bf16 v[2:5], v[154:157], v[206:209], v[2:5]
	v_mfma_f32_16x16x32_bf16 v[54:57], v[150:153], v[166:169], v[54:57]
	v_mfma_f32_16x16x32_bf16 v[50:53], v[158:161], v[166:169], v[50:53]
	v_mfma_f32_16x16x32_bf16 v[38:41], v[150:153], v[174:177], v[38:41]
	v_mfma_f32_16x16x32_bf16 v[34:37], v[158:161], v[174:177], v[34:37]
	v_mfma_f32_16x16x32_bf16 v[22:25], v[150:153], v[182:185], v[22:25]
	v_mfma_f32_16x16x32_bf16 v[18:21], v[158:161], v[182:185], v[18:21]
	v_mfma_f32_16x16x32_bf16 v[6:9], v[150:153], v[210:213], v[6:9]
	v_mfma_f32_16x16x32_bf16 v[2:5], v[158:161], v[210:213], v[2:5]
	s_setprio 0
	s_barrier
	s_add_i32 s72, 0, 0x18000
	s_add_i32 s73, 0, 0x1c000
	v_add_u32_e32 v142, s72, v224
	v_add_u32_e32 v158, s73, v224
	ds_read_b128 v[114:117], v142
	ds_read_b128 v[126:129], v142 offset:1024
	ds_read_b128 v[138:141], v142 offset:2048
	ds_read_b128 v[142:145], v142 offset:3072
	ds_read_b128 v[146:149], v158
	ds_read_b128 v[150:153], v158 offset:1024
	ds_read_b128 v[154:157], v158 offset:2048
	ds_read_b128 v[158:161], v158 offset:3072
	s_add_u32 s44, s50, 0xb0000
	s_addc_u32 s45, s51, 0
	s_mov_b32 m0, s55
	v_lshl_add_u64 v[222:223], s[44:45], 0, v[186:187]
	ds_read_b128 v[162:165], v227 offset:32768
	ds_read_b128 v[166:169], v227 offset:33792
	ds_read_b128 v[170:173], v227 offset:34816
	ds_read_b128 v[174:177], v227 offset:35840
	ds_read_b128 v[178:181], v227 offset:36864
	ds_read_b128 v[182:185], v227 offset:37888
	ds_read_b128 v[206:209], v227 offset:38912
	ds_read_b128 v[210:213], v227 offset:39936
	global_load_lds_dwordx4 v[222:223], off
	v_lshl_add_u64 v[222:223], s[44:45], 0, v[190:191]
	s_mov_b32 m0, s56
	s_nop 0
	global_load_lds_dwordx4 v[222:223], off
	s_waitcnt vmcnt(8)
	s_waitcnt lgkmcnt(0)
	s_setprio 1
	s_barrier
	v_mfma_f32_16x16x32_bf16 v[134:137], v[114:117], v[162:165], v[134:137]
	v_mfma_f32_16x16x32_bf16 v[130:133], v[138:141], v[162:165], v[130:133]
	v_mfma_f32_16x16x32_bf16 v[110:113], v[114:117], v[170:173], v[110:113]
	v_mfma_f32_16x16x32_bf16 v[106:109], v[138:141], v[170:173], v[106:109]
	v_mfma_f32_16x16x32_bf16 v[94:97], v[114:117], v[178:181], v[94:97]
	v_mfma_f32_16x16x32_bf16 v[90:93], v[138:141], v[178:181], v[90:93]
	v_mfma_f32_16x16x32_bf16 v[78:81], v[114:117], v[206:209], v[78:81]
	v_mfma_f32_16x16x32_bf16 v[74:77], v[138:141], v[206:209], v[74:77]
	v_mfma_f32_16x16x32_bf16 v[134:137], v[126:129], v[166:169], v[134:137]
	v_mfma_f32_16x16x32_bf16 v[130:133], v[142:145], v[166:169], v[130:133]
	v_mfma_f32_16x16x32_bf16 v[110:113], v[126:129], v[174:177], v[110:113]
	v_mfma_f32_16x16x32_bf16 v[106:109], v[142:145], v[174:177], v[106:109]
	v_mfma_f32_16x16x32_bf16 v[94:97], v[126:129], v[182:185], v[94:97]
	v_mfma_f32_16x16x32_bf16 v[90:93], v[142:145], v[182:185], v[90:93]
	v_mfma_f32_16x16x32_bf16 v[78:81], v[126:129], v[210:213], v[78:81]
	v_mfma_f32_16x16x32_bf16 v[74:77], v[142:145], v[210:213], v[74:77]
	s_setprio 0
	s_setprio 1
	v_mfma_f32_16x16x32_bf16 v[122:125], v[146:149], v[162:165], v[122:125]
	v_mfma_f32_16x16x32_bf16 v[118:121], v[154:157], v[162:165], v[118:121]
	v_mfma_f32_16x16x32_bf16 v[102:105], v[146:149], v[170:173], v[102:105]
	v_mfma_f32_16x16x32_bf16 v[98:101], v[154:157], v[170:173], v[98:101]
	v_mfma_f32_16x16x32_bf16 v[86:89], v[146:149], v[178:181], v[86:89]
	v_mfma_f32_16x16x32_bf16 v[82:85], v[154:157], v[178:181], v[82:85]
	v_mfma_f32_16x16x32_bf16 v[70:73], v[146:149], v[206:209], v[70:73]
	v_mfma_f32_16x16x32_bf16 v[66:69], v[154:157], v[206:209], v[66:69]
	v_mfma_f32_16x16x32_bf16 v[122:125], v[150:153], v[166:169], v[122:125]
	v_mfma_f32_16x16x32_bf16 v[118:121], v[158:161], v[166:169], v[118:121]
	v_mfma_f32_16x16x32_bf16 v[102:105], v[150:153], v[174:177], v[102:105]
	v_mfma_f32_16x16x32_bf16 v[98:101], v[158:161], v[174:177], v[98:101]
	v_mfma_f32_16x16x32_bf16 v[86:89], v[150:153], v[182:185], v[86:89]
	v_mfma_f32_16x16x32_bf16 v[82:85], v[158:161], v[182:185], v[82:85]
	v_mfma_f32_16x16x32_bf16 v[70:73], v[150:153], v[210:213], v[70:73]
	v_mfma_f32_16x16x32_bf16 v[66:69], v[158:161], v[210:213], v[66:69]
	s_setprio 0
	s_barrier
	s_add_i32 s44, s72, s52
	v_lshl_add_u64 v[214:215], v[214:215], 0, s[24:25]
	s_mov_b32 m0, s44
	ds_read_b128 v[162:165], v227 offset:49152
	ds_read_b128 v[166:169], v227 offset:50176
	ds_read_b128 v[170:173], v227 offset:51200
	ds_read_b128 v[174:177], v227 offset:52224
	ds_read_b128 v[178:181], v227 offset:53248
	ds_read_b128 v[182:185], v227 offset:54272
	ds_read_b128 v[206:209], v227 offset:55296
	ds_read_b128 v[210:213], v227 offset:56320
	global_load_lds_dwordx4 v[214:215], off
	s_add_i32 m0, s44, 0x2000
	s_add_u32 s44, s48, 0xb0080
	v_lshl_add_u64 v[214:215], v[216:217], 0, s[24:25]
	s_addc_u32 s45, s49, 0
	s_add_i32 s48, s73, s52
	global_load_lds_dwordx4 v[214:215], off
	v_lshl_add_u64 v[214:215], s[44:45], 0, v[188:189]
	s_mov_b32 m0, s48
	s_nop 0
	global_load_lds_dwordx4 v[214:215], off
	v_lshl_add_u64 v[214:215], s[44:45], 0, v[192:193]
	s_add_i32 m0, s48, 0x2000
	s_nop 0
	global_load_lds_dwordx4 v[214:215], off
	v_lshl_add_u64 v[214:215], v[218:219], 0, s[24:25]
	s_mov_b32 m0, s58
	s_nop 0
	global_load_lds_dwordx4 v[214:215], off
	v_lshl_add_u64 v[214:215], v[220:221], 0, s[24:25]
	s_mov_b32 m0, s59
	s_nop 0
	global_load_lds_dwordx4 v[214:215], off
	s_waitcnt vmcnt(8)
	s_waitcnt lgkmcnt(0)
	s_setprio 1
	s_barrier
	v_mfma_f32_16x16x32_bf16 v[62:65], v[114:117], v[162:165], v[62:65]
	v_mfma_f32_16x16x32_bf16 v[58:61], v[138:141], v[162:165], v[58:61]
	v_mfma_f32_16x16x32_bf16 v[46:49], v[114:117], v[170:173], v[46:49]
	v_mfma_f32_16x16x32_bf16 v[42:45], v[138:141], v[170:173], v[42:45]
	v_mfma_f32_16x16x32_bf16 v[30:33], v[114:117], v[178:181], v[30:33]
	v_mfma_f32_16x16x32_bf16 v[26:29], v[138:141], v[178:181], v[26:29]
	v_mfma_f32_16x16x32_bf16 v[14:17], v[114:117], v[206:209], v[14:17]
	v_mfma_f32_16x16x32_bf16 v[10:13], v[138:141], v[206:209], v[10:13]
	v_mfma_f32_16x16x32_bf16 v[62:65], v[126:129], v[166:169], v[62:65]
	v_mfma_f32_16x16x32_bf16 v[58:61], v[142:145], v[166:169], v[58:61]
	v_mfma_f32_16x16x32_bf16 v[46:49], v[126:129], v[174:177], v[46:49]
	v_mfma_f32_16x16x32_bf16 v[42:45], v[142:145], v[174:177], v[42:45]
	v_mfma_f32_16x16x32_bf16 v[30:33], v[126:129], v[182:185], v[30:33]
	v_mfma_f32_16x16x32_bf16 v[26:29], v[142:145], v[182:185], v[26:29]
	v_mfma_f32_16x16x32_bf16 v[14:17], v[126:129], v[210:213], v[14:17]
	v_mfma_f32_16x16x32_bf16 v[10:13], v[142:145], v[210:213], v[10:13]
	s_setprio 0
	s_setprio 1
	v_mfma_f32_16x16x32_bf16 v[54:57], v[146:149], v[162:165], v[54:57]
	v_mfma_f32_16x16x32_bf16 v[50:53], v[154:157], v[162:165], v[50:53]
	v_mfma_f32_16x16x32_bf16 v[38:41], v[146:149], v[170:173], v[38:41]
	v_mfma_f32_16x16x32_bf16 v[34:37], v[154:157], v[170:173], v[34:37]
	v_mfma_f32_16x16x32_bf16 v[22:25], v[146:149], v[178:181], v[22:25]
	v_mfma_f32_16x16x32_bf16 v[18:21], v[154:157], v[178:181], v[18:21]
	v_mfma_f32_16x16x32_bf16 v[6:9], v[146:149], v[206:209], v[6:9]
	v_mfma_f32_16x16x32_bf16 v[2:5], v[154:157], v[206:209], v[2:5]
	v_mfma_f32_16x16x32_bf16 v[54:57], v[150:153], v[166:169], v[54:57]
	v_mfma_f32_16x16x32_bf16 v[50:53], v[158:161], v[166:169], v[50:53]
	v_mfma_f32_16x16x32_bf16 v[38:41], v[150:153], v[174:177], v[38:41]
	v_mfma_f32_16x16x32_bf16 v[34:37], v[158:161], v[174:177], v[34:37]
	v_mfma_f32_16x16x32_bf16 v[22:25], v[150:153], v[182:185], v[22:25]
	v_mfma_f32_16x16x32_bf16 v[18:21], v[158:161], v[182:185], v[18:21]
	v_mfma_f32_16x16x32_bf16 v[6:9], v[150:153], v[210:213], v[6:9]
	v_mfma_f32_16x16x32_bf16 v[2:5], v[158:161], v[210:213], v[2:5]
	s_setprio 0
	s_add_i32 s71, s71, 2
	s_add_u32 s69, s69, 0x100
	s_addc_u32 s70, s70, 0
	s_cmp_gt_u32 s71, 41
	s_mov_b64 s[44:45], s[46:47]
	s_barrier
	s_cbranch_scc0 .LBB0_1909
